# v13 + GEMM K-loop load-segment balancing: As[0][0] stage moved from SP2(t) to SP1(t+1) (DMA 2/6/2/6 -> 2/4/4/6), SP2 waits vmcnt(6)
# baseline (speedup 1.0000x reference)
; #define PG8_STAGE(bufoff, gbase, voff) do { _Pragma("unroll") for (int _i = 0; _i < 2; ++_i) \
;         __builtin_amdgcn_global_load_lds((const unsigned*)((const char*)(gbase) + (voff)[_i]), (PG8_LAS unsigned*)(lds + (bufoff) + ldsw + _i * 8192), 16, 0, 0); } while (0)
; #define PG8_LDA(dst, b, h) do { _Pragma("unroll") for (int m = 0; m < 4; ++m) _Pragma("unroll") for (int k = 0; k < 2; ++k) dst[m][k] = *(const PG8_LAS bf16x8*)(lds + PG8_SA(b, h) + aoff + m * 2048 + k * 1024); } while (0)
; #define PG8_LDB(dst, b, h) do { _Pragma("unroll") for (int n = 0; n < 2; ++n) _Pragma("unroll") for (int k = 0; k < 2; ++k) dst[n][k] = *(const PG8_LAS bf16x8*)(lds + PG8_SB(b, h) + boff + n * 2048 + k * 1024); } while (0)
; #define PG8_MMA(ai, bj, At, Bt) do { __builtin_amdgcn_s_setprio(1); _Pragma("unroll") for (int m = 0; m < 4; ++m) _Pragma("unroll") for (int n = 0; n < 2; ++n) _Pragma("unroll") for (int k = 0; k < 2; ++k) \
;         acc[ai][bj][m][n] = __builtin_amdgcn_mfma_f32_16x16x32_bf16(Bt[n][k], At[m][k], acc[ai][bj][m][n], 0, 0, 0); __builtin_amdgcn_s_setprio(0); } while (0)
; #define PG8_WAIT_V(n) asm volatile("s_waitcnt vmcnt(" #n ")" ::: "memory")
; #define PG8_WAIT_L(n) asm volatile("s_waitcnt lgkmcnt(" #n ")" ::: "memory")
; #define PG8_BAR __builtin_amdgcn_s_barrier()
; #define PG8_SCHED __builtin_amdgcn_sched_barrier(0)
; template <class Epi, class Sched, bool ALIGN_EPI = false, bool SP2 = false>
; __device__ __forceinline__ void gemm_phase(PG8_LAS unsigned char* lds, const Gemm g, const Sched& S, const Epi& E) {
;     ...
;             PG8_LDB(B0, 0, 0); PG8_LDB(B1, 0, 1); PG8_SCHED; PG8_LDA(At, 0, 0); PG8_STAGE(PG8_SA(1, 1), a1 + hstep, voffA);
;             PG8_WAIT_V(8); PG8_WAIT_L(0); PG8_BAR; PG8_MMA(0, 0, At, B0); PG8_MMA(0, 1, At, B1); PG8_BAR; PG8_SCHED;
;             PG8_LDA(At, 0, 1); PG8_STAGE(PG8_SB(0, 0), b2, voffB); PG8_STAGE(PG8_SB(0, 1), b2 + hstep, voffB); PG8_STAGE(PG8_SA(0, 0), a2, voffA);
;             PG8_WAIT_V(8); PG8_WAIT_L(0); PG8_BAR; PG8_MMA(1, 0, At, B0); PG8_MMA(1, 1, At, B1); PG8_BAR; PG8_SCHED;
.LBB0_510:
	ds_read_b128 v[128:131], v184
	ds_read_b128 v[148:151], v184 offset:1024
	ds_read_b128 v[152:155], v184 offset:2048
	ds_read_b128 v[158:161], v184 offset:3072
	ds_read_b128 v[190:193], v185
	ds_read_b128 v[194:197], v185 offset:1024
	ds_read_b128 v[198:201], v185 offset:2048
	ds_read_b128 v[202:205], v185 offset:3072
	s_add_u32 s34, s10, 0xfffc0080
	s_addc_u32 s35, s11, -1
	s_cmp_eq_u32 vcc_lo, 12
	s_cselect_b32 s69, s57, s35
	s_cselect_b32 s68, s63, s34
	s_cselect_b32 s67, s55, s97
	s_cselect_b32 s66, s95, s96
	s_add_i32 m0, s65, 0xc000
	ds_read_b128 v[206:209], v186
	ds_read_b128 v[210:213], v186 offset:1024
	ds_read_b128 v[214:217], v186 offset:2048
	ds_read_b128 v[218:221], v186 offset:3072
	ds_read_b128 v[222:225], v186 offset:4096
	ds_read_b128 v[226:229], v186 offset:5120
	ds_read_b128 v[230:233], v186 offset:6144
	ds_read_b128 v[234:237], v186 offset:7168
	global_load_lds_dwordx4 v142, s[10:11]
	s_add_i32 m0, s65, 0xe000
	s_nop 0
	global_load_lds_dwordx4 v140, s[10:11]
	s_waitcnt vmcnt(8)
	s_waitcnt lgkmcnt(0)
	s_barrier
	v_mfma_f32_16x16x32_bf16 v[124:127], v[128:131], v[206:209], v[124:127]
	v_mfma_f32_16x16x32_bf16 v[124:127], v[148:151], v[210:213], v[124:127]
	v_mfma_f32_16x16x32_bf16 v[120:123], v[152:155], v[206:209], v[120:123]
	v_mfma_f32_16x16x32_bf16 v[120:123], v[158:161], v[210:213], v[120:123]
	v_mfma_f32_16x16x32_bf16 v[104:107], v[152:155], v[214:217], v[104:107]
	v_mfma_f32_16x16x32_bf16 v[104:107], v[158:161], v[218:221], v[104:107]
	v_mfma_f32_16x16x32_bf16 v[108:111], v[128:131], v[214:217], v[108:111]
	v_mfma_f32_16x16x32_bf16 v[108:111], v[148:151], v[218:221], v[108:111]
	v_mfma_f32_16x16x32_bf16 v[92:95], v[128:131], v[222:225], v[92:95]
	v_mfma_f32_16x16x32_bf16 v[92:95], v[148:151], v[226:229], v[92:95]
	v_mfma_f32_16x16x32_bf16 v[88:91], v[152:155], v[222:225], v[88:91]
	v_mfma_f32_16x16x32_bf16 v[88:91], v[158:161], v[226:229], v[88:91]
	v_mfma_f32_16x16x32_bf16 v[72:75], v[152:155], v[230:233], v[72:75]
	v_mfma_f32_16x16x32_bf16 v[72:75], v[158:161], v[234:237], v[72:75]
	v_mfma_f32_16x16x32_bf16 v[76:79], v[128:131], v[230:233], v[76:79]
	v_mfma_f32_16x16x32_bf16 v[76:79], v[148:151], v[234:237], v[76:79]
	v_mfma_f32_16x16x32_bf16 v[116:119], v[190:193], v[206:209], v[116:119]
	v_mfma_f32_16x16x32_bf16 v[116:119], v[194:197], v[210:213], v[116:119]
	v_mfma_f32_16x16x32_bf16 v[112:115], v[198:201], v[206:209], v[112:115]
	v_mfma_f32_16x16x32_bf16 v[112:115], v[202:205], v[210:213], v[112:115]
	v_mfma_f32_16x16x32_bf16 v[96:99], v[198:201], v[214:217], v[96:99]
	v_mfma_f32_16x16x32_bf16 v[96:99], v[202:205], v[218:221], v[96:99]
	v_mfma_f32_16x16x32_bf16 v[100:103], v[190:193], v[214:217], v[100:103]
	v_mfma_f32_16x16x32_bf16 v[100:103], v[194:197], v[218:221], v[100:103]
	v_mfma_f32_16x16x32_bf16 v[84:87], v[190:193], v[222:225], v[84:87]
	v_mfma_f32_16x16x32_bf16 v[84:87], v[194:197], v[226:229], v[84:87]
	v_mfma_f32_16x16x32_bf16 v[80:83], v[198:201], v[222:225], v[80:83]
	v_mfma_f32_16x16x32_bf16 v[80:83], v[202:205], v[226:229], v[80:83]
	v_mfma_f32_16x16x32_bf16 v[64:67], v[198:201], v[230:233], v[64:67]
	v_mfma_f32_16x16x32_bf16 v[64:67], v[202:205], v[234:237], v[64:67]
	v_mfma_f32_16x16x32_bf16 v[68:71], v[190:193], v[230:233], v[68:71]
	v_mfma_f32_16x16x32_bf16 v[68:71], v[194:197], v[234:237], v[68:71]
	s_barrier
	s_add_i32 s34, s84, s71
	s_mov_b32 m0, s34
	ds_read_b128 v[206:209], v186 offset:16384
	ds_read_b128 v[210:213], v186 offset:17408
	ds_read_b128 v[214:217], v186 offset:18432
	ds_read_b128 v[218:221], v186 offset:19456
	ds_read_b128 v[222:225], v186 offset:20480
	ds_read_b128 v[226:229], v186 offset:21504
	ds_read_b128 v[230:233], v186 offset:22528
	ds_read_b128 v[234:237], v186 offset:23552
	global_load_lds_dwordx4 v134, s[66:67]
	s_add_i32 m0, s34, 0x2000
	s_add_u32 s34, s66, 0x40000
	s_addc_u32 s35, s67, 0
	s_add_i32 vcc_hi, s85, s71
	global_load_lds_dwordx4 v138, s[66:67]
	s_mov_b32 m0, vcc_hi
	s_nop 0
	global_load_lds_dwordx4 v134, s[34:35]
	s_add_i32 m0, vcc_hi, 0x2000
	s_nop 0
	global_load_lds_dwordx4 v138, s[34:35]
	s_waitcnt vmcnt(6)
	s_waitcnt lgkmcnt(0)
	s_barrier
	v_mfma_f32_16x16x32_bf16 v[60:63], v[128:131], v[206:209], v[60:63]
	v_mfma_f32_16x16x32_bf16 v[60:63], v[148:151], v[210:213], v[60:63]
	v_mfma_f32_16x16x32_bf16 v[56:59], v[152:155], v[206:209], v[56:59]
	v_mfma_f32_16x16x32_bf16 v[56:59], v[158:161], v[210:213], v[56:59]
	v_mfma_f32_16x16x32_bf16 v[40:43], v[152:155], v[214:217], v[40:43]
	v_mfma_f32_16x16x32_bf16 v[40:43], v[158:161], v[218:221], v[40:43]
	v_mfma_f32_16x16x32_bf16 v[44:47], v[128:131], v[214:217], v[44:47]
	v_mfma_f32_16x16x32_bf16 v[44:47], v[148:151], v[218:221], v[44:47]
	v_mfma_f32_16x16x32_bf16 v[28:31], v[128:131], v[222:225], v[28:31]
	v_mfma_f32_16x16x32_bf16 v[28:31], v[148:151], v[226:229], v[28:31]
	v_mfma_f32_16x16x32_bf16 v[24:27], v[152:155], v[222:225], v[24:27]
	v_mfma_f32_16x16x32_bf16 v[24:27], v[158:161], v[226:229], v[24:27]
	v_mfma_f32_16x16x32_bf16 v[8:11], v[152:155], v[230:233], v[8:11]
	v_mfma_f32_16x16x32_bf16 v[8:11], v[158:161], v[234:237], v[8:11]
	v_mfma_f32_16x16x32_bf16 v[12:15], v[128:131], v[230:233], v[12:15]
	v_mfma_f32_16x16x32_bf16 v[12:15], v[148:151], v[234:237], v[12:15]
	v_mfma_f32_16x16x32_bf16 v[52:55], v[190:193], v[206:209], v[52:55]
	v_mfma_f32_16x16x32_bf16 v[52:55], v[194:197], v[210:213], v[52:55]
	v_mfma_f32_16x16x32_bf16 v[48:51], v[198:201], v[206:209], v[48:51]
	v_mfma_f32_16x16x32_bf16 v[48:51], v[202:205], v[210:213], v[48:51]
	v_mfma_f32_16x16x32_bf16 v[32:35], v[198:201], v[214:217], v[32:35]
	v_mfma_f32_16x16x32_bf16 v[32:35], v[202:205], v[218:221], v[32:35]
	v_mfma_f32_16x16x32_bf16 v[36:39], v[190:193], v[214:217], v[36:39]
	v_mfma_f32_16x16x32_bf16 v[36:39], v[194:197], v[218:221], v[36:39]
	v_mfma_f32_16x16x32_bf16 v[20:23], v[190:193], v[222:225], v[20:23]
	v_mfma_f32_16x16x32_bf16 v[20:23], v[194:197], v[226:229], v[20:23]
	v_mfma_f32_16x16x32_bf16 v[16:19], v[198:201], v[222:225], v[16:19]
	v_mfma_f32_16x16x32_bf16 v[16:19], v[202:205], v[226:229], v[16:19]
	v_mfma_f32_16x16x32_bf16 v[0:3], v[198:201], v[230:233], v[0:3]
	v_mfma_f32_16x16x32_bf16 v[0:3], v[202:205], v[234:237], v[0:3]
	v_mfma_f32_16x16x32_bf16 v[4:7], v[190:193], v[230:233], v[4:7]
	v_mfma_f32_16x16x32_bf16 v[4:7], v[194:197], v[234:237], v[4:7]
	s_barrier
; #define PG8_STAGE(bufoff, gbase, voff) do { _Pragma("unroll") for (int _i = 0; _i < 2; ++_i) \
;         __builtin_amdgcn_global_load_lds((const unsigned*)((const char*)(gbase) + (voff)[_i]), (PG8_LAS unsigned*)(lds + (bufoff) + ldsw + _i * 8192), 16, 0, 0); } while (0)
; #define PG8_LDA(dst, b, h) do { _Pragma("unroll") for (int m = 0; m < 4; ++m) _Pragma("unroll") for (int k = 0; k < 2; ++k) dst[m][k] = *(const PG8_LAS bf16x8*)(lds + PG8_SA(b, h) + aoff + m * 2048 + k * 1024); } while (0)
; #define PG8_LDB(dst, b, h) do { _Pragma("unroll") for (int n = 0; n < 2; ++n) _Pragma("unroll") for (int k = 0; k < 2; ++k) dst[n][k] = *(const PG8_LAS bf16x8*)(lds + PG8_SB(b, h) + boff + n * 2048 + k * 1024); } while (0)
; #define PG8_MMA(ai, bj, At, Bt) do { __builtin_amdgcn_s_setprio(1); _Pragma("unroll") for (int m = 0; m < 4; ++m) _Pragma("unroll") for (int n = 0; n < 2; ++n) _Pragma("unroll") for (int k = 0; k < 2; ++k) \
;         acc[ai][bj][m][n] = __builtin_amdgcn_mfma_f32_16x16x32_bf16(Bt[n][k], At[m][k], acc[ai][bj][m][n], 0, 0, 0); __builtin_amdgcn_s_setprio(0); } while (0)
; #define PG8_WAIT_V(n) asm volatile("s_waitcnt vmcnt(" #n ")" ::: "memory")
; #define PG8_WAIT_L(n) asm volatile("s_waitcnt lgkmcnt(" #n ")" ::: "memory")
; #define PG8_BAR __builtin_amdgcn_s_barrier()
; #define PG8_SCHED __builtin_amdgcn_sched_barrier(0)
; template <class Epi, class Sched, bool ALIGN_EPI = false, bool SP2 = false>
; __device__ __forceinline__ void gemm_phase(PG8_LAS unsigned char* lds, const Gemm g, const Sched& S, const Epi& E) {
;     ...
;             PG8_LDB(B0, 1, 0); PG8_LDB(B1, 1, 1); PG8_SCHED; PG8_LDA(At, 1, 0); PG8_STAGE(PG8_SA(0, 1), a2 + hstep, voffA);
;             PG8_WAIT_V(8); PG8_WAIT_L(0); PG8_BAR; PG8_MMA(0, 0, At, B0); PG8_MMA(0, 1, At, B1); PG8_BAR; PG8_SCHED;
;             PG8_LDA(At, 1, 1); PG8_STAGE(PG8_SB(1, 0), b3, voffB); PG8_STAGE(PG8_SB(1, 1), b3 + hstep, voffB); PG8_STAGE(PG8_SA(1, 0), a3, voffA);
;             PG8_WAIT_V(8); PG8_WAIT_L(0); PG8_BAR; PG8_MMA(1, 0, At, B0); PG8_MMA(1, 1, At, B1); PG8_BAR; PG8_SCHED;
	s_add_i32 vcc_hi, 0, 0x18000
	s_add_i32 s14, 0, 0x1c000
	v_add_u32_e32 v158, vcc_hi, v163
	v_add_u32_e32 v202, s14, v163
	ds_read_b128 v[128:131], v158
	ds_read_b128 v[148:151], v158 offset:1024
	ds_read_b128 v[152:155], v158 offset:2048
	ds_read_b128 v[158:161], v158 offset:3072
	ds_read_b128 v[190:193], v202
	ds_read_b128 v[194:197], v202 offset:1024
	ds_read_b128 v[198:201], v202 offset:2048
	ds_read_b128 v[202:205], v202 offset:3072
	s_add_u32 s34, s68, 0x40000
	s_addc_u32 s35, s69, 0
	s_mov_b32 m0, s74
	ds_read_b128 v[206:209], v186 offset:32768
	ds_read_b128 v[210:213], v186 offset:33792
	ds_read_b128 v[214:217], v186 offset:34816
	ds_read_b128 v[218:221], v186 offset:35840
	ds_read_b128 v[222:225], v186 offset:36864
	ds_read_b128 v[226:229], v186 offset:37888
	ds_read_b128 v[230:233], v186 offset:38912
	ds_read_b128 v[234:237], v186 offset:39936
	global_load_lds_dwordx4 v132, s[34:35]
	s_mov_b32 m0, s75
	s_nop 0
	global_load_lds_dwordx4 v136, s[34:35]
	s_mov_b32 m0, s65
	s_nop 0
	global_load_lds_dwordx4 v132, s[68:69]
	s_mov_b32 m0, s73
	s_nop 0
	global_load_lds_dwordx4 v136, s[68:69]
	s_waitcnt vmcnt(8)
	s_waitcnt lgkmcnt(0)
	s_barrier
	v_mfma_f32_16x16x32_bf16 v[124:127], v[128:131], v[206:209], v[124:127]
	v_mfma_f32_16x16x32_bf16 v[124:127], v[148:151], v[210:213], v[124:127]
	v_mfma_f32_16x16x32_bf16 v[120:123], v[152:155], v[206:209], v[120:123]
	v_mfma_f32_16x16x32_bf16 v[120:123], v[158:161], v[210:213], v[120:123]
	v_mfma_f32_16x16x32_bf16 v[104:107], v[152:155], v[214:217], v[104:107]
	v_mfma_f32_16x16x32_bf16 v[104:107], v[158:161], v[218:221], v[104:107]
	v_mfma_f32_16x16x32_bf16 v[108:111], v[128:131], v[214:217], v[108:111]
	v_mfma_f32_16x16x32_bf16 v[108:111], v[148:151], v[218:221], v[108:111]
	v_mfma_f32_16x16x32_bf16 v[92:95], v[128:131], v[222:225], v[92:95]
	v_mfma_f32_16x16x32_bf16 v[92:95], v[148:151], v[226:229], v[92:95]
	v_mfma_f32_16x16x32_bf16 v[88:91], v[152:155], v[222:225], v[88:91]
	v_mfma_f32_16x16x32_bf16 v[88:91], v[158:161], v[226:229], v[88:91]
	v_mfma_f32_16x16x32_bf16 v[72:75], v[152:155], v[230:233], v[72:75]
	v_mfma_f32_16x16x32_bf16 v[72:75], v[158:161], v[234:237], v[72:75]
	v_mfma_f32_16x16x32_bf16 v[76:79], v[128:131], v[230:233], v[76:79]
	v_mfma_f32_16x16x32_bf16 v[76:79], v[148:151], v[234:237], v[76:79]
	v_mfma_f32_16x16x32_bf16 v[116:119], v[190:193], v[206:209], v[116:119]
	v_mfma_f32_16x16x32_bf16 v[116:119], v[194:197], v[210:213], v[116:119]
	v_mfma_f32_16x16x32_bf16 v[112:115], v[198:201], v[206:209], v[112:115]
	v_mfma_f32_16x16x32_bf16 v[112:115], v[202:205], v[210:213], v[112:115]
	v_mfma_f32_16x16x32_bf16 v[96:99], v[198:201], v[214:217], v[96:99]
	v_mfma_f32_16x16x32_bf16 v[96:99], v[202:205], v[218:221], v[96:99]
	v_mfma_f32_16x16x32_bf16 v[100:103], v[190:193], v[214:217], v[100:103]
	v_mfma_f32_16x16x32_bf16 v[100:103], v[194:197], v[218:221], v[100:103]
	v_mfma_f32_16x16x32_bf16 v[84:87], v[190:193], v[222:225], v[84:87]
	v_mfma_f32_16x16x32_bf16 v[84:87], v[194:197], v[226:229], v[84:87]
	v_mfma_f32_16x16x32_bf16 v[80:83], v[198:201], v[222:225], v[80:83]
	v_mfma_f32_16x16x32_bf16 v[80:83], v[202:205], v[226:229], v[80:83]
	v_mfma_f32_16x16x32_bf16 v[64:67], v[198:201], v[230:233], v[64:67]
	v_mfma_f32_16x16x32_bf16 v[64:67], v[202:205], v[234:237], v[64:67]
	v_mfma_f32_16x16x32_bf16 v[68:71], v[190:193], v[230:233], v[68:71]
	v_mfma_f32_16x16x32_bf16 v[68:71], v[194:197], v[234:237], v[68:71]
	s_barrier
	s_add_i32 s15, vcc_hi, s71
	s_add_u32 s98, s66, s42
	s_addc_u32 s99, s67, s43
	s_add_u32 s100, s68, s42
	s_addc_u32 s101, s69, s43
	s_mov_b32 m0, s15
	ds_read_b128 v[206:209], v186 offset:49152
	ds_read_b128 v[210:213], v186 offset:50176
	ds_read_b128 v[214:217], v186 offset:51200
	ds_read_b128 v[218:221], v186 offset:52224
	ds_read_b128 v[222:225], v186 offset:53248
	ds_read_b128 v[226:229], v186 offset:54272
	ds_read_b128 v[230:233], v186 offset:55296
	ds_read_b128 v[234:237], v186 offset:56320
	global_load_lds_dwordx4 v134, s[98:99]
	s_add_i32 m0, s15, 0x2000
	s_add_u32 s34, s66, 0x40080
	s_addc_u32 s35, s67, 0
	s_add_i32 s14, s14, s71
	global_load_lds_dwordx4 v138, s[98:99]
	s_mov_b32 m0, s14
	s_nop 0
	global_load_lds_dwordx4 v134, s[34:35]
	s_add_i32 m0, s14, 0x2000
	s_nop 0
	global_load_lds_dwordx4 v138, s[34:35]
	s_mov_b32 m0, s78
	s_nop 0
	global_load_lds_dwordx4 v132, s[100:101]
	s_mov_b32 m0, s79
	s_nop 0
	global_load_lds_dwordx4 v136, s[100:101]
	s_waitcnt vmcnt(6)
	s_waitcnt lgkmcnt(0)
	s_barrier
	v_mfma_f32_16x16x32_bf16 v[60:63], v[128:131], v[206:209], v[60:63]
	v_mfma_f32_16x16x32_bf16 v[60:63], v[148:151], v[210:213], v[60:63]
	v_mfma_f32_16x16x32_bf16 v[56:59], v[152:155], v[206:209], v[56:59]
	v_mfma_f32_16x16x32_bf16 v[56:59], v[158:161], v[210:213], v[56:59]
	v_mfma_f32_16x16x32_bf16 v[40:43], v[152:155], v[214:217], v[40:43]
	v_mfma_f32_16x16x32_bf16 v[40:43], v[158:161], v[218:221], v[40:43]
	v_mfma_f32_16x16x32_bf16 v[44:47], v[128:131], v[214:217], v[44:47]
	v_mfma_f32_16x16x32_bf16 v[44:47], v[148:151], v[218:221], v[44:47]
	v_mfma_f32_16x16x32_bf16 v[28:31], v[128:131], v[222:225], v[28:31]
	v_mfma_f32_16x16x32_bf16 v[28:31], v[148:151], v[226:229], v[28:31]
	v_mfma_f32_16x16x32_bf16 v[24:27], v[152:155], v[222:225], v[24:27]
	v_mfma_f32_16x16x32_bf16 v[24:27], v[158:161], v[226:229], v[24:27]
	v_mfma_f32_16x16x32_bf16 v[8:11], v[152:155], v[230:233], v[8:11]
	v_mfma_f32_16x16x32_bf16 v[8:11], v[158:161], v[234:237], v[8:11]
	v_mfma_f32_16x16x32_bf16 v[12:15], v[128:131], v[230:233], v[12:15]
	v_mfma_f32_16x16x32_bf16 v[12:15], v[148:151], v[234:237], v[12:15]
	v_mfma_f32_16x16x32_bf16 v[52:55], v[190:193], v[206:209], v[52:55]
	v_mfma_f32_16x16x32_bf16 v[52:55], v[194:197], v[210:213], v[52:55]
	v_mfma_f32_16x16x32_bf16 v[48:51], v[198:201], v[206:209], v[48:51]
	v_mfma_f32_16x16x32_bf16 v[48:51], v[202:205], v[210:213], v[48:51]
	v_mfma_f32_16x16x32_bf16 v[32:35], v[198:201], v[214:217], v[32:35]
	v_mfma_f32_16x16x32_bf16 v[32:35], v[202:205], v[218:221], v[32:35]
	v_mfma_f32_16x16x32_bf16 v[36:39], v[190:193], v[214:217], v[36:39]
	v_mfma_f32_16x16x32_bf16 v[36:39], v[194:197], v[218:221], v[36:39]
	v_mfma_f32_16x16x32_bf16 v[20:23], v[190:193], v[222:225], v[20:23]
	v_mfma_f32_16x16x32_bf16 v[20:23], v[194:197], v[226:229], v[20:23]
	v_mfma_f32_16x16x32_bf16 v[16:19], v[198:201], v[222:225], v[16:19]
	v_mfma_f32_16x16x32_bf16 v[16:19], v[202:205], v[226:229], v[16:19]
	v_mfma_f32_16x16x32_bf16 v[0:3], v[198:201], v[230:233], v[0:3]
	v_mfma_f32_16x16x32_bf16 v[0:3], v[202:205], v[234:237], v[0:3]
	v_mfma_f32_16x16x32_bf16 v[4:7], v[190:193], v[230:233], v[4:7]
	v_mfma_f32_16x16x32_bf16 v[4:7], v[194:197], v[234:237], v[4:7]
	s_barrier
	s_add_i32 vcc_lo, vcc_lo, 2
	s_add_u32 s96, s96, 0x100
	s_addc_u32 s97, s97, 0
	s_add_u32 s10, s10, 0x100
	s_addc_u32 s11, s11, 0
	s_cmp_gt_u32 vcc_lo, 13
	s_cbranch_scc0 .LBB0_510
	s_and_b64 vcc, exec, s[44:45]
	s_cbranch_vccz .LBB0_513
	s_barrier

; #define PG8_STAGE(bufoff, gbase, voff) do { _Pragma("unroll") for (int _i = 0; _i < 2; ++_i) \
;         __builtin_amdgcn_global_load_lds((const unsigned*)((const char*)(gbase) + (voff)[_i]), (PG8_LAS unsigned*)(lds + (bufoff) + ldsw + _i * 8192), 16, 0, 0); } while (0)
; #define PG8_LDA(dst, b, h) do { _Pragma("unroll") for (int m = 0; m < 4; ++m) _Pragma("unroll") for (int k = 0; k < 2; ++k) dst[m][k] = *(const PG8_LAS bf16x8*)(lds + PG8_SA(b, h) + aoff + m * 2048 + k * 1024); } while (0)
; #define PG8_LDB(dst, b, h) do { _Pragma("unroll") for (int n = 0; n < 2; ++n) _Pragma("unroll") for (int k = 0; k < 2; ++k) dst[n][k] = *(const PG8_LAS bf16x8*)(lds + PG8_SB(b, h) + boff + n * 2048 + k * 1024); } while (0)
; #define PG8_MMA(ai, bj, At, Bt) do { __builtin_amdgcn_s_setprio(1); _Pragma("unroll") for (int m = 0; m < 4; ++m) _Pragma("unroll") for (int n = 0; n < 2; ++n) _Pragma("unroll") for (int k = 0; k < 2; ++k) \
;         acc[ai][bj][m][n] = __builtin_amdgcn_mfma_f32_16x16x32_bf16(Bt[n][k], At[m][k], acc[ai][bj][m][n], 0, 0, 0); __builtin_amdgcn_s_setprio(0); } while (0)
; #define PG8_WAIT_V(n) asm volatile("s_waitcnt vmcnt(" #n ")" ::: "memory")
; #define PG8_WAIT_L(n) asm volatile("s_waitcnt lgkmcnt(" #n ")" ::: "memory")
; #define PG8_BAR __builtin_amdgcn_s_barrier()
; #define PG8_SCHED __builtin_amdgcn_sched_barrier(0)
; template <class Epi, class Sched, bool ALIGN_EPI = false, bool SP2 = false>
; __device__ __forceinline__ void gemm_phase(PG8_LAS unsigned char* lds, const Gemm g, const Sched& S, const Epi& E) {
;     ...
;             PG8_LDB(B0, 0, 0); PG8_LDB(B1, 0, 1); PG8_SCHED; PG8_LDA(At, 0, 0); PG8_STAGE(PG8_SA(1, 1), a1 + hstep, voffA);
;             PG8_WAIT_V(8); PG8_WAIT_L(0); PG8_BAR; PG8_MMA(0, 0, At, B0); PG8_MMA(0, 1, At, B1); PG8_BAR; PG8_SCHED;
;             PG8_LDA(At, 0, 1); PG8_STAGE(PG8_SB(0, 0), b2, voffB); PG8_STAGE(PG8_SB(0, 1), b2 + hstep, voffB); PG8_STAGE(PG8_SA(0, 0), a2, voffA);
;             PG8_WAIT_V(8); PG8_WAIT_L(0); PG8_BAR; PG8_MMA(1, 0, At, B0); PG8_MMA(1, 1, At, B1); PG8_BAR; PG8_SCHED;
.LBB0_710:
	ds_read_b128 v[128:131], v169
	ds_read_b128 v[132:135], v169 offset:1024
	ds_read_b128 v[136:139], v169 offset:2048
	ds_read_b128 v[140:143], v169 offset:3072
	ds_read_b128 v[162:165], v170
	ds_read_b128 v[172:175], v170 offset:1024
	ds_read_b128 v[176:179], v170 offset:2048
	ds_read_b128 v[184:187], v170 offset:3072
	s_add_u32 s14, s54, 0xfffc0080
	s_addc_u32 s15, s55, -1
	s_cmp_eq_u32 s84, 12
	s_cselect_b32 s59, s45, s15
	s_cselect_b32 s58, s51, s14
	s_cselect_b32 s57, s43, s83
	s_cselect_b32 s56, s53, s82
	s_add_i32 m0, s64, 0xc000
	ds_read_b128 v[188:191], v171
	ds_read_b128 v[192:195], v171 offset:1024
	ds_read_b128 v[196:199], v171 offset:2048
	ds_read_b128 v[200:203], v171 offset:3072
	ds_read_b128 v[204:207], v171 offset:4096
	ds_read_b128 v[208:211], v171 offset:5120
	ds_read_b128 v[212:215], v171 offset:6144
	ds_read_b128 v[216:219], v171 offset:7168
	global_load_lds_dwordx4 v154, s[54:55]
	s_add_i32 m0, s64, 0xe000
	s_nop 0
	global_load_lds_dwordx4 v152, s[54:55]
	s_waitcnt vmcnt(8)
	s_waitcnt lgkmcnt(0)
	s_barrier
	v_mfma_f32_16x16x32_bf16 v[124:127], v[128:131], v[188:191], v[124:127]
	v_mfma_f32_16x16x32_bf16 v[124:127], v[132:135], v[192:195], v[124:127]
	v_mfma_f32_16x16x32_bf16 v[120:123], v[136:139], v[188:191], v[120:123]
	v_mfma_f32_16x16x32_bf16 v[120:123], v[140:143], v[192:195], v[120:123]
	v_mfma_f32_16x16x32_bf16 v[108:111], v[136:139], v[196:199], v[108:111]
	v_mfma_f32_16x16x32_bf16 v[108:111], v[140:143], v[200:203], v[108:111]
	v_mfma_f32_16x16x32_bf16 v[116:119], v[128:131], v[196:199], v[116:119]
	v_mfma_f32_16x16x32_bf16 v[116:119], v[132:135], v[200:203], v[116:119]
	v_mfma_f32_16x16x32_bf16 v[100:103], v[128:131], v[204:207], v[100:103]
	v_mfma_f32_16x16x32_bf16 v[100:103], v[132:135], v[208:211], v[100:103]
	v_mfma_f32_16x16x32_bf16 v[92:95], v[136:139], v[204:207], v[92:95]
	v_mfma_f32_16x16x32_bf16 v[92:95], v[140:143], v[208:211], v[92:95]
	v_mfma_f32_16x16x32_bf16 v[76:79], v[136:139], v[212:215], v[76:79]
	v_mfma_f32_16x16x32_bf16 v[76:79], v[140:143], v[216:219], v[76:79]
	v_mfma_f32_16x16x32_bf16 v[84:87], v[128:131], v[212:215], v[84:87]
	v_mfma_f32_16x16x32_bf16 v[84:87], v[132:135], v[216:219], v[84:87]
	v_mfma_f32_16x16x32_bf16 v[112:115], v[162:165], v[188:191], v[112:115]
	v_mfma_f32_16x16x32_bf16 v[112:115], v[172:175], v[192:195], v[112:115]
	v_mfma_f32_16x16x32_bf16 v[104:107], v[176:179], v[188:191], v[104:107]
	v_mfma_f32_16x16x32_bf16 v[104:107], v[184:187], v[192:195], v[104:107]
	v_mfma_f32_16x16x32_bf16 v[88:91], v[176:179], v[196:199], v[88:91]
	v_mfma_f32_16x16x32_bf16 v[88:91], v[184:187], v[200:203], v[88:91]
	v_mfma_f32_16x16x32_bf16 v[96:99], v[162:165], v[196:199], v[96:99]
	v_mfma_f32_16x16x32_bf16 v[96:99], v[172:175], v[200:203], v[96:99]
	v_mfma_f32_16x16x32_bf16 v[80:83], v[162:165], v[204:207], v[80:83]
	v_mfma_f32_16x16x32_bf16 v[80:83], v[172:175], v[208:211], v[80:83]
	v_mfma_f32_16x16x32_bf16 v[72:75], v[176:179], v[204:207], v[72:75]
	v_mfma_f32_16x16x32_bf16 v[72:75], v[184:187], v[208:211], v[72:75]
	v_mfma_f32_16x16x32_bf16 v[64:67], v[176:179], v[212:215], v[64:67]
	v_mfma_f32_16x16x32_bf16 v[64:67], v[184:187], v[216:219], v[64:67]
	v_mfma_f32_16x16x32_bf16 v[68:71], v[162:165], v[212:215], v[68:71]
	v_mfma_f32_16x16x32_bf16 v[68:71], v[172:175], v[216:219], v[68:71]
	s_barrier
	s_add_i32 s14, s80, s63
	s_mov_b32 m0, s14
	ds_read_b128 v[188:191], v171 offset:16384
	ds_read_b128 v[192:195], v171 offset:17408
	ds_read_b128 v[196:199], v171 offset:18432
	ds_read_b128 v[200:203], v171 offset:19456
	ds_read_b128 v[204:207], v171 offset:20480
	ds_read_b128 v[208:211], v171 offset:21504
	ds_read_b128 v[212:215], v171 offset:22528
	ds_read_b128 v[216:219], v171 offset:23552
	global_load_lds_dwordx4 v146, s[56:57]
	s_add_i32 m0, s14, 0x2000
	s_add_u32 s34, s56, 0x40000
	s_addc_u32 s35, s57, 0
	s_add_i32 s14, s81, s63
	global_load_lds_dwordx4 v150, s[56:57]
	s_mov_b32 m0, s14
	s_nop 0
	global_load_lds_dwordx4 v146, s[34:35]
	s_add_i32 m0, s14, 0x2000
	s_nop 0
	global_load_lds_dwordx4 v150, s[34:35]
	s_waitcnt vmcnt(6)
	s_waitcnt lgkmcnt(0)
	s_barrier
	v_mfma_f32_16x16x32_bf16 v[60:63], v[128:131], v[188:191], v[60:63]
	v_mfma_f32_16x16x32_bf16 v[60:63], v[132:135], v[192:195], v[60:63]
	v_mfma_f32_16x16x32_bf16 v[56:59], v[136:139], v[188:191], v[56:59]
	v_mfma_f32_16x16x32_bf16 v[56:59], v[140:143], v[192:195], v[56:59]
	v_mfma_f32_16x16x32_bf16 v[44:47], v[136:139], v[196:199], v[44:47]
	v_mfma_f32_16x16x32_bf16 v[44:47], v[140:143], v[200:203], v[44:47]
	v_mfma_f32_16x16x32_bf16 v[48:51], v[128:131], v[196:199], v[48:51]
	v_mfma_f32_16x16x32_bf16 v[48:51], v[132:135], v[200:203], v[48:51]
	v_mfma_f32_16x16x32_bf16 v[36:39], v[128:131], v[204:207], v[36:39]
	v_mfma_f32_16x16x32_bf16 v[36:39], v[132:135], v[208:211], v[36:39]
	v_mfma_f32_16x16x32_bf16 v[28:31], v[136:139], v[204:207], v[28:31]
	v_mfma_f32_16x16x32_bf16 v[28:31], v[140:143], v[208:211], v[28:31]
	v_mfma_f32_16x16x32_bf16 v[12:15], v[136:139], v[212:215], v[12:15]
	v_mfma_f32_16x16x32_bf16 v[12:15], v[140:143], v[216:219], v[12:15]
	v_mfma_f32_16x16x32_bf16 v[20:23], v[128:131], v[212:215], v[20:23]
	v_mfma_f32_16x16x32_bf16 v[20:23], v[132:135], v[216:219], v[20:23]
	v_mfma_f32_16x16x32_bf16 v[52:55], v[162:165], v[188:191], v[52:55]
	v_mfma_f32_16x16x32_bf16 v[52:55], v[172:175], v[192:195], v[52:55]
	v_mfma_f32_16x16x32_bf16 v[40:43], v[176:179], v[188:191], v[40:43]
	v_mfma_f32_16x16x32_bf16 v[40:43], v[184:187], v[192:195], v[40:43]
	v_mfma_f32_16x16x32_bf16 v[24:27], v[176:179], v[196:199], v[24:27]
	v_mfma_f32_16x16x32_bf16 v[24:27], v[184:187], v[200:203], v[24:27]
	v_mfma_f32_16x16x32_bf16 v[32:35], v[162:165], v[196:199], v[32:35]
	v_mfma_f32_16x16x32_bf16 v[32:35], v[172:175], v[200:203], v[32:35]
	v_mfma_f32_16x16x32_bf16 v[16:19], v[162:165], v[204:207], v[16:19]
	v_mfma_f32_16x16x32_bf16 v[16:19], v[172:175], v[208:211], v[16:19]
	v_mfma_f32_16x16x32_bf16 v[8:11], v[176:179], v[204:207], v[8:11]
	v_mfma_f32_16x16x32_bf16 v[8:11], v[184:187], v[208:211], v[8:11]
	v_mfma_f32_16x16x32_bf16 v[0:3], v[176:179], v[212:215], v[0:3]
	v_mfma_f32_16x16x32_bf16 v[0:3], v[184:187], v[216:219], v[0:3]
	v_mfma_f32_16x16x32_bf16 v[4:7], v[162:165], v[212:215], v[4:7]
	v_mfma_f32_16x16x32_bf16 v[4:7], v[172:175], v[216:219], v[4:7]
	s_barrier
; #define PG8_STAGE(bufoff, gbase, voff) do { _Pragma("unroll") for (int _i = 0; _i < 2; ++_i) \
;         __builtin_amdgcn_global_load_lds((const unsigned*)((const char*)(gbase) + (voff)[_i]), (PG8_LAS unsigned*)(lds + (bufoff) + ldsw + _i * 8192), 16, 0, 0); } while (0)
; #define PG8_LDA(dst, b, h) do { _Pragma("unroll") for (int m = 0; m < 4; ++m) _Pragma("unroll") for (int k = 0; k < 2; ++k) dst[m][k] = *(const PG8_LAS bf16x8*)(lds + PG8_SA(b, h) + aoff + m * 2048 + k * 1024); } while (0)
; #define PG8_LDB(dst, b, h) do { _Pragma("unroll") for (int n = 0; n < 2; ++n) _Pragma("unroll") for (int k = 0; k < 2; ++k) dst[n][k] = *(const PG8_LAS bf16x8*)(lds + PG8_SB(b, h) + boff + n * 2048 + k * 1024); } while (0)
; #define PG8_MMA(ai, bj, At, Bt) do { __builtin_amdgcn_s_setprio(1); _Pragma("unroll") for (int m = 0; m < 4; ++m) _Pragma("unroll") for (int n = 0; n < 2; ++n) _Pragma("unroll") for (int k = 0; k < 2; ++k) \
;         acc[ai][bj][m][n] = __builtin_amdgcn_mfma_f32_16x16x32_bf16(Bt[n][k], At[m][k], acc[ai][bj][m][n], 0, 0, 0); __builtin_amdgcn_s_setprio(0); } while (0)
; #define PG8_WAIT_V(n) asm volatile("s_waitcnt vmcnt(" #n ")" ::: "memory")
; #define PG8_WAIT_L(n) asm volatile("s_waitcnt lgkmcnt(" #n ")" ::: "memory")
; #define PG8_BAR __builtin_amdgcn_s_barrier()
; #define PG8_SCHED __builtin_amdgcn_sched_barrier(0)
; template <class Epi, class Sched, bool ALIGN_EPI = false, bool SP2 = false>
; __device__ __forceinline__ void gemm_phase(PG8_LAS unsigned char* lds, const Gemm g, const Sched& S, const Epi& E) {
;     ...
;             PG8_LDB(B0, 1, 0); PG8_LDB(B1, 1, 1); PG8_SCHED; PG8_LDA(At, 1, 0); PG8_STAGE(PG8_SA(0, 1), a2 + hstep, voffA);
;             PG8_WAIT_V(8); PG8_WAIT_L(0); PG8_BAR; PG8_MMA(0, 0, At, B0); PG8_MMA(0, 1, At, B1); PG8_BAR; PG8_SCHED;
;             PG8_LDA(At, 1, 1); PG8_STAGE(PG8_SB(1, 0), b3, voffB); PG8_STAGE(PG8_SB(1, 1), b3 + hstep, voffB); PG8_STAGE(PG8_SA(1, 0), a3, voffA);
;             PG8_WAIT_V(8); PG8_WAIT_L(0); PG8_BAR; PG8_MMA(1, 0, At, B0); PG8_MMA(1, 1, At, B1); PG8_BAR; PG8_SCHED;
	s_add_i32 s14, 0, 0x18000
	s_add_i32 s15, 0, 0x1c000
	v_add_u32_e32 v140, s14, v167
	v_add_u32_e32 v183, s15, v167
	ds_read_b128 v[128:131], v140
	ds_read_b128 v[132:135], v140 offset:1024
	ds_read_b128 v[136:139], v140 offset:2048
	ds_read_b128 v[140:143], v140 offset:3072
	ds_read_b128 v[162:165], v183
	ds_read_b128 v[172:175], v183 offset:1024
	ds_read_b128 v[176:179], v183 offset:2048
	ds_read_b128 v[184:187], v183 offset:3072
	s_add_u32 s34, s58, 0x40000
	s_addc_u32 s35, s59, 0
	s_mov_b32 m0, s66
	ds_read_b128 v[188:191], v171 offset:32768
	ds_read_b128 v[192:195], v171 offset:33792
	ds_read_b128 v[196:199], v171 offset:34816
	ds_read_b128 v[200:203], v171 offset:35840
	ds_read_b128 v[204:207], v171 offset:36864
	ds_read_b128 v[208:211], v171 offset:37888
	ds_read_b128 v[212:215], v171 offset:38912
	ds_read_b128 v[216:219], v171 offset:39936
	global_load_lds_dwordx4 v144, s[34:35]
	s_mov_b32 m0, s67
	s_nop 0
	global_load_lds_dwordx4 v148, s[34:35]
	s_mov_b32 m0, s64
	s_nop 0
	global_load_lds_dwordx4 v144, s[58:59]
	s_mov_b32 m0, s65
	s_nop 0
	global_load_lds_dwordx4 v148, s[58:59]
	s_waitcnt vmcnt(8)
	s_waitcnt lgkmcnt(0)
	s_barrier
	v_mfma_f32_16x16x32_bf16 v[124:127], v[128:131], v[188:191], v[124:127]
	v_mfma_f32_16x16x32_bf16 v[124:127], v[132:135], v[192:195], v[124:127]
	v_mfma_f32_16x16x32_bf16 v[120:123], v[136:139], v[188:191], v[120:123]
	v_mfma_f32_16x16x32_bf16 v[120:123], v[140:143], v[192:195], v[120:123]
	v_mfma_f32_16x16x32_bf16 v[108:111], v[136:139], v[196:199], v[108:111]
	v_mfma_f32_16x16x32_bf16 v[108:111], v[140:143], v[200:203], v[108:111]
	v_mfma_f32_16x16x32_bf16 v[116:119], v[128:131], v[196:199], v[116:119]
	v_mfma_f32_16x16x32_bf16 v[116:119], v[132:135], v[200:203], v[116:119]
	v_mfma_f32_16x16x32_bf16 v[100:103], v[128:131], v[204:207], v[100:103]
	v_mfma_f32_16x16x32_bf16 v[100:103], v[132:135], v[208:211], v[100:103]
	v_mfma_f32_16x16x32_bf16 v[92:95], v[136:139], v[204:207], v[92:95]
	v_mfma_f32_16x16x32_bf16 v[92:95], v[140:143], v[208:211], v[92:95]
	v_mfma_f32_16x16x32_bf16 v[76:79], v[136:139], v[212:215], v[76:79]
	v_mfma_f32_16x16x32_bf16 v[76:79], v[140:143], v[216:219], v[76:79]
	v_mfma_f32_16x16x32_bf16 v[84:87], v[128:131], v[212:215], v[84:87]
	v_mfma_f32_16x16x32_bf16 v[84:87], v[132:135], v[216:219], v[84:87]
	v_mfma_f32_16x16x32_bf16 v[112:115], v[162:165], v[188:191], v[112:115]
	v_mfma_f32_16x16x32_bf16 v[112:115], v[172:175], v[192:195], v[112:115]
	v_mfma_f32_16x16x32_bf16 v[104:107], v[176:179], v[188:191], v[104:107]
	v_mfma_f32_16x16x32_bf16 v[104:107], v[184:187], v[192:195], v[104:107]
	v_mfma_f32_16x16x32_bf16 v[88:91], v[176:179], v[196:199], v[88:91]
	v_mfma_f32_16x16x32_bf16 v[88:91], v[184:187], v[200:203], v[88:91]
	v_mfma_f32_16x16x32_bf16 v[96:99], v[162:165], v[196:199], v[96:99]
	v_mfma_f32_16x16x32_bf16 v[96:99], v[172:175], v[200:203], v[96:99]
	v_mfma_f32_16x16x32_bf16 v[80:83], v[162:165], v[204:207], v[80:83]
	v_mfma_f32_16x16x32_bf16 v[80:83], v[172:175], v[208:211], v[80:83]
	v_mfma_f32_16x16x32_bf16 v[72:75], v[176:179], v[204:207], v[72:75]
	v_mfma_f32_16x16x32_bf16 v[72:75], v[184:187], v[208:211], v[72:75]
	v_mfma_f32_16x16x32_bf16 v[64:67], v[176:179], v[212:215], v[64:67]
	v_mfma_f32_16x16x32_bf16 v[64:67], v[184:187], v[216:219], v[64:67]
	v_mfma_f32_16x16x32_bf16 v[68:71], v[162:165], v[212:215], v[68:71]
	v_mfma_f32_16x16x32_bf16 v[68:71], v[172:175], v[216:219], v[68:71]
	s_barrier
	s_add_i32 s14, s14, s63
	s_add_u32 s98, s56, s36
	s_addc_u32 s99, s57, s37
	s_add_u32 s100, s58, s36
	s_addc_u32 s101, s59, s37
	s_mov_b32 m0, s14
	ds_read_b128 v[188:191], v171 offset:49152
	ds_read_b128 v[192:195], v171 offset:50176
	ds_read_b128 v[196:199], v171 offset:51200
	ds_read_b128 v[200:203], v171 offset:52224
	ds_read_b128 v[204:207], v171 offset:53248
	ds_read_b128 v[208:211], v171 offset:54272
	ds_read_b128 v[212:215], v171 offset:55296
	ds_read_b128 v[216:219], v171 offset:56320
	global_load_lds_dwordx4 v146, s[98:99]
	s_add_i32 m0, s14, 0x2000
	s_add_u32 s34, s56, 0x40080
	s_addc_u32 s35, s57, 0
	s_add_i32 s14, s15, s63
	global_load_lds_dwordx4 v150, s[98:99]
	s_mov_b32 m0, s14
	s_nop 0
	global_load_lds_dwordx4 v146, s[34:35]
	s_add_i32 m0, s14, 0x2000
	s_nop 0
	global_load_lds_dwordx4 v150, s[34:35]
	s_mov_b32 m0, s74
	s_nop 0
	global_load_lds_dwordx4 v144, s[100:101]
	s_mov_b32 m0, s75
	s_nop 0
	global_load_lds_dwordx4 v148, s[100:101]
	s_waitcnt vmcnt(6)
	s_waitcnt lgkmcnt(0)
	s_barrier
	v_mfma_f32_16x16x32_bf16 v[60:63], v[128:131], v[188:191], v[60:63]
	v_mfma_f32_16x16x32_bf16 v[60:63], v[132:135], v[192:195], v[60:63]
	v_mfma_f32_16x16x32_bf16 v[56:59], v[136:139], v[188:191], v[56:59]
	v_mfma_f32_16x16x32_bf16 v[56:59], v[140:143], v[192:195], v[56:59]
	v_mfma_f32_16x16x32_bf16 v[44:47], v[136:139], v[196:199], v[44:47]
	v_mfma_f32_16x16x32_bf16 v[44:47], v[140:143], v[200:203], v[44:47]
	v_mfma_f32_16x16x32_bf16 v[48:51], v[128:131], v[196:199], v[48:51]
	v_mfma_f32_16x16x32_bf16 v[48:51], v[132:135], v[200:203], v[48:51]
	v_mfma_f32_16x16x32_bf16 v[36:39], v[128:131], v[204:207], v[36:39]
	v_mfma_f32_16x16x32_bf16 v[36:39], v[132:135], v[208:211], v[36:39]
	v_mfma_f32_16x16x32_bf16 v[28:31], v[136:139], v[204:207], v[28:31]
	v_mfma_f32_16x16x32_bf16 v[28:31], v[140:143], v[208:211], v[28:31]
	v_mfma_f32_16x16x32_bf16 v[12:15], v[136:139], v[212:215], v[12:15]
	v_mfma_f32_16x16x32_bf16 v[12:15], v[140:143], v[216:219], v[12:15]
	v_mfma_f32_16x16x32_bf16 v[20:23], v[128:131], v[212:215], v[20:23]
	v_mfma_f32_16x16x32_bf16 v[20:23], v[132:135], v[216:219], v[20:23]
	v_mfma_f32_16x16x32_bf16 v[52:55], v[162:165], v[188:191], v[52:55]
	v_mfma_f32_16x16x32_bf16 v[52:55], v[172:175], v[192:195], v[52:55]
	v_mfma_f32_16x16x32_bf16 v[40:43], v[176:179], v[188:191], v[40:43]
	v_mfma_f32_16x16x32_bf16 v[40:43], v[184:187], v[192:195], v[40:43]
	v_mfma_f32_16x16x32_bf16 v[24:27], v[176:179], v[196:199], v[24:27]
	v_mfma_f32_16x16x32_bf16 v[24:27], v[184:187], v[200:203], v[24:27]
	v_mfma_f32_16x16x32_bf16 v[32:35], v[162:165], v[196:199], v[32:35]
	v_mfma_f32_16x16x32_bf16 v[32:35], v[172:175], v[200:203], v[32:35]
	v_mfma_f32_16x16x32_bf16 v[16:19], v[162:165], v[204:207], v[16:19]
	v_mfma_f32_16x16x32_bf16 v[16:19], v[172:175], v[208:211], v[16:19]
	v_mfma_f32_16x16x32_bf16 v[8:11], v[176:179], v[204:207], v[8:11]
	v_mfma_f32_16x16x32_bf16 v[8:11], v[184:187], v[208:211], v[8:11]
	v_mfma_f32_16x16x32_bf16 v[0:3], v[176:179], v[212:215], v[0:3]
	v_mfma_f32_16x16x32_bf16 v[0:3], v[184:187], v[216:219], v[0:3]
	v_mfma_f32_16x16x32_bf16 v[4:7], v[162:165], v[212:215], v[4:7]
	v_mfma_f32_16x16x32_bf16 v[4:7], v[172:175], v[216:219], v[4:7]
	s_barrier
	s_add_i32 s84, s84, 2
	s_add_u32 s82, s82, 0x100
	s_addc_u32 s83, s83, 0
	s_add_u32 s54, s54, 0x100
	s_addc_u32 s55, s55, 0
	s_cmp_gt_u32 s84, 13
	s_cbranch_scc0 .LBB0_710
	s_and_b64 vcc, exec, s[40:41]
	s_cbranch_vccz .LBB0_713
	s_barrier

; #define PG8_STAGE(bufoff, gbase, voff) do { _Pragma("unroll") for (int _i = 0; _i < 2; ++_i) \
;         __builtin_amdgcn_global_load_lds((const unsigned*)((const char*)(gbase) + (voff)[_i]), (PG8_LAS unsigned*)(lds + (bufoff) + ldsw + _i * 8192), 16, 0, 0); } while (0)
; #define PG8_LDA(dst, b, h) do { _Pragma("unroll") for (int m = 0; m < 4; ++m) _Pragma("unroll") for (int k = 0; k < 2; ++k) dst[m][k] = *(const PG8_LAS bf16x8*)(lds + PG8_SA(b, h) + aoff + m * 2048 + k * 1024); } while (0)
; #define PG8_LDB(dst, b, h) do { _Pragma("unroll") for (int n = 0; n < 2; ++n) _Pragma("unroll") for (int k = 0; k < 2; ++k) dst[n][k] = *(const PG8_LAS bf16x8*)(lds + PG8_SB(b, h) + boff + n * 2048 + k * 1024); } while (0)
; #define PG8_MMA(ai, bj, At, Bt) do { __builtin_amdgcn_s_setprio(1); _Pragma("unroll") for (int m = 0; m < 4; ++m) _Pragma("unroll") for (int n = 0; n < 2; ++n) _Pragma("unroll") for (int k = 0; k < 2; ++k) \
;         acc[ai][bj][m][n] = __builtin_amdgcn_mfma_f32_16x16x32_bf16(Bt[n][k], At[m][k], acc[ai][bj][m][n], 0, 0, 0); __builtin_amdgcn_s_setprio(0); } while (0)
; #define PG8_WAIT_V(n) asm volatile("s_waitcnt vmcnt(" #n ")" ::: "memory")
; #define PG8_WAIT_L(n) asm volatile("s_waitcnt lgkmcnt(" #n ")" ::: "memory")
; #define PG8_BAR __builtin_amdgcn_s_barrier()
; #define PG8_SCHED __builtin_amdgcn_sched_barrier(0)
; template <class Epi, class Sched, bool ALIGN_EPI = false, bool SP2 = false>
; __device__ __forceinline__ void gemm_phase(PG8_LAS unsigned char* lds, const Gemm g, const Sched& S, const Epi& E) {
;     ...
;             PG8_LDB(B0, 0, 0); PG8_LDB(B1, 0, 1); PG8_SCHED; PG8_LDA(At, 0, 0); PG8_STAGE(PG8_SA(1, 1), a1 + hstep, voffA);
;             PG8_WAIT_V(8); PG8_WAIT_L(0); PG8_BAR; PG8_MMA(0, 0, At, B0); PG8_MMA(0, 1, At, B1); PG8_BAR; PG8_SCHED;
;             PG8_LDA(At, 0, 1); PG8_STAGE(PG8_SB(0, 0), b2, voffB); PG8_STAGE(PG8_SB(0, 1), b2 + hstep, voffB); PG8_STAGE(PG8_SA(0, 0), a2, voffA);
;             PG8_WAIT_V(8); PG8_WAIT_L(0); PG8_BAR; PG8_MMA(1, 0, At, B0); PG8_MMA(1, 1, At, B1); PG8_BAR; PG8_SCHED;
.LBB0_796:
	v_add_u32_e32 v130, s76, v165
	ds_read_b128 v[118:121], v130
	ds_read_b128 v[122:125], v130 offset:1024
	ds_read_b128 v[126:129], v130 offset:2048
	ds_read_b128 v[172:175], v130 offset:3072
	v_add_u32_e32 v130, s77, v165
	ds_read_b128 v[176:179], v130
	ds_read_b128 v[184:187], v130 offset:1024
	ds_read_b128 v[188:191], v130 offset:2048
	ds_read_b128 v[192:195], v130 offset:3072
	s_add_u32 s12, s52, 0xfffc0080
	s_addc_u32 s13, s53, -1
	s_and_b64 s[34:35], s[54:55], exec
	s_cselect_b32 s57, s43, s13
	s_cselect_b32 s56, s78, s12
	s_cselect_b32 s55, s41, s51
	s_cselect_b32 s54, s79, s49
	s_add_i32 m0, s62, 0xc000
	ds_read_b128 v[196:199], v170
	ds_read_b128 v[200:203], v170 offset:1024
	ds_read_b128 v[204:207], v170 offset:2048
	ds_read_b128 v[208:211], v170 offset:3072
	ds_read_b128 v[212:215], v170 offset:4096
	ds_read_b128 v[216:219], v170 offset:5120
	ds_read_b128 v[220:223], v170 offset:6144
	ds_read_b128 v[224:227], v170 offset:7168
	global_load_lds_dwordx4 v154, s[52:53]
	s_add_i32 m0, s62, 0xe000
	s_nop 0
	global_load_lds_dwordx4 v152, s[52:53]
	s_waitcnt vmcnt(8)
	s_waitcnt lgkmcnt(0)
	s_barrier
	v_mfma_f32_16x16x32_bf16 v[140:143], v[118:121], v[196:199], v[140:143]
	v_mfma_f32_16x16x32_bf16 v[140:143], v[122:125], v[200:203], v[140:143]
	v_mfma_f32_16x16x32_bf16 v[136:139], v[126:129], v[196:199], v[136:139]
	v_mfma_f32_16x16x32_bf16 v[136:139], v[172:175], v[200:203], v[136:139]
	v_mfma_f32_16x16x32_bf16 v[104:107], v[126:129], v[204:207], v[104:107]
	v_mfma_f32_16x16x32_bf16 v[104:107], v[172:175], v[208:211], v[104:107]
	v_mfma_f32_16x16x32_bf16 v[108:111], v[118:121], v[204:207], v[108:111]
	v_mfma_f32_16x16x32_bf16 v[108:111], v[122:125], v[208:211], v[108:111]
	v_mfma_f32_16x16x32_bf16 v[92:95], v[118:121], v[212:215], v[92:95]
	v_mfma_f32_16x16x32_bf16 v[92:95], v[122:125], v[216:219], v[92:95]
	v_mfma_f32_16x16x32_bf16 v[88:91], v[126:129], v[212:215], v[88:91]
	v_mfma_f32_16x16x32_bf16 v[88:91], v[172:175], v[216:219], v[88:91]
	v_mfma_f32_16x16x32_bf16 v[72:75], v[126:129], v[220:223], v[72:75]
	v_mfma_f32_16x16x32_bf16 v[72:75], v[172:175], v[224:227], v[72:75]
	v_mfma_f32_16x16x32_bf16 v[76:79], v[118:121], v[220:223], v[76:79]
	v_mfma_f32_16x16x32_bf16 v[76:79], v[122:125], v[224:227], v[76:79]
	v_mfma_f32_16x16x32_bf16 v[130:133], v[176:179], v[196:199], v[132:135]
	v_mfma_f32_16x16x32_bf16 v[130:133], v[184:187], v[200:203], v[130:133]
	v_mfma_f32_16x16x32_bf16 v[112:115], v[188:191], v[196:199], v[112:115]
	v_mfma_f32_16x16x32_bf16 v[112:115], v[192:195], v[200:203], v[112:115]
	v_mfma_f32_16x16x32_bf16 v[96:99], v[188:191], v[204:207], v[96:99]
	v_mfma_f32_16x16x32_bf16 v[96:99], v[192:195], v[208:211], v[96:99]
	v_mfma_f32_16x16x32_bf16 v[100:103], v[176:179], v[204:207], v[100:103]
	v_mfma_f32_16x16x32_bf16 v[100:103], v[184:187], v[208:211], v[100:103]
	v_mfma_f32_16x16x32_bf16 v[84:87], v[176:179], v[212:215], v[84:87]
	v_mfma_f32_16x16x32_bf16 v[84:87], v[184:187], v[216:219], v[84:87]
	v_mfma_f32_16x16x32_bf16 v[80:83], v[188:191], v[212:215], v[80:83]
	v_mfma_f32_16x16x32_bf16 v[80:83], v[192:195], v[216:219], v[80:83]
	v_mfma_f32_16x16x32_bf16 v[64:67], v[188:191], v[220:223], v[64:67]
	v_mfma_f32_16x16x32_bf16 v[64:67], v[192:195], v[224:227], v[64:67]
	v_mfma_f32_16x16x32_bf16 v[68:71], v[176:179], v[220:223], v[68:71]
	v_mfma_f32_16x16x32_bf16 v[68:71], v[184:187], v[224:227], v[68:71]
	s_barrier
	s_add_i32 s12, s76, s59
	s_mov_b32 m0, s12
	ds_read_b128 v[196:199], v170 offset:16384
	ds_read_b128 v[200:203], v170 offset:17408
	ds_read_b128 v[204:207], v170 offset:18432
	ds_read_b128 v[208:211], v170 offset:19456
	ds_read_b128 v[212:215], v170 offset:20480
	ds_read_b128 v[216:219], v170 offset:21504
	ds_read_b128 v[220:223], v170 offset:22528
	ds_read_b128 v[224:227], v170 offset:23552
	global_load_lds_dwordx4 v148, s[54:55]
	s_add_i32 m0, s12, 0x2000
	s_add_u32 s34, s54, 0x40000
	s_addc_u32 s35, s55, 0
	s_add_i32 s12, s77, s59
	global_load_lds_dwordx4 v144, s[54:55]
	s_mov_b32 m0, s12
	s_nop 0
	global_load_lds_dwordx4 v148, s[34:35]
	s_add_i32 m0, s12, 0x2000
	s_nop 0
	global_load_lds_dwordx4 v144, s[34:35]
	s_waitcnt vmcnt(6)
	s_waitcnt lgkmcnt(0)
	s_barrier
	v_mfma_f32_16x16x32_bf16 v[60:63], v[118:121], v[196:199], v[60:63]
	v_mfma_f32_16x16x32_bf16 v[60:63], v[122:125], v[200:203], v[60:63]
	v_mfma_f32_16x16x32_bf16 v[56:59], v[126:129], v[196:199], v[56:59]
	v_mfma_f32_16x16x32_bf16 v[56:59], v[172:175], v[200:203], v[56:59]
	v_mfma_f32_16x16x32_bf16 v[40:43], v[126:129], v[204:207], v[40:43]
	v_mfma_f32_16x16x32_bf16 v[40:43], v[172:175], v[208:211], v[40:43]
	v_mfma_f32_16x16x32_bf16 v[44:47], v[118:121], v[204:207], v[44:47]
	v_mfma_f32_16x16x32_bf16 v[44:47], v[122:125], v[208:211], v[44:47]
	v_mfma_f32_16x16x32_bf16 v[28:31], v[118:121], v[212:215], v[28:31]
	v_mfma_f32_16x16x32_bf16 v[28:31], v[122:125], v[216:219], v[28:31]
	v_mfma_f32_16x16x32_bf16 v[24:27], v[126:129], v[212:215], v[24:27]
	v_mfma_f32_16x16x32_bf16 v[24:27], v[172:175], v[216:219], v[24:27]
	v_mfma_f32_16x16x32_bf16 v[8:11], v[126:129], v[220:223], v[8:11]
	v_mfma_f32_16x16x32_bf16 v[8:11], v[172:175], v[224:227], v[8:11]
	v_mfma_f32_16x16x32_bf16 v[12:15], v[118:121], v[220:223], v[12:15]
	v_mfma_f32_16x16x32_bf16 v[12:15], v[122:125], v[224:227], v[12:15]
	v_mfma_f32_16x16x32_bf16 v[52:55], v[176:179], v[196:199], v[52:55]
	v_mfma_f32_16x16x32_bf16 v[52:55], v[184:187], v[200:203], v[52:55]
	v_mfma_f32_16x16x32_bf16 v[48:51], v[188:191], v[196:199], v[48:51]
	v_mfma_f32_16x16x32_bf16 v[48:51], v[192:195], v[200:203], v[48:51]
	v_mfma_f32_16x16x32_bf16 v[32:35], v[188:191], v[204:207], v[32:35]
	v_mfma_f32_16x16x32_bf16 v[32:35], v[192:195], v[208:211], v[32:35]
	v_mfma_f32_16x16x32_bf16 v[36:39], v[176:179], v[204:207], v[36:39]
	v_mfma_f32_16x16x32_bf16 v[36:39], v[184:187], v[208:211], v[36:39]
	v_mfma_f32_16x16x32_bf16 v[20:23], v[176:179], v[212:215], v[20:23]
	v_mfma_f32_16x16x32_bf16 v[20:23], v[184:187], v[216:219], v[20:23]
	v_mfma_f32_16x16x32_bf16 v[16:19], v[188:191], v[212:215], v[16:19]
	v_mfma_f32_16x16x32_bf16 v[16:19], v[192:195], v[216:219], v[16:19]
	v_mfma_f32_16x16x32_bf16 v[0:3], v[188:191], v[220:223], v[0:3]
	v_mfma_f32_16x16x32_bf16 v[0:3], v[192:195], v[224:227], v[0:3]
	v_mfma_f32_16x16x32_bf16 v[4:7], v[176:179], v[220:223], v[4:7]
	v_mfma_f32_16x16x32_bf16 v[4:7], v[184:187], v[224:227], v[4:7]
	s_barrier
; #define PG8_STAGE(bufoff, gbase, voff) do { _Pragma("unroll") for (int _i = 0; _i < 2; ++_i) \
;         __builtin_amdgcn_global_load_lds((const unsigned*)((const char*)(gbase) + (voff)[_i]), (PG8_LAS unsigned*)(lds + (bufoff) + ldsw + _i * 8192), 16, 0, 0); } while (0)
; #define PG8_LDA(dst, b, h) do { _Pragma("unroll") for (int m = 0; m < 4; ++m) _Pragma("unroll") for (int k = 0; k < 2; ++k) dst[m][k] = *(const PG8_LAS bf16x8*)(lds + PG8_SA(b, h) + aoff + m * 2048 + k * 1024); } while (0)
; #define PG8_LDB(dst, b, h) do { _Pragma("unroll") for (int n = 0; n < 2; ++n) _Pragma("unroll") for (int k = 0; k < 2; ++k) dst[n][k] = *(const PG8_LAS bf16x8*)(lds + PG8_SB(b, h) + boff + n * 2048 + k * 1024); } while (0)
; #define PG8_MMA(ai, bj, At, Bt) do { __builtin_amdgcn_s_setprio(1); _Pragma("unroll") for (int m = 0; m < 4; ++m) _Pragma("unroll") for (int n = 0; n < 2; ++n) _Pragma("unroll") for (int k = 0; k < 2; ++k) \
;         acc[ai][bj][m][n] = __builtin_amdgcn_mfma_f32_16x16x32_bf16(Bt[n][k], At[m][k], acc[ai][bj][m][n], 0, 0, 0); __builtin_amdgcn_s_setprio(0); } while (0)
; #define PG8_WAIT_V(n) asm volatile("s_waitcnt vmcnt(" #n ")" ::: "memory")
; #define PG8_WAIT_L(n) asm volatile("s_waitcnt lgkmcnt(" #n ")" ::: "memory")
; #define PG8_BAR __builtin_amdgcn_s_barrier()
; #define PG8_SCHED __builtin_amdgcn_sched_barrier(0)
; template <class Epi, class Sched, bool ALIGN_EPI = false, bool SP2 = false>
; __device__ __forceinline__ void gemm_phase(PG8_LAS unsigned char* lds, const Gemm g, const Sched& S, const Epi& E) {
;     ...
;             PG8_LDB(B0, 1, 0); PG8_LDB(B1, 1, 1); PG8_SCHED; PG8_LDA(At, 1, 0); PG8_STAGE(PG8_SA(0, 1), a2 + hstep, voffA);
;             PG8_WAIT_V(8); PG8_WAIT_L(0); PG8_BAR; PG8_MMA(0, 0, At, B0); PG8_MMA(0, 1, At, B1); PG8_BAR; PG8_SCHED;
;             PG8_LDA(At, 1, 1); PG8_STAGE(PG8_SB(1, 0), b3, voffB); PG8_STAGE(PG8_SB(1, 1), b3 + hstep, voffB); PG8_STAGE(PG8_SA(1, 0), a3, voffA);
;             PG8_WAIT_V(8); PG8_WAIT_L(0); PG8_BAR; PG8_MMA(1, 0, At, B0); PG8_MMA(1, 1, At, B1); PG8_BAR; PG8_SCHED;
	s_add_i32 s12, 0, 0x18000
	v_add_u32_e32 v134, s12, v165
	s_add_i32 s13, 0, 0x1c000
	ds_read_b128 v[118:121], v134
	ds_read_b128 v[122:125], v134 offset:1024
	ds_read_b128 v[126:129], v134 offset:2048
	ds_read_b128 v[172:175], v134 offset:3072
	v_add_u32_e32 v134, s13, v165
	ds_read_b128 v[176:179], v134
	ds_read_b128 v[184:187], v134 offset:1024
	ds_read_b128 v[188:191], v134 offset:2048
	ds_read_b128 v[192:195], v134 offset:3072
	s_add_u32 s34, s56, 0x40000
	s_addc_u32 s35, s57, 0
	s_mov_b32 m0, s64
	ds_read_b128 v[196:199], v170 offset:32768
	ds_read_b128 v[200:203], v170 offset:33792
	ds_read_b128 v[204:207], v170 offset:34816
	ds_read_b128 v[208:211], v170 offset:35840
	ds_read_b128 v[212:215], v170 offset:36864
	ds_read_b128 v[216:219], v170 offset:37888
	ds_read_b128 v[220:223], v170 offset:38912
	ds_read_b128 v[224:227], v170 offset:39936
	global_load_lds_dwordx4 v150, s[34:35]
	s_mov_b32 m0, s65
	s_nop 0
	global_load_lds_dwordx4 v146, s[34:35]
	s_mov_b32 m0, s62
	s_nop 0
	global_load_lds_dwordx4 v150, s[56:57]
	s_mov_b32 m0, s63
	s_nop 0
	global_load_lds_dwordx4 v146, s[56:57]
	s_waitcnt vmcnt(8)
	s_waitcnt lgkmcnt(0)
	s_barrier
	v_mfma_f32_16x16x32_bf16 v[140:143], v[118:121], v[196:199], v[140:143]
	v_mfma_f32_16x16x32_bf16 v[140:143], v[122:125], v[200:203], v[140:143]
	v_mfma_f32_16x16x32_bf16 v[134:137], v[126:129], v[196:199], v[136:139]
	v_mfma_f32_16x16x32_bf16 v[136:139], v[172:175], v[200:203], v[134:137]
	v_mfma_f32_16x16x32_bf16 v[104:107], v[126:129], v[204:207], v[104:107]
	v_mfma_f32_16x16x32_bf16 v[104:107], v[172:175], v[208:211], v[104:107]
	v_mfma_f32_16x16x32_bf16 v[108:111], v[118:121], v[204:207], v[108:111]
	v_mfma_f32_16x16x32_bf16 v[108:111], v[122:125], v[208:211], v[108:111]
	v_mfma_f32_16x16x32_bf16 v[92:95], v[118:121], v[212:215], v[92:95]
	v_mfma_f32_16x16x32_bf16 v[92:95], v[122:125], v[216:219], v[92:95]
	v_mfma_f32_16x16x32_bf16 v[88:91], v[126:129], v[212:215], v[88:91]
	v_mfma_f32_16x16x32_bf16 v[88:91], v[172:175], v[216:219], v[88:91]
	v_mfma_f32_16x16x32_bf16 v[72:75], v[126:129], v[220:223], v[72:75]
	v_mfma_f32_16x16x32_bf16 v[72:75], v[172:175], v[224:227], v[72:75]
	v_mfma_f32_16x16x32_bf16 v[76:79], v[118:121], v[220:223], v[76:79]
	v_mfma_f32_16x16x32_bf16 v[76:79], v[122:125], v[224:227], v[76:79]
	v_mfma_f32_16x16x32_bf16 v[130:133], v[176:179], v[196:199], v[130:133]
	v_mfma_f32_16x16x32_bf16 v[132:135], v[184:187], v[200:203], v[130:133]
	v_mfma_f32_16x16x32_bf16 v[112:115], v[188:191], v[196:199], v[112:115]
	v_mfma_f32_16x16x32_bf16 v[112:115], v[192:195], v[200:203], v[112:115]
	v_mfma_f32_16x16x32_bf16 v[96:99], v[188:191], v[204:207], v[96:99]
	v_mfma_f32_16x16x32_bf16 v[96:99], v[192:195], v[208:211], v[96:99]
	v_mfma_f32_16x16x32_bf16 v[100:103], v[176:179], v[204:207], v[100:103]
	v_mfma_f32_16x16x32_bf16 v[100:103], v[184:187], v[208:211], v[100:103]
	v_mfma_f32_16x16x32_bf16 v[84:87], v[176:179], v[212:215], v[84:87]
	v_mfma_f32_16x16x32_bf16 v[84:87], v[184:187], v[216:219], v[84:87]
	v_mfma_f32_16x16x32_bf16 v[80:83], v[188:191], v[212:215], v[80:83]
	v_mfma_f32_16x16x32_bf16 v[80:83], v[192:195], v[216:219], v[80:83]
	v_mfma_f32_16x16x32_bf16 v[64:67], v[188:191], v[220:223], v[64:67]
	v_mfma_f32_16x16x32_bf16 v[64:67], v[192:195], v[224:227], v[64:67]
	v_mfma_f32_16x16x32_bf16 v[68:71], v[176:179], v[220:223], v[68:71]
	v_mfma_f32_16x16x32_bf16 v[68:71], v[184:187], v[224:227], v[68:71]
	s_barrier
	s_add_i32 s12, s12, s59
	s_add_u32 s98, s54, s18
	s_addc_u32 s99, s55, s19
	s_add_u32 s100, s56, s18
	s_addc_u32 s101, s57, s19
	s_mov_b32 m0, s12
	ds_read_b128 v[196:199], v170 offset:49152
	ds_read_b128 v[200:203], v170 offset:50176
	ds_read_b128 v[204:207], v170 offset:51200
	ds_read_b128 v[208:211], v170 offset:52224
	ds_read_b128 v[212:215], v170 offset:53248
	ds_read_b128 v[216:219], v170 offset:54272
	ds_read_b128 v[220:223], v170 offset:55296
	ds_read_b128 v[224:227], v170 offset:56320
	global_load_lds_dwordx4 v148, s[98:99]
	s_add_i32 m0, s12, 0x2000
	s_add_u32 s34, s54, 0x40080
	s_addc_u32 s35, s55, 0
	s_add_i32 s12, s13, s59
	global_load_lds_dwordx4 v144, s[98:99]
	s_mov_b32 m0, s12
	s_nop 0
	global_load_lds_dwordx4 v148, s[34:35]
	s_add_i32 m0, s12, 0x2000
	s_nop 0
	global_load_lds_dwordx4 v144, s[34:35]
	s_mov_b32 m0, s68
	s_nop 0
	global_load_lds_dwordx4 v150, s[100:101]
	s_mov_b32 m0, s69
	s_nop 0
	global_load_lds_dwordx4 v146, s[100:101]
	s_waitcnt vmcnt(6)
	s_waitcnt lgkmcnt(0)
	s_barrier
	v_mfma_f32_16x16x32_bf16 v[60:63], v[118:121], v[196:199], v[60:63]
	v_mfma_f32_16x16x32_bf16 v[60:63], v[122:125], v[200:203], v[60:63]
	v_mfma_f32_16x16x32_bf16 v[56:59], v[126:129], v[196:199], v[56:59]
	v_mfma_f32_16x16x32_bf16 v[56:59], v[172:175], v[200:203], v[56:59]
	v_mfma_f32_16x16x32_bf16 v[40:43], v[126:129], v[204:207], v[40:43]
	v_mfma_f32_16x16x32_bf16 v[40:43], v[172:175], v[208:211], v[40:43]
	v_mfma_f32_16x16x32_bf16 v[44:47], v[118:121], v[204:207], v[44:47]
	v_mfma_f32_16x16x32_bf16 v[44:47], v[122:125], v[208:211], v[44:47]
	v_mfma_f32_16x16x32_bf16 v[28:31], v[118:121], v[212:215], v[28:31]
	v_mfma_f32_16x16x32_bf16 v[28:31], v[122:125], v[216:219], v[28:31]
	v_mfma_f32_16x16x32_bf16 v[24:27], v[126:129], v[212:215], v[24:27]
	v_mfma_f32_16x16x32_bf16 v[24:27], v[172:175], v[216:219], v[24:27]
	v_mfma_f32_16x16x32_bf16 v[8:11], v[126:129], v[220:223], v[8:11]
	v_mfma_f32_16x16x32_bf16 v[8:11], v[172:175], v[224:227], v[8:11]
	v_mfma_f32_16x16x32_bf16 v[12:15], v[118:121], v[220:223], v[12:15]
	v_mfma_f32_16x16x32_bf16 v[12:15], v[122:125], v[224:227], v[12:15]
	v_mfma_f32_16x16x32_bf16 v[52:55], v[176:179], v[196:199], v[52:55]
	v_mfma_f32_16x16x32_bf16 v[52:55], v[184:187], v[200:203], v[52:55]
	v_mfma_f32_16x16x32_bf16 v[48:51], v[188:191], v[196:199], v[48:51]
	v_mfma_f32_16x16x32_bf16 v[48:51], v[192:195], v[200:203], v[48:51]
	v_mfma_f32_16x16x32_bf16 v[32:35], v[188:191], v[204:207], v[32:35]
	v_mfma_f32_16x16x32_bf16 v[32:35], v[192:195], v[208:211], v[32:35]
	v_mfma_f32_16x16x32_bf16 v[36:39], v[176:179], v[204:207], v[36:39]
	v_mfma_f32_16x16x32_bf16 v[36:39], v[184:187], v[208:211], v[36:39]
	v_mfma_f32_16x16x32_bf16 v[20:23], v[176:179], v[212:215], v[20:23]
	v_mfma_f32_16x16x32_bf16 v[20:23], v[184:187], v[216:219], v[20:23]
	v_mfma_f32_16x16x32_bf16 v[16:19], v[188:191], v[212:215], v[16:19]
	v_mfma_f32_16x16x32_bf16 v[16:19], v[192:195], v[216:219], v[16:19]
	v_mfma_f32_16x16x32_bf16 v[0:3], v[188:191], v[220:223], v[0:3]
	v_mfma_f32_16x16x32_bf16 v[0:3], v[192:195], v[224:227], v[0:3]
	v_mfma_f32_16x16x32_bf16 v[4:7], v[176:179], v[220:223], v[4:7]
	v_mfma_f32_16x16x32_bf16 v[4:7], v[184:187], v[224:227], v[4:7]
	s_barrier
	s_add_i32 s80, s80, 2
	s_add_u32 s49, s49, 0x100
	s_addc_u32 s51, s51, 0
	s_add_u32 s52, s52, 0x100
	s_addc_u32 s53, s53, 0
	s_cmp_gt_u32 s80, 13
	s_cbranch_scc1 .LBB0_799

; #define PG8_STAGE(bufoff, gbase, voff) do { _Pragma("unroll") for (int _i = 0; _i < 2; ++_i) \
;         __builtin_amdgcn_global_load_lds((const unsigned*)((const char*)(gbase) + (voff)[_i]), (PG8_LAS unsigned*)(lds + (bufoff) + ldsw + _i * 8192), 16, 0, 0); } while (0)
; #define PG8_LDA(dst, b, h) do { _Pragma("unroll") for (int m = 0; m < 4; ++m) _Pragma("unroll") for (int k = 0; k < 2; ++k) dst[m][k] = *(const PG8_LAS bf16x8*)(lds + PG8_SA(b, h) + aoff + m * 2048 + k * 1024); } while (0)
; #define PG8_LDB(dst, b, h) do { _Pragma("unroll") for (int n = 0; n < 2; ++n) _Pragma("unroll") for (int k = 0; k < 2; ++k) dst[n][k] = *(const PG8_LAS bf16x8*)(lds + PG8_SB(b, h) + boff + n * 2048 + k * 1024); } while (0)
; #define PG8_MMA(ai, bj, At, Bt) do { __builtin_amdgcn_s_setprio(1); _Pragma("unroll") for (int m = 0; m < 4; ++m) _Pragma("unroll") for (int n = 0; n < 2; ++n) _Pragma("unroll") for (int k = 0; k < 2; ++k) \
;         acc[ai][bj][m][n] = __builtin_amdgcn_mfma_f32_16x16x32_bf16(Bt[n][k], At[m][k], acc[ai][bj][m][n], 0, 0, 0); __builtin_amdgcn_s_setprio(0); } while (0)
; #define PG8_WAIT_V(n) asm volatile("s_waitcnt vmcnt(" #n ")" ::: "memory")
; #define PG8_WAIT_L(n) asm volatile("s_waitcnt lgkmcnt(" #n ")" ::: "memory")
; #define PG8_BAR __builtin_amdgcn_s_barrier()
; #define PG8_SCHED __builtin_amdgcn_sched_barrier(0)
; template <class Epi, class Sched, bool ALIGN_EPI = false, bool SP2 = false>
; __device__ __forceinline__ void gemm_phase(PG8_LAS unsigned char* lds, const Gemm g, const Sched& S, const Epi& E) {
;     ...
;             PG8_LDB(B0, 0, 0); PG8_LDB(B1, 0, 1); PG8_SCHED; PG8_LDA(At, 0, 0); PG8_STAGE(PG8_SA(1, 1), a1 + hstep, voffA);
;             PG8_WAIT_V(8); PG8_WAIT_L(0); PG8_BAR; PG8_MMA(0, 0, At, B0); PG8_MMA(0, 1, At, B1); PG8_BAR; PG8_SCHED;
;             PG8_LDA(At, 0, 1); PG8_STAGE(PG8_SB(0, 0), b2, voffB); PG8_STAGE(PG8_SB(0, 1), b2 + hstep, voffB); PG8_STAGE(PG8_SA(0, 0), a2, voffA);
;             PG8_WAIT_V(8); PG8_WAIT_L(0); PG8_BAR; PG8_MMA(1, 0, At, B0); PG8_MMA(1, 1, At, B1); PG8_BAR; PG8_SCHED;
.LBB0_872:
	ds_read_b128 v[128:131], v169
	ds_read_b128 v[132:135], v169 offset:1024
	ds_read_b128 v[136:139], v169 offset:2048
	ds_read_b128 v[140:143], v169 offset:3072
	ds_read_b128 v[162:165], v170
	ds_read_b128 v[172:175], v170 offset:1024
	ds_read_b128 v[176:179], v170 offset:2048
	ds_read_b128 v[184:187], v170 offset:3072
	s_add_u32 s42, s40, 0x100
	s_addc_u32 s43, s41, 0
	s_cmp_eq_u32 s74, 40
	s_cselect_b32 s47, s11, s43
	s_cselect_b32 s46, s10, s42
	s_cselect_b32 s45, s37, s73
	s_cselect_b32 s44, s36, s71
	v_lshl_add_u64 v[180:181], s[40:41], 0, v[154:155]
	s_add_i32 m0, s50, 0xc000
	ds_read_b128 v[188:191], v171
	ds_read_b128 v[192:195], v171 offset:1024
	ds_read_b128 v[196:199], v171 offset:2048
	ds_read_b128 v[200:203], v171 offset:3072
	ds_read_b128 v[204:207], v171 offset:4096
	ds_read_b128 v[208:211], v171 offset:5120
	ds_read_b128 v[212:215], v171 offset:6144
	ds_read_b128 v[216:219], v171 offset:7168
	global_load_lds_dwordx4 v[180:181], off
	v_lshl_add_u64 v[180:181], s[40:41], 0, v[152:153]
	s_add_i32 m0, s50, 0xe000
	s_nop 0
	global_load_lds_dwordx4 v[180:181], off
	s_waitcnt vmcnt(8)
	s_waitcnt lgkmcnt(0)
	s_barrier
	v_mfma_f32_16x16x32_bf16 v[124:127], v[128:131], v[188:191], v[124:127]
	v_mfma_f32_16x16x32_bf16 v[124:127], v[132:135], v[192:195], v[124:127]
	v_mfma_f32_16x16x32_bf16 v[120:123], v[136:139], v[188:191], v[120:123]
	v_mfma_f32_16x16x32_bf16 v[120:123], v[140:143], v[192:195], v[120:123]
	v_mfma_f32_16x16x32_bf16 v[108:111], v[136:139], v[196:199], v[108:111]
	v_mfma_f32_16x16x32_bf16 v[108:111], v[140:143], v[200:203], v[108:111]
	v_mfma_f32_16x16x32_bf16 v[116:119], v[128:131], v[196:199], v[116:119]
	v_mfma_f32_16x16x32_bf16 v[116:119], v[132:135], v[200:203], v[116:119]
	v_mfma_f32_16x16x32_bf16 v[100:103], v[128:131], v[204:207], v[100:103]
	v_mfma_f32_16x16x32_bf16 v[100:103], v[132:135], v[208:211], v[100:103]
	v_mfma_f32_16x16x32_bf16 v[92:95], v[136:139], v[204:207], v[92:95]
	v_mfma_f32_16x16x32_bf16 v[92:95], v[140:143], v[208:211], v[92:95]
	v_mfma_f32_16x16x32_bf16 v[76:79], v[136:139], v[212:215], v[76:79]
	v_mfma_f32_16x16x32_bf16 v[76:79], v[140:143], v[216:219], v[76:79]
	v_mfma_f32_16x16x32_bf16 v[84:87], v[128:131], v[212:215], v[84:87]
	v_mfma_f32_16x16x32_bf16 v[84:87], v[132:135], v[216:219], v[84:87]
	v_mfma_f32_16x16x32_bf16 v[112:115], v[162:165], v[188:191], v[112:115]
	v_mfma_f32_16x16x32_bf16 v[112:115], v[172:175], v[192:195], v[112:115]
	v_mfma_f32_16x16x32_bf16 v[104:107], v[176:179], v[188:191], v[104:107]
	v_mfma_f32_16x16x32_bf16 v[104:107], v[184:187], v[192:195], v[104:107]
	v_mfma_f32_16x16x32_bf16 v[88:91], v[176:179], v[196:199], v[88:91]
	v_mfma_f32_16x16x32_bf16 v[88:91], v[184:187], v[200:203], v[88:91]
	v_mfma_f32_16x16x32_bf16 v[96:99], v[162:165], v[196:199], v[96:99]
	v_mfma_f32_16x16x32_bf16 v[96:99], v[172:175], v[200:203], v[96:99]
	v_mfma_f32_16x16x32_bf16 v[80:83], v[162:165], v[204:207], v[80:83]
	v_mfma_f32_16x16x32_bf16 v[80:83], v[172:175], v[208:211], v[80:83]
	v_mfma_f32_16x16x32_bf16 v[72:75], v[176:179], v[204:207], v[72:75]
	v_mfma_f32_16x16x32_bf16 v[72:75], v[184:187], v[208:211], v[72:75]
	v_mfma_f32_16x16x32_bf16 v[64:67], v[176:179], v[212:215], v[64:67]
	v_mfma_f32_16x16x32_bf16 v[64:67], v[184:187], v[216:219], v[64:67]
	v_mfma_f32_16x16x32_bf16 v[68:71], v[162:165], v[212:215], v[68:71]
	v_mfma_f32_16x16x32_bf16 v[68:71], v[172:175], v[216:219], v[68:71]
	s_barrier
	s_add_i32 s12, s65, s49
	s_mov_b32 m0, s12
	ds_read_b128 v[188:191], v171 offset:16384
	ds_read_b128 v[192:195], v171 offset:17408
	ds_read_b128 v[196:199], v171 offset:18432
	ds_read_b128 v[200:203], v171 offset:19456
	ds_read_b128 v[204:207], v171 offset:20480
	ds_read_b128 v[208:211], v171 offset:21504
	ds_read_b128 v[212:215], v171 offset:22528
	ds_read_b128 v[216:219], v171 offset:23552
	global_load_lds_dwordx4 v146, s[44:45]
	s_add_i32 m0, s12, 0x2000
	s_add_u32 s40, s44, 0xb0000
	s_addc_u32 s41, s45, 0
	s_add_i32 s12, s66, s49
	global_load_lds_dwordx4 v150, s[44:45]
	s_mov_b32 m0, s12
	s_nop 0
	global_load_lds_dwordx4 v146, s[40:41]
	s_add_i32 m0, s12, 0x2000
	s_nop 0
	global_load_lds_dwordx4 v150, s[40:41]
	s_waitcnt vmcnt(6)
	s_waitcnt lgkmcnt(0)
	s_barrier
	v_mfma_f32_16x16x32_bf16 v[60:63], v[128:131], v[188:191], v[60:63]
	v_mfma_f32_16x16x32_bf16 v[60:63], v[132:135], v[192:195], v[60:63]
	v_mfma_f32_16x16x32_bf16 v[56:59], v[136:139], v[188:191], v[56:59]
	v_mfma_f32_16x16x32_bf16 v[56:59], v[140:143], v[192:195], v[56:59]
	v_mfma_f32_16x16x32_bf16 v[44:47], v[136:139], v[196:199], v[44:47]
	v_mfma_f32_16x16x32_bf16 v[44:47], v[140:143], v[200:203], v[44:47]
	v_mfma_f32_16x16x32_bf16 v[48:51], v[128:131], v[196:199], v[48:51]
	v_mfma_f32_16x16x32_bf16 v[48:51], v[132:135], v[200:203], v[48:51]
	v_mfma_f32_16x16x32_bf16 v[36:39], v[128:131], v[204:207], v[36:39]
	v_mfma_f32_16x16x32_bf16 v[36:39], v[132:135], v[208:211], v[36:39]
	v_mfma_f32_16x16x32_bf16 v[28:31], v[136:139], v[204:207], v[28:31]
	v_mfma_f32_16x16x32_bf16 v[28:31], v[140:143], v[208:211], v[28:31]
	v_mfma_f32_16x16x32_bf16 v[12:15], v[136:139], v[212:215], v[12:15]
	v_mfma_f32_16x16x32_bf16 v[12:15], v[140:143], v[216:219], v[12:15]
	v_mfma_f32_16x16x32_bf16 v[20:23], v[128:131], v[212:215], v[20:23]
	v_mfma_f32_16x16x32_bf16 v[20:23], v[132:135], v[216:219], v[20:23]
	v_mfma_f32_16x16x32_bf16 v[52:55], v[162:165], v[188:191], v[52:55]
	v_mfma_f32_16x16x32_bf16 v[52:55], v[172:175], v[192:195], v[52:55]
	v_mfma_f32_16x16x32_bf16 v[40:43], v[176:179], v[188:191], v[40:43]
	v_mfma_f32_16x16x32_bf16 v[40:43], v[184:187], v[192:195], v[40:43]
	v_mfma_f32_16x16x32_bf16 v[24:27], v[176:179], v[196:199], v[24:27]
	v_mfma_f32_16x16x32_bf16 v[24:27], v[184:187], v[200:203], v[24:27]
	v_mfma_f32_16x16x32_bf16 v[32:35], v[162:165], v[196:199], v[32:35]
	v_mfma_f32_16x16x32_bf16 v[32:35], v[172:175], v[200:203], v[32:35]
	v_mfma_f32_16x16x32_bf16 v[16:19], v[162:165], v[204:207], v[16:19]
	v_mfma_f32_16x16x32_bf16 v[16:19], v[172:175], v[208:211], v[16:19]
	v_mfma_f32_16x16x32_bf16 v[8:11], v[176:179], v[204:207], v[8:11]
	v_mfma_f32_16x16x32_bf16 v[8:11], v[184:187], v[208:211], v[8:11]
	v_mfma_f32_16x16x32_bf16 v[0:3], v[176:179], v[212:215], v[0:3]
	v_mfma_f32_16x16x32_bf16 v[0:3], v[184:187], v[216:219], v[0:3]
	v_mfma_f32_16x16x32_bf16 v[4:7], v[162:165], v[212:215], v[4:7]
	v_mfma_f32_16x16x32_bf16 v[4:7], v[172:175], v[216:219], v[4:7]
	s_barrier
; #define PG8_STAGE(bufoff, gbase, voff) do { _Pragma("unroll") for (int _i = 0; _i < 2; ++_i) \
;         __builtin_amdgcn_global_load_lds((const unsigned*)((const char*)(gbase) + (voff)[_i]), (PG8_LAS unsigned*)(lds + (bufoff) + ldsw + _i * 8192), 16, 0, 0); } while (0)
; #define PG8_LDA(dst, b, h) do { _Pragma("unroll") for (int m = 0; m < 4; ++m) _Pragma("unroll") for (int k = 0; k < 2; ++k) dst[m][k] = *(const PG8_LAS bf16x8*)(lds + PG8_SA(b, h) + aoff + m * 2048 + k * 1024); } while (0)
; #define PG8_LDB(dst, b, h) do { _Pragma("unroll") for (int n = 0; n < 2; ++n) _Pragma("unroll") for (int k = 0; k < 2; ++k) dst[n][k] = *(const PG8_LAS bf16x8*)(lds + PG8_SB(b, h) + boff + n * 2048 + k * 1024); } while (0)
; #define PG8_MMA(ai, bj, At, Bt) do { __builtin_amdgcn_s_setprio(1); _Pragma("unroll") for (int m = 0; m < 4; ++m) _Pragma("unroll") for (int n = 0; n < 2; ++n) _Pragma("unroll") for (int k = 0; k < 2; ++k) \
;         acc[ai][bj][m][n] = __builtin_amdgcn_mfma_f32_16x16x32_bf16(Bt[n][k], At[m][k], acc[ai][bj][m][n], 0, 0, 0); __builtin_amdgcn_s_setprio(0); } while (0)
; #define PG8_WAIT_V(n) asm volatile("s_waitcnt vmcnt(" #n ")" ::: "memory")
; #define PG8_WAIT_L(n) asm volatile("s_waitcnt lgkmcnt(" #n ")" ::: "memory")
; #define PG8_BAR __builtin_amdgcn_s_barrier()
; #define PG8_SCHED __builtin_amdgcn_sched_barrier(0)
; template <class Epi, class Sched, bool ALIGN_EPI = false, bool SP2 = false>
; __device__ __forceinline__ void gemm_phase(PG8_LAS unsigned char* lds, const Gemm g, const Sched& S, const Epi& E) {
;     ...
;             PG8_LDB(B0, 1, 0); PG8_LDB(B1, 1, 1); PG8_SCHED; PG8_LDA(At, 1, 0); PG8_STAGE(PG8_SA(0, 1), a2 + hstep, voffA);
;             PG8_WAIT_V(8); PG8_WAIT_L(0); PG8_BAR; PG8_MMA(0, 0, At, B0); PG8_MMA(0, 1, At, B1); PG8_BAR; PG8_SCHED;
;             PG8_LDA(At, 1, 1); PG8_STAGE(PG8_SB(1, 0), b3, voffB); PG8_STAGE(PG8_SB(1, 1), b3 + hstep, voffB); PG8_STAGE(PG8_SA(1, 0), a3, voffA);
;             PG8_WAIT_V(8); PG8_WAIT_L(0); PG8_BAR; PG8_MMA(1, 0, At, B0); PG8_MMA(1, 1, At, B1); PG8_BAR; PG8_SCHED;
	s_add_i32 s12, 0, 0x18000
	s_add_i32 s13, 0, 0x1c000
	v_add_u32_e32 v140, s12, v167
	v_add_u32_e32 v183, s13, v167
	ds_read_b128 v[128:131], v140
	ds_read_b128 v[132:135], v140 offset:1024
	ds_read_b128 v[136:139], v140 offset:2048
	ds_read_b128 v[140:143], v140 offset:3072
	ds_read_b128 v[162:165], v183
	ds_read_b128 v[172:175], v183 offset:1024
	ds_read_b128 v[176:179], v183 offset:2048
	ds_read_b128 v[184:187], v183 offset:3072
	s_add_u32 s40, s46, 0xb0000
	s_addc_u32 s41, s47, 0
	s_mov_b32 m0, s52
	ds_read_b128 v[188:191], v171 offset:32768
	ds_read_b128 v[192:195], v171 offset:33792
	ds_read_b128 v[196:199], v171 offset:34816
	ds_read_b128 v[200:203], v171 offset:35840
	ds_read_b128 v[204:207], v171 offset:36864
	ds_read_b128 v[208:211], v171 offset:37888
	ds_read_b128 v[212:215], v171 offset:38912
	ds_read_b128 v[216:219], v171 offset:39936
	global_load_lds_dwordx4 v144, s[40:41]
	s_mov_b32 m0, s53
	s_nop 0
	global_load_lds_dwordx4 v148, s[40:41]
	s_mov_b32 m0, s50
	s_nop 0
	global_load_lds_dwordx4 v144, s[46:47]
	s_mov_b32 m0, s51
	s_nop 0
	global_load_lds_dwordx4 v148, s[46:47]
	s_waitcnt vmcnt(8)
	s_waitcnt lgkmcnt(0)
	s_barrier
	v_mfma_f32_16x16x32_bf16 v[124:127], v[128:131], v[188:191], v[124:127]
	v_mfma_f32_16x16x32_bf16 v[124:127], v[132:135], v[192:195], v[124:127]
	v_mfma_f32_16x16x32_bf16 v[120:123], v[136:139], v[188:191], v[120:123]
	v_mfma_f32_16x16x32_bf16 v[120:123], v[140:143], v[192:195], v[120:123]
	v_mfma_f32_16x16x32_bf16 v[108:111], v[136:139], v[196:199], v[108:111]
	v_mfma_f32_16x16x32_bf16 v[108:111], v[140:143], v[200:203], v[108:111]
	v_mfma_f32_16x16x32_bf16 v[116:119], v[128:131], v[196:199], v[116:119]
	v_mfma_f32_16x16x32_bf16 v[116:119], v[132:135], v[200:203], v[116:119]
	v_mfma_f32_16x16x32_bf16 v[100:103], v[128:131], v[204:207], v[100:103]
	v_mfma_f32_16x16x32_bf16 v[100:103], v[132:135], v[208:211], v[100:103]
	v_mfma_f32_16x16x32_bf16 v[92:95], v[136:139], v[204:207], v[92:95]
	v_mfma_f32_16x16x32_bf16 v[92:95], v[140:143], v[208:211], v[92:95]
	v_mfma_f32_16x16x32_bf16 v[76:79], v[136:139], v[212:215], v[76:79]
	v_mfma_f32_16x16x32_bf16 v[76:79], v[140:143], v[216:219], v[76:79]
	v_mfma_f32_16x16x32_bf16 v[84:87], v[128:131], v[212:215], v[84:87]
	v_mfma_f32_16x16x32_bf16 v[84:87], v[132:135], v[216:219], v[84:87]
	v_mfma_f32_16x16x32_bf16 v[112:115], v[162:165], v[188:191], v[112:115]
	v_mfma_f32_16x16x32_bf16 v[112:115], v[172:175], v[192:195], v[112:115]
	v_mfma_f32_16x16x32_bf16 v[104:107], v[176:179], v[188:191], v[104:107]
	v_mfma_f32_16x16x32_bf16 v[104:107], v[184:187], v[192:195], v[104:107]
	v_mfma_f32_16x16x32_bf16 v[88:91], v[176:179], v[196:199], v[88:91]
	v_mfma_f32_16x16x32_bf16 v[88:91], v[184:187], v[200:203], v[88:91]
	v_mfma_f32_16x16x32_bf16 v[96:99], v[162:165], v[196:199], v[96:99]
	v_mfma_f32_16x16x32_bf16 v[96:99], v[172:175], v[200:203], v[96:99]
	v_mfma_f32_16x16x32_bf16 v[80:83], v[162:165], v[204:207], v[80:83]
	v_mfma_f32_16x16x32_bf16 v[80:83], v[172:175], v[208:211], v[80:83]
	v_mfma_f32_16x16x32_bf16 v[72:75], v[176:179], v[204:207], v[72:75]
	v_mfma_f32_16x16x32_bf16 v[72:75], v[184:187], v[208:211], v[72:75]
	v_mfma_f32_16x16x32_bf16 v[64:67], v[176:179], v[212:215], v[64:67]
	v_mfma_f32_16x16x32_bf16 v[64:67], v[184:187], v[216:219], v[64:67]
	v_mfma_f32_16x16x32_bf16 v[68:71], v[162:165], v[212:215], v[68:71]
	v_mfma_f32_16x16x32_bf16 v[68:71], v[172:175], v[216:219], v[68:71]
	s_barrier
	s_add_i32 s12, s12, s49
	s_add_u32 s98, s44, s30
	s_addc_u32 s99, s45, s31
	s_add_u32 s100, s46, s30
	s_addc_u32 s101, s47, s31
	s_mov_b32 m0, s12
	ds_read_b128 v[188:191], v171 offset:49152
	ds_read_b128 v[192:195], v171 offset:50176
	ds_read_b128 v[196:199], v171 offset:51200
	ds_read_b128 v[200:203], v171 offset:52224
	ds_read_b128 v[204:207], v171 offset:53248
	ds_read_b128 v[208:211], v171 offset:54272
	ds_read_b128 v[212:215], v171 offset:55296
	ds_read_b128 v[216:219], v171 offset:56320
	global_load_lds_dwordx4 v146, s[98:99]
	s_add_i32 m0, s12, 0x2000
	s_add_u32 s40, s44, 0xb0080
	s_addc_u32 s41, s45, 0
	s_add_i32 s12, s13, s49
	global_load_lds_dwordx4 v150, s[98:99]
	s_mov_b32 m0, s12
	s_nop 0
	global_load_lds_dwordx4 v146, s[40:41]
	s_add_i32 m0, s12, 0x2000
	s_nop 0
	global_load_lds_dwordx4 v150, s[40:41]
	s_mov_b32 m0, s59
	s_nop 0
	global_load_lds_dwordx4 v144, s[100:101]
	s_mov_b32 m0, s60
	s_nop 0
	global_load_lds_dwordx4 v148, s[100:101]
	s_waitcnt vmcnt(6)
	s_waitcnt lgkmcnt(0)
	s_barrier
	v_mfma_f32_16x16x32_bf16 v[60:63], v[128:131], v[188:191], v[60:63]
	v_mfma_f32_16x16x32_bf16 v[60:63], v[132:135], v[192:195], v[60:63]
	v_mfma_f32_16x16x32_bf16 v[56:59], v[136:139], v[188:191], v[56:59]
	v_mfma_f32_16x16x32_bf16 v[56:59], v[140:143], v[192:195], v[56:59]
	v_mfma_f32_16x16x32_bf16 v[44:47], v[136:139], v[196:199], v[44:47]
	v_mfma_f32_16x16x32_bf16 v[44:47], v[140:143], v[200:203], v[44:47]
	v_mfma_f32_16x16x32_bf16 v[48:51], v[128:131], v[196:199], v[48:51]
	v_mfma_f32_16x16x32_bf16 v[48:51], v[132:135], v[200:203], v[48:51]
	v_mfma_f32_16x16x32_bf16 v[36:39], v[128:131], v[204:207], v[36:39]
	v_mfma_f32_16x16x32_bf16 v[36:39], v[132:135], v[208:211], v[36:39]
	v_mfma_f32_16x16x32_bf16 v[28:31], v[136:139], v[204:207], v[28:31]
	v_mfma_f32_16x16x32_bf16 v[28:31], v[140:143], v[208:211], v[28:31]
	v_mfma_f32_16x16x32_bf16 v[12:15], v[136:139], v[212:215], v[12:15]
	v_mfma_f32_16x16x32_bf16 v[12:15], v[140:143], v[216:219], v[12:15]
	v_mfma_f32_16x16x32_bf16 v[20:23], v[128:131], v[212:215], v[20:23]
	v_mfma_f32_16x16x32_bf16 v[20:23], v[132:135], v[216:219], v[20:23]
	v_mfma_f32_16x16x32_bf16 v[52:55], v[162:165], v[188:191], v[52:55]
	v_mfma_f32_16x16x32_bf16 v[52:55], v[172:175], v[192:195], v[52:55]
	v_mfma_f32_16x16x32_bf16 v[40:43], v[176:179], v[188:191], v[40:43]
	v_mfma_f32_16x16x32_bf16 v[40:43], v[184:187], v[192:195], v[40:43]
	v_mfma_f32_16x16x32_bf16 v[24:27], v[176:179], v[196:199], v[24:27]
	v_mfma_f32_16x16x32_bf16 v[24:27], v[184:187], v[200:203], v[24:27]
	v_mfma_f32_16x16x32_bf16 v[32:35], v[162:165], v[196:199], v[32:35]
	v_mfma_f32_16x16x32_bf16 v[32:35], v[172:175], v[200:203], v[32:35]
	v_mfma_f32_16x16x32_bf16 v[16:19], v[162:165], v[204:207], v[16:19]
	v_mfma_f32_16x16x32_bf16 v[16:19], v[172:175], v[208:211], v[16:19]
	v_mfma_f32_16x16x32_bf16 v[8:11], v[176:179], v[204:207], v[8:11]
	v_mfma_f32_16x16x32_bf16 v[8:11], v[184:187], v[208:211], v[8:11]
	v_mfma_f32_16x16x32_bf16 v[0:3], v[176:179], v[212:215], v[0:3]
	v_mfma_f32_16x16x32_bf16 v[0:3], v[184:187], v[216:219], v[0:3]
	v_mfma_f32_16x16x32_bf16 v[4:7], v[162:165], v[212:215], v[4:7]
	v_mfma_f32_16x16x32_bf16 v[4:7], v[172:175], v[216:219], v[4:7]
	s_barrier
	s_add_i32 s74, s74, 2
	s_add_u32 s71, s71, 0x100
	s_addc_u32 s73, s73, 0
	s_cmp_gt_u32 s74, 41
	s_mov_b64 s[40:41], s[42:43]
	s_cbranch_scc0 .LBB0_872
	s_and_b64 vcc, exec, s[34:35]
	s_cbranch_vccz .LBB0_875
	s_barrier

; #define PG8_STAGE(bufoff, gbase, voff) do { _Pragma("unroll") for (int _i = 0; _i < 2; ++_i) \
;         __builtin_amdgcn_global_load_lds((const unsigned*)((const char*)(gbase) + (voff)[_i]), (PG8_LAS unsigned*)(lds + (bufoff) + ldsw + _i * 8192), 16, 0, 0); } while (0)
; #define PG8_LDA(dst, b, h) do { _Pragma("unroll") for (int m = 0; m < 4; ++m) _Pragma("unroll") for (int k = 0; k < 2; ++k) dst[m][k] = *(const PG8_LAS bf16x8*)(lds + PG8_SA(b, h) + aoff + m * 2048 + k * 1024); } while (0)
; #define PG8_LDB(dst, b, h) do { _Pragma("unroll") for (int n = 0; n < 2; ++n) _Pragma("unroll") for (int k = 0; k < 2; ++k) dst[n][k] = *(const PG8_LAS bf16x8*)(lds + PG8_SB(b, h) + boff + n * 2048 + k * 1024); } while (0)
; #define PG8_MMA(ai, bj, At, Bt) do { __builtin_amdgcn_s_setprio(1); _Pragma("unroll") for (int m = 0; m < 4; ++m) _Pragma("unroll") for (int n = 0; n < 2; ++n) _Pragma("unroll") for (int k = 0; k < 2; ++k) \
;         acc[ai][bj][m][n] = __builtin_amdgcn_mfma_f32_16x16x32_bf16(Bt[n][k], At[m][k], acc[ai][bj][m][n], 0, 0, 0); __builtin_amdgcn_s_setprio(0); } while (0)
; #define PG8_WAIT_V(n) asm volatile("s_waitcnt vmcnt(" #n ")" ::: "memory")
; #define PG8_WAIT_L(n) asm volatile("s_waitcnt lgkmcnt(" #n ")" ::: "memory")
; #define PG8_BAR __builtin_amdgcn_s_barrier()
; #define PG8_SCHED __builtin_amdgcn_sched_barrier(0)
; template <class Epi, class Sched, bool ALIGN_EPI = false, bool SP2 = false>
; __device__ __forceinline__ void gemm_phase(PG8_LAS unsigned char* lds, const Gemm g, const Sched& S, const Epi& E) {
;     ...
;             PG8_LDB(B0, 0, 0); PG8_LDB(B1, 0, 1); PG8_SCHED; PG8_LDA(At, 0, 0); PG8_STAGE(PG8_SA(1, 1), a1 + hstep, voffA);
;             PG8_WAIT_V(8); PG8_WAIT_L(0); PG8_BAR; PG8_MMA(0, 0, At, B0); PG8_MMA(0, 1, At, B1); PG8_BAR; PG8_SCHED;
;             PG8_LDA(At, 0, 1); PG8_STAGE(PG8_SB(0, 0), b2, voffB); PG8_STAGE(PG8_SB(0, 1), b2 + hstep, voffB); PG8_STAGE(PG8_SA(0, 0), a2, voffA);
;             PG8_WAIT_V(8); PG8_WAIT_L(0); PG8_BAR; PG8_MMA(1, 0, At, B0); PG8_MMA(1, 1, At, B1); PG8_BAR; PG8_SCHED;
.LBB0_960:
	v_add_u32_e32 v130, s89, v169
	ds_read_b128 v[150:153], v130
	ds_read_b128 v[158:161], v130 offset:1024
	ds_read_b128 v[162:165], v130 offset:2048
	ds_read_b128 v[196:199], v130 offset:3072
	v_add_u32_e32 v130, s90, v169
	ds_read_b128 v[200:203], v130
	ds_read_b128 v[204:207], v130 offset:1024
	ds_read_b128 v[208:211], v130 offset:2048
	ds_read_b128 v[212:215], v130 offset:3072
	s_add_u32 s12, s10, 0xfffc0080
	s_addc_u32 s13, s11, -1
	s_and_b64 s[66:67], s[66:67], exec
	s_cselect_b32 s69, s57, s13
	s_cselect_b32 s68, s63, s12
	s_cselect_b32 s67, s55, s71
	s_cselect_b32 s66, s70, s65
	s_add_i32 m0, s75, 0xc000
	ds_read_b128 v[216:219], v191
	ds_read_b128 v[220:223], v191 offset:1024
	ds_read_b128 v[224:227], v191 offset:2048
	ds_read_b128 v[228:231], v191 offset:3072
	ds_read_b128 v[232:235], v191 offset:4096
	ds_read_b128 v[236:239], v191 offset:5120
	ds_read_b128 v[240:243], v191 offset:6144
	ds_read_b128 v[244:247], v191 offset:7168
	global_load_lds_dwordx4 v142, s[10:11]
	s_add_i32 m0, s75, 0xe000
	s_nop 0
	global_load_lds_dwordx4 v140, s[10:11]
	s_waitcnt vmcnt(8)
	s_waitcnt lgkmcnt(0)
	s_barrier
	v_mfma_f32_16x16x32_bf16 v[124:127], v[150:153], v[216:219], v[124:127]
	v_mfma_f32_16x16x32_bf16 v[124:127], v[158:161], v[220:223], v[124:127]
	v_mfma_f32_16x16x32_bf16 v[120:123], v[162:165], v[216:219], v[120:123]
	v_mfma_f32_16x16x32_bf16 v[120:123], v[196:199], v[220:223], v[120:123]
	v_mfma_f32_16x16x32_bf16 v[104:107], v[162:165], v[224:227], v[104:107]
	v_mfma_f32_16x16x32_bf16 v[104:107], v[196:199], v[228:231], v[104:107]
	v_mfma_f32_16x16x32_bf16 v[112:115], v[150:153], v[224:227], v[112:115]
	v_mfma_f32_16x16x32_bf16 v[112:115], v[158:161], v[228:231], v[112:115]
	v_mfma_f32_16x16x32_bf16 v[100:103], v[150:153], v[232:235], v[100:103]
	v_mfma_f32_16x16x32_bf16 v[100:103], v[158:161], v[236:239], v[100:103]
	v_mfma_f32_16x16x32_bf16 v[96:99], v[162:165], v[232:235], v[96:99]
	v_mfma_f32_16x16x32_bf16 v[96:99], v[196:199], v[236:239], v[96:99]
	v_mfma_f32_16x16x32_bf16 v[72:75], v[162:165], v[240:243], v[72:75]
	v_mfma_f32_16x16x32_bf16 v[72:75], v[196:199], v[244:247], v[72:75]
	v_mfma_f32_16x16x32_bf16 v[80:83], v[150:153], v[240:243], v[80:83]
	v_mfma_f32_16x16x32_bf16 v[80:83], v[158:161], v[244:247], v[80:83]
	v_mfma_f32_16x16x32_bf16 v[116:119], v[200:203], v[216:219], v[116:119]
	v_mfma_f32_16x16x32_bf16 v[116:119], v[204:207], v[220:223], v[116:119]
	v_mfma_f32_16x16x32_bf16 v[108:111], v[208:211], v[216:219], v[108:111]
	v_mfma_f32_16x16x32_bf16 v[108:111], v[212:215], v[220:223], v[108:111]
	v_mfma_f32_16x16x32_bf16 v[88:91], v[208:211], v[224:227], v[88:91]
	v_mfma_f32_16x16x32_bf16 v[88:91], v[212:215], v[228:231], v[88:91]
	v_mfma_f32_16x16x32_bf16 v[92:95], v[200:203], v[224:227], v[92:95]
	v_mfma_f32_16x16x32_bf16 v[92:95], v[204:207], v[228:231], v[92:95]
	v_mfma_f32_16x16x32_bf16 v[84:87], v[200:203], v[232:235], v[84:87]
	v_mfma_f32_16x16x32_bf16 v[84:87], v[204:207], v[236:239], v[84:87]
	v_mfma_f32_16x16x32_bf16 v[76:79], v[208:211], v[232:235], v[76:79]
	v_mfma_f32_16x16x32_bf16 v[76:79], v[212:215], v[236:239], v[76:79]
	v_mfma_f32_16x16x32_bf16 v[64:67], v[208:211], v[240:243], v[64:67]
	v_mfma_f32_16x16x32_bf16 v[64:67], v[212:215], v[244:247], v[64:67]
	v_mfma_f32_16x16x32_bf16 v[68:71], v[200:203], v[240:243], v[68:71]
	v_mfma_f32_16x16x32_bf16 v[68:71], v[204:207], v[244:247], v[68:71]
	s_barrier
	s_add_i32 s12, s89, s74
	s_mov_b32 m0, s12
	ds_read_b128 v[216:219], v191 offset:16384
	ds_read_b128 v[220:223], v191 offset:17408
	ds_read_b128 v[224:227], v191 offset:18432
	ds_read_b128 v[228:231], v191 offset:19456
	ds_read_b128 v[232:235], v191 offset:20480
	ds_read_b128 v[236:239], v191 offset:21504
	ds_read_b128 v[240:243], v191 offset:22528
	ds_read_b128 v[244:247], v191 offset:23552
	global_load_lds_dwordx4 v134, s[66:67]
	s_add_i32 m0, s12, 0x2000
	s_add_u32 vcc_lo, s66, 0x40000
	v_lshl_add_u64 v[154:155], s[66:67], 0, v[138:139]
	s_addc_u32 vcc_hi, s67, 0
	s_add_i32 s12, s90, s74
	global_load_lds_dwordx4 v138, s[66:67]
	v_lshl_add_u64 v[166:167], vcc, 0, v[134:135]
	s_mov_b32 m0, s12
	v_lshl_add_u64 v[248:249], s[68:69], 0, v[136:137]
	global_load_lds_dwordx4 v[166:167], off
	v_lshl_add_u64 v[166:167], vcc, 0, v[138:139]
	s_add_i32 m0, s12, 0x2000
	s_nop 0
	global_load_lds_dwordx4 v[166:167], off
	v_lshl_add_u64 v[166:167], s[68:69], 0, v[132:133]
	s_waitcnt vmcnt(6)
	s_waitcnt lgkmcnt(0)
	s_barrier
	v_mfma_f32_16x16x32_bf16 v[60:63], v[150:153], v[216:219], v[60:63]
	v_mfma_f32_16x16x32_bf16 v[60:63], v[158:161], v[220:223], v[60:63]
	v_mfma_f32_16x16x32_bf16 v[56:59], v[162:165], v[216:219], v[56:59]
	v_mfma_f32_16x16x32_bf16 v[56:59], v[196:199], v[220:223], v[56:59]
	v_mfma_f32_16x16x32_bf16 v[40:43], v[162:165], v[224:227], v[40:43]
	v_mfma_f32_16x16x32_bf16 v[40:43], v[196:199], v[228:231], v[40:43]
	v_mfma_f32_16x16x32_bf16 v[48:51], v[150:153], v[224:227], v[48:51]
	v_mfma_f32_16x16x32_bf16 v[48:51], v[158:161], v[228:231], v[48:51]
	v_mfma_f32_16x16x32_bf16 v[36:39], v[150:153], v[232:235], v[36:39]
	v_mfma_f32_16x16x32_bf16 v[36:39], v[158:161], v[236:239], v[36:39]
	v_mfma_f32_16x16x32_bf16 v[32:35], v[162:165], v[232:235], v[32:35]
	v_mfma_f32_16x16x32_bf16 v[32:35], v[196:199], v[236:239], v[32:35]
	v_mfma_f32_16x16x32_bf16 v[16:19], v[162:165], v[240:243], v[16:19]
	v_mfma_f32_16x16x32_bf16 v[16:19], v[196:199], v[244:247], v[16:19]
	v_mfma_f32_16x16x32_bf16 v[20:23], v[150:153], v[240:243], v[20:23]
	v_mfma_f32_16x16x32_bf16 v[20:23], v[158:161], v[244:247], v[20:23]
	v_mfma_f32_16x16x32_bf16 v[52:55], v[200:203], v[216:219], v[52:55]
	v_mfma_f32_16x16x32_bf16 v[52:55], v[204:207], v[220:223], v[52:55]
	v_mfma_f32_16x16x32_bf16 v[44:47], v[208:211], v[216:219], v[44:47]
	v_mfma_f32_16x16x32_bf16 v[44:47], v[212:215], v[220:223], v[44:47]
	v_mfma_f32_16x16x32_bf16 v[24:27], v[208:211], v[224:227], v[24:27]
	v_mfma_f32_16x16x32_bf16 v[24:27], v[212:215], v[228:231], v[24:27]
	v_mfma_f32_16x16x32_bf16 v[28:31], v[200:203], v[224:227], v[28:31]
	v_mfma_f32_16x16x32_bf16 v[28:31], v[204:207], v[228:231], v[28:31]
	v_mfma_f32_16x16x32_bf16 v[12:15], v[200:203], v[232:235], v[12:15]
	v_mfma_f32_16x16x32_bf16 v[12:15], v[204:207], v[236:239], v[12:15]
	v_mfma_f32_16x16x32_bf16 v[8:11], v[208:211], v[232:235], v[8:11]
	v_mfma_f32_16x16x32_bf16 v[8:11], v[212:215], v[236:239], v[8:11]
	v_mfma_f32_16x16x32_bf16 v[0:3], v[208:211], v[240:243], v[0:3]
	v_mfma_f32_16x16x32_bf16 v[0:3], v[212:215], v[244:247], v[0:3]
	v_mfma_f32_16x16x32_bf16 v[4:7], v[200:203], v[240:243], v[4:7]
	v_mfma_f32_16x16x32_bf16 v[4:7], v[204:207], v[244:247], v[4:7]
	s_barrier
; #define PG8_STAGE(bufoff, gbase, voff) do { _Pragma("unroll") for (int _i = 0; _i < 2; ++_i) \
;         __builtin_amdgcn_global_load_lds((const unsigned*)((const char*)(gbase) + (voff)[_i]), (PG8_LAS unsigned*)(lds + (bufoff) + ldsw + _i * 8192), 16, 0, 0); } while (0)
; #define PG8_LDA(dst, b, h) do { _Pragma("unroll") for (int m = 0; m < 4; ++m) _Pragma("unroll") for (int k = 0; k < 2; ++k) dst[m][k] = *(const PG8_LAS bf16x8*)(lds + PG8_SA(b, h) + aoff + m * 2048 + k * 1024); } while (0)
; #define PG8_LDB(dst, b, h) do { _Pragma("unroll") for (int n = 0; n < 2; ++n) _Pragma("unroll") for (int k = 0; k < 2; ++k) dst[n][k] = *(const PG8_LAS bf16x8*)(lds + PG8_SB(b, h) + boff + n * 2048 + k * 1024); } while (0)
; #define PG8_MMA(ai, bj, At, Bt) do { __builtin_amdgcn_s_setprio(1); _Pragma("unroll") for (int m = 0; m < 4; ++m) _Pragma("unroll") for (int n = 0; n < 2; ++n) _Pragma("unroll") for (int k = 0; k < 2; ++k) \
;         acc[ai][bj][m][n] = __builtin_amdgcn_mfma_f32_16x16x32_bf16(Bt[n][k], At[m][k], acc[ai][bj][m][n], 0, 0, 0); __builtin_amdgcn_s_setprio(0); } while (0)
; #define PG8_WAIT_V(n) asm volatile("s_waitcnt vmcnt(" #n ")" ::: "memory")
; #define PG8_WAIT_L(n) asm volatile("s_waitcnt lgkmcnt(" #n ")" ::: "memory")
; #define PG8_BAR __builtin_amdgcn_s_barrier()
; #define PG8_SCHED __builtin_amdgcn_sched_barrier(0)
; template <class Epi, class Sched, bool ALIGN_EPI = false, bool SP2 = false>
; __device__ __forceinline__ void gemm_phase(PG8_LAS unsigned char* lds, const Gemm g, const Sched& S, const Epi& E) {
;     ...
;             PG8_LDB(B0, 1, 0); PG8_LDB(B1, 1, 1); PG8_SCHED; PG8_LDA(At, 1, 0); PG8_STAGE(PG8_SA(0, 1), a2 + hstep, voffA);
;             PG8_WAIT_V(8); PG8_WAIT_L(0); PG8_BAR; PG8_MMA(0, 0, At, B0); PG8_MMA(0, 1, At, B1); PG8_BAR; PG8_SCHED;
;             PG8_LDA(At, 1, 1); PG8_STAGE(PG8_SB(1, 0), b3, voffB); PG8_STAGE(PG8_SB(1, 1), b3 + hstep, voffB); PG8_STAGE(PG8_SA(1, 0), a3, voffA);
;             PG8_WAIT_V(8); PG8_WAIT_L(0); PG8_BAR; PG8_MMA(1, 0, At, B0); PG8_MMA(1, 1, At, B1); PG8_BAR; PG8_SCHED;
	s_add_i32 s12, 0, 0x18000
	v_add_u32_e32 v195, s12, v169
	s_add_i32 s13, 0, 0x1c000
	ds_read_b128 v[150:153], v195
	ds_read_b128 v[158:161], v195 offset:1024
	ds_read_b128 v[162:165], v195 offset:2048
	ds_read_b128 v[196:199], v195 offset:3072
	v_add_u32_e32 v195, s13, v169
	ds_read_b128 v[200:203], v195
	ds_read_b128 v[204:207], v195 offset:1024
	ds_read_b128 v[208:211], v195 offset:2048
	ds_read_b128 v[212:215], v195 offset:3072
	s_mov_b32 m0, s75
	s_nop 0
	global_load_lds_dwordx4 v132, s[68:69]
	s_mov_b32 m0, s76
	s_nop 0
	global_load_lds_dwordx4 v136, s[68:69]
	s_add_u32 s68, s68, 0x40000
	s_addc_u32 s69, s69, 0
	s_mov_b32 m0, s77
	ds_read_b128 v[216:219], v191 offset:32768
	ds_read_b128 v[220:223], v191 offset:33792
	ds_read_b128 v[224:227], v191 offset:34816
	ds_read_b128 v[228:231], v191 offset:35840
	ds_read_b128 v[232:235], v191 offset:36864
	ds_read_b128 v[236:239], v191 offset:37888
	ds_read_b128 v[240:243], v191 offset:38912
	ds_read_b128 v[244:247], v191 offset:39936
	global_load_lds_dwordx4 v132, s[68:69]
	s_mov_b32 m0, s78
	s_nop 0
	global_load_lds_dwordx4 v136, s[68:69]
	s_waitcnt vmcnt(8)
	s_waitcnt lgkmcnt(0)
	s_barrier
	v_mfma_f32_16x16x32_bf16 v[124:127], v[150:153], v[216:219], v[124:127]
	v_mfma_f32_16x16x32_bf16 v[124:127], v[158:161], v[220:223], v[124:127]
	v_mfma_f32_16x16x32_bf16 v[120:123], v[162:165], v[216:219], v[120:123]
	v_mfma_f32_16x16x32_bf16 v[120:123], v[196:199], v[220:223], v[120:123]
	v_mfma_f32_16x16x32_bf16 v[104:107], v[162:165], v[224:227], v[104:107]
	v_mfma_f32_16x16x32_bf16 v[104:107], v[196:199], v[228:231], v[104:107]
	v_mfma_f32_16x16x32_bf16 v[112:115], v[150:153], v[224:227], v[112:115]
	v_mfma_f32_16x16x32_bf16 v[112:115], v[158:161], v[228:231], v[112:115]
	v_mfma_f32_16x16x32_bf16 v[100:103], v[150:153], v[232:235], v[100:103]
	v_mfma_f32_16x16x32_bf16 v[100:103], v[158:161], v[236:239], v[100:103]
	v_mfma_f32_16x16x32_bf16 v[96:99], v[162:165], v[232:235], v[96:99]
	v_mfma_f32_16x16x32_bf16 v[96:99], v[196:199], v[236:239], v[96:99]
	v_mfma_f32_16x16x32_bf16 v[72:75], v[162:165], v[240:243], v[72:75]
	v_mfma_f32_16x16x32_bf16 v[72:75], v[196:199], v[244:247], v[72:75]
	v_mfma_f32_16x16x32_bf16 v[80:83], v[150:153], v[240:243], v[80:83]
	v_mfma_f32_16x16x32_bf16 v[80:83], v[158:161], v[244:247], v[80:83]
	v_mfma_f32_16x16x32_bf16 v[116:119], v[200:203], v[216:219], v[116:119]
	v_mfma_f32_16x16x32_bf16 v[116:119], v[204:207], v[220:223], v[116:119]
	v_mfma_f32_16x16x32_bf16 v[108:111], v[208:211], v[216:219], v[108:111]
	v_mfma_f32_16x16x32_bf16 v[108:111], v[212:215], v[220:223], v[108:111]
	v_mfma_f32_16x16x32_bf16 v[88:91], v[208:211], v[224:227], v[88:91]
	v_mfma_f32_16x16x32_bf16 v[88:91], v[212:215], v[228:231], v[88:91]
	v_mfma_f32_16x16x32_bf16 v[92:95], v[200:203], v[224:227], v[92:95]
	v_mfma_f32_16x16x32_bf16 v[92:95], v[204:207], v[228:231], v[92:95]
	v_mfma_f32_16x16x32_bf16 v[84:87], v[200:203], v[232:235], v[84:87]
	v_mfma_f32_16x16x32_bf16 v[84:87], v[204:207], v[236:239], v[84:87]
	v_mfma_f32_16x16x32_bf16 v[76:79], v[208:211], v[232:235], v[76:79]
	v_mfma_f32_16x16x32_bf16 v[76:79], v[212:215], v[236:239], v[76:79]
	v_mfma_f32_16x16x32_bf16 v[64:67], v[208:211], v[240:243], v[64:67]
	v_mfma_f32_16x16x32_bf16 v[64:67], v[212:215], v[244:247], v[64:67]
	v_mfma_f32_16x16x32_bf16 v[68:71], v[200:203], v[240:243], v[68:71]
	v_mfma_f32_16x16x32_bf16 v[68:71], v[204:207], v[244:247], v[68:71]
	s_barrier
	s_add_i32 s12, s12, s74
	s_add_u32 s98, s66, s42
	s_addc_u32 s99, s67, s43
	s_mov_b32 m0, s12
	ds_read_b128 v[216:219], v191 offset:49152
	ds_read_b128 v[220:223], v191 offset:50176
	ds_read_b128 v[224:227], v191 offset:51200
	ds_read_b128 v[228:231], v191 offset:52224
	ds_read_b128 v[232:235], v191 offset:53248
	ds_read_b128 v[236:239], v191 offset:54272
	ds_read_b128 v[240:243], v191 offset:55296
	ds_read_b128 v[244:247], v191 offset:56320
	global_load_lds_dwordx4 v134, s[98:99]
	s_add_i32 m0, s12, 0x2000
	s_add_u32 s66, s66, 0x40080
	v_lshl_add_u64 v[130:131], v[154:155], 0, s[42:43]
	s_addc_u32 s67, s67, 0
	s_add_i32 s12, s13, s74
	global_load_lds_dwordx4 v[130:131], off
	s_mov_b32 m0, s12
	s_nop 0
	global_load_lds_dwordx4 v134, s[66:67]
	s_add_i32 m0, s12, 0x2000
	s_nop 0
	global_load_lds_dwordx4 v138, s[66:67]
	v_lshl_add_u64 v[130:131], v[166:167], 0, s[42:43]
	s_mov_b32 m0, s79
	s_nop 0
	global_load_lds_dwordx4 v[130:131], off
	v_lshl_add_u64 v[130:131], v[248:249], 0, s[42:43]
	s_mov_b32 m0, s80
	s_nop 0
	global_load_lds_dwordx4 v[130:131], off
	s_waitcnt vmcnt(6)
	s_waitcnt lgkmcnt(0)
	s_barrier
	v_mfma_f32_16x16x32_bf16 v[60:63], v[150:153], v[216:219], v[60:63]
	v_mfma_f32_16x16x32_bf16 v[60:63], v[158:161], v[220:223], v[60:63]
	v_mfma_f32_16x16x32_bf16 v[56:59], v[162:165], v[216:219], v[56:59]
	v_mfma_f32_16x16x32_bf16 v[56:59], v[196:199], v[220:223], v[56:59]
	v_mfma_f32_16x16x32_bf16 v[40:43], v[162:165], v[224:227], v[40:43]
	v_mfma_f32_16x16x32_bf16 v[40:43], v[196:199], v[228:231], v[40:43]
	v_mfma_f32_16x16x32_bf16 v[48:51], v[150:153], v[224:227], v[48:51]
	v_mfma_f32_16x16x32_bf16 v[48:51], v[158:161], v[228:231], v[48:51]
	v_mfma_f32_16x16x32_bf16 v[36:39], v[150:153], v[232:235], v[36:39]
	v_mfma_f32_16x16x32_bf16 v[36:39], v[158:161], v[236:239], v[36:39]
	v_mfma_f32_16x16x32_bf16 v[32:35], v[162:165], v[232:235], v[32:35]
	v_mfma_f32_16x16x32_bf16 v[32:35], v[196:199], v[236:239], v[32:35]
	v_mfma_f32_16x16x32_bf16 v[16:19], v[162:165], v[240:243], v[16:19]
	v_mfma_f32_16x16x32_bf16 v[16:19], v[196:199], v[244:247], v[16:19]
	v_mfma_f32_16x16x32_bf16 v[20:23], v[150:153], v[240:243], v[20:23]
	v_mfma_f32_16x16x32_bf16 v[20:23], v[158:161], v[244:247], v[20:23]
	v_mfma_f32_16x16x32_bf16 v[52:55], v[200:203], v[216:219], v[52:55]
	v_mfma_f32_16x16x32_bf16 v[52:55], v[204:207], v[220:223], v[52:55]
	v_mfma_f32_16x16x32_bf16 v[44:47], v[208:211], v[216:219], v[44:47]
	v_mfma_f32_16x16x32_bf16 v[44:47], v[212:215], v[220:223], v[44:47]
	v_mfma_f32_16x16x32_bf16 v[24:27], v[208:211], v[224:227], v[24:27]
	v_mfma_f32_16x16x32_bf16 v[24:27], v[212:215], v[228:231], v[24:27]
	v_mfma_f32_16x16x32_bf16 v[28:31], v[200:203], v[224:227], v[28:31]
	v_mfma_f32_16x16x32_bf16 v[28:31], v[204:207], v[228:231], v[28:31]
	v_mfma_f32_16x16x32_bf16 v[12:15], v[200:203], v[232:235], v[12:15]
	v_mfma_f32_16x16x32_bf16 v[12:15], v[204:207], v[236:239], v[12:15]
	v_mfma_f32_16x16x32_bf16 v[8:11], v[208:211], v[232:235], v[8:11]
	v_mfma_f32_16x16x32_bf16 v[8:11], v[212:215], v[236:239], v[8:11]
	v_mfma_f32_16x16x32_bf16 v[0:3], v[208:211], v[240:243], v[0:3]
	v_mfma_f32_16x16x32_bf16 v[0:3], v[212:215], v[244:247], v[0:3]
	v_mfma_f32_16x16x32_bf16 v[4:7], v[200:203], v[240:243], v[4:7]
	v_mfma_f32_16x16x32_bf16 v[4:7], v[204:207], v[244:247], v[4:7]
	s_barrier
	s_add_i32 s96, s96, 2
	s_add_u32 s65, s65, 0x100
	s_addc_u32 s71, s71, 0
	s_add_u32 s10, s10, 0x100
	s_addc_u32 s11, s11, 0
	s_cmp_gt_u32 s96, 13
	s_cbranch_scc1 .LBB0_963

; #define PG8_STAGE(bufoff, gbase, voff) do { _Pragma("unroll") for (int _i = 0; _i < 2; ++_i) \
;         __builtin_amdgcn_global_load_lds((const unsigned*)((const char*)(gbase) + (voff)[_i]), (PG8_LAS unsigned*)(lds + (bufoff) + ldsw + _i * 8192), 16, 0, 0); } while (0)
; #define PG8_LDA(dst, b, h) do { _Pragma("unroll") for (int m = 0; m < 4; ++m) _Pragma("unroll") for (int k = 0; k < 2; ++k) dst[m][k] = *(const PG8_LAS bf16x8*)(lds + PG8_SA(b, h) + aoff + m * 2048 + k * 1024); } while (0)
; #define PG8_LDB(dst, b, h) do { _Pragma("unroll") for (int n = 0; n < 2; ++n) _Pragma("unroll") for (int k = 0; k < 2; ++k) dst[n][k] = *(const PG8_LAS bf16x8*)(lds + PG8_SB(b, h) + boff + n * 2048 + k * 1024); } while (0)
; #define PG8_MMA(ai, bj, At, Bt) do { __builtin_amdgcn_s_setprio(1); _Pragma("unroll") for (int m = 0; m < 4; ++m) _Pragma("unroll") for (int n = 0; n < 2; ++n) _Pragma("unroll") for (int k = 0; k < 2; ++k) \
;         acc[ai][bj][m][n] = __builtin_amdgcn_mfma_f32_16x16x32_bf16(Bt[n][k], At[m][k], acc[ai][bj][m][n], 0, 0, 0); __builtin_amdgcn_s_setprio(0); } while (0)
; #define PG8_WAIT_V(n) asm volatile("s_waitcnt vmcnt(" #n ")" ::: "memory")
; #define PG8_WAIT_L(n) asm volatile("s_waitcnt lgkmcnt(" #n ")" ::: "memory")
; #define PG8_BAR __builtin_amdgcn_s_barrier()
; #define PG8_SCHED __builtin_amdgcn_sched_barrier(0)
; template <class Epi, class Sched, bool ALIGN_EPI = false, bool SP2 = false>
; __device__ __forceinline__ void gemm_phase(PG8_LAS unsigned char* lds, const Gemm g, const Sched& S, const Epi& E) {
;     ...
;             PG8_LDB(B0, 0, 0); PG8_LDB(B1, 0, 1); PG8_SCHED; PG8_LDA(At, 0, 0); PG8_STAGE(PG8_SA(1, 1), a1 + hstep, voffA);
;             PG8_WAIT_V(8); PG8_WAIT_L(0); PG8_BAR; PG8_MMA(0, 0, At, B0); PG8_MMA(0, 1, At, B1); PG8_BAR; PG8_SCHED;
;             PG8_LDA(At, 0, 1); PG8_STAGE(PG8_SB(0, 0), b2, voffB); PG8_STAGE(PG8_SB(0, 1), b2 + hstep, voffB); PG8_STAGE(PG8_SA(0, 0), a2, voffA);
;             PG8_WAIT_V(8); PG8_WAIT_L(0); PG8_BAR; PG8_MMA(1, 0, At, B0); PG8_MMA(1, 1, At, B1); PG8_BAR; PG8_SCHED;
.LBB0_1272:
	ds_read_b128 v[128:131], v167
	ds_read_b128 v[132:135], v167 offset:1024
	ds_read_b128 v[136:139], v167 offset:2048
	ds_read_b128 v[140:143], v167 offset:3072
	ds_read_b128 v[160:163], v168
	ds_read_b128 v[170:173], v168 offset:1024
	ds_read_b128 v[174:177], v168 offset:2048
	ds_read_b128 v[178:181], v168 offset:3072
	s_add_u32 s12, s50, 0xfffc0080
	s_addc_u32 s13, s51, -1
	s_cmp_eq_u32 s79, 12
	s_cselect_b32 s55, s41, s13
	s_cselect_b32 s54, s47, s12
	s_cselect_b32 s53, s39, s78
	s_cselect_b32 s52, s49, s77
	s_add_i32 m0, s60, 0xc000
	ds_read_b128 v[188:191], v169
	ds_read_b128 v[192:195], v169 offset:1024
	ds_read_b128 v[196:199], v169 offset:2048
	ds_read_b128 v[200:203], v169 offset:3072
	ds_read_b128 v[204:207], v169 offset:4096
	ds_read_b128 v[208:211], v169 offset:5120
	ds_read_b128 v[212:215], v169 offset:6144
	ds_read_b128 v[216:219], v169 offset:7168
	global_load_lds_dwordx4 v154, s[50:51]
	s_add_i32 m0, s60, 0xe000
	s_nop 0
	global_load_lds_dwordx4 v152, s[50:51]
	s_waitcnt vmcnt(8)
	s_waitcnt lgkmcnt(0)
	s_barrier
	v_mfma_f32_16x16x32_bf16 v[124:127], v[128:131], v[188:191], v[124:127]
	v_mfma_f32_16x16x32_bf16 v[124:127], v[132:135], v[192:195], v[124:127]
	v_mfma_f32_16x16x32_bf16 v[120:123], v[136:139], v[188:191], v[120:123]
	v_mfma_f32_16x16x32_bf16 v[120:123], v[140:143], v[192:195], v[120:123]
	v_mfma_f32_16x16x32_bf16 v[108:111], v[136:139], v[196:199], v[108:111]
	v_mfma_f32_16x16x32_bf16 v[108:111], v[140:143], v[200:203], v[108:111]
	v_mfma_f32_16x16x32_bf16 v[116:119], v[128:131], v[196:199], v[116:119]
	v_mfma_f32_16x16x32_bf16 v[116:119], v[132:135], v[200:203], v[116:119]
	v_mfma_f32_16x16x32_bf16 v[100:103], v[128:131], v[204:207], v[100:103]
	v_mfma_f32_16x16x32_bf16 v[100:103], v[132:135], v[208:211], v[100:103]
	v_mfma_f32_16x16x32_bf16 v[92:95], v[136:139], v[204:207], v[92:95]
	v_mfma_f32_16x16x32_bf16 v[92:95], v[140:143], v[208:211], v[92:95]
	v_mfma_f32_16x16x32_bf16 v[76:79], v[136:139], v[212:215], v[76:79]
	v_mfma_f32_16x16x32_bf16 v[76:79], v[140:143], v[216:219], v[76:79]
	v_mfma_f32_16x16x32_bf16 v[84:87], v[128:131], v[212:215], v[84:87]
	v_mfma_f32_16x16x32_bf16 v[84:87], v[132:135], v[216:219], v[84:87]
	v_mfma_f32_16x16x32_bf16 v[112:115], v[160:163], v[188:191], v[112:115]
	v_mfma_f32_16x16x32_bf16 v[112:115], v[170:173], v[192:195], v[112:115]
	v_mfma_f32_16x16x32_bf16 v[104:107], v[174:177], v[188:191], v[104:107]
	v_mfma_f32_16x16x32_bf16 v[104:107], v[178:181], v[192:195], v[104:107]
	v_mfma_f32_16x16x32_bf16 v[88:91], v[174:177], v[196:199], v[88:91]
	v_mfma_f32_16x16x32_bf16 v[88:91], v[178:181], v[200:203], v[88:91]
	v_mfma_f32_16x16x32_bf16 v[96:99], v[160:163], v[196:199], v[96:99]
	v_mfma_f32_16x16x32_bf16 v[96:99], v[170:173], v[200:203], v[96:99]
	v_mfma_f32_16x16x32_bf16 v[80:83], v[160:163], v[204:207], v[80:83]
	v_mfma_f32_16x16x32_bf16 v[80:83], v[170:173], v[208:211], v[80:83]
	v_mfma_f32_16x16x32_bf16 v[72:75], v[174:177], v[204:207], v[72:75]
	v_mfma_f32_16x16x32_bf16 v[72:75], v[178:181], v[208:211], v[72:75]
	v_mfma_f32_16x16x32_bf16 v[64:67], v[174:177], v[212:215], v[64:67]
	v_mfma_f32_16x16x32_bf16 v[64:67], v[178:181], v[216:219], v[64:67]
	v_mfma_f32_16x16x32_bf16 v[68:71], v[160:163], v[212:215], v[68:71]
	v_mfma_f32_16x16x32_bf16 v[68:71], v[170:173], v[216:219], v[68:71]
	s_barrier
	s_add_i32 s12, s75, s59
	s_mov_b32 m0, s12
	ds_read_b128 v[188:191], v169 offset:16384
	ds_read_b128 v[192:195], v169 offset:17408
	ds_read_b128 v[196:199], v169 offset:18432
	ds_read_b128 v[200:203], v169 offset:19456
	ds_read_b128 v[204:207], v169 offset:20480
	ds_read_b128 v[208:211], v169 offset:21504
	ds_read_b128 v[212:215], v169 offset:22528
	ds_read_b128 v[216:219], v169 offset:23552
	global_load_lds_dwordx4 v146, s[52:53]
	s_add_i32 m0, s12, 0x2000
	s_add_u32 s80, s52, 0x40000
	v_lshl_add_u64 v[220:221], s[52:53], 0, v[150:151]
	s_addc_u32 s81, s53, 0
	s_add_i32 s12, s76, s59
	global_load_lds_dwordx4 v150, s[52:53]
	s_mov_b32 m0, s12
	v_lshl_add_u64 v[224:225], s[54:55], 0, v[148:149]
	global_load_lds_dwordx4 v146, s[80:81]
	s_add_i32 m0, s12, 0x2000
	s_nop 0
	global_load_lds_dwordx4 v150, s[80:81]
	v_lshl_add_u64 v[222:223], s[54:55], 0, v[144:145]
	s_waitcnt vmcnt(6)
	s_waitcnt lgkmcnt(0)
	s_barrier
	v_mfma_f32_16x16x32_bf16 v[60:63], v[128:131], v[188:191], v[60:63]
	v_mfma_f32_16x16x32_bf16 v[60:63], v[132:135], v[192:195], v[60:63]
	v_mfma_f32_16x16x32_bf16 v[56:59], v[136:139], v[188:191], v[56:59]
	v_mfma_f32_16x16x32_bf16 v[56:59], v[140:143], v[192:195], v[56:59]
	v_mfma_f32_16x16x32_bf16 v[44:47], v[136:139], v[196:199], v[44:47]
	v_mfma_f32_16x16x32_bf16 v[44:47], v[140:143], v[200:203], v[44:47]
	v_mfma_f32_16x16x32_bf16 v[48:51], v[128:131], v[196:199], v[48:51]
	v_mfma_f32_16x16x32_bf16 v[48:51], v[132:135], v[200:203], v[48:51]
	v_mfma_f32_16x16x32_bf16 v[36:39], v[128:131], v[204:207], v[36:39]
	v_mfma_f32_16x16x32_bf16 v[36:39], v[132:135], v[208:211], v[36:39]
	v_mfma_f32_16x16x32_bf16 v[28:31], v[136:139], v[204:207], v[28:31]
	v_mfma_f32_16x16x32_bf16 v[28:31], v[140:143], v[208:211], v[28:31]
	v_mfma_f32_16x16x32_bf16 v[12:15], v[136:139], v[212:215], v[12:15]
	v_mfma_f32_16x16x32_bf16 v[12:15], v[140:143], v[216:219], v[12:15]
	v_mfma_f32_16x16x32_bf16 v[20:23], v[128:131], v[212:215], v[20:23]
	v_mfma_f32_16x16x32_bf16 v[20:23], v[132:135], v[216:219], v[20:23]
	v_mfma_f32_16x16x32_bf16 v[52:55], v[160:163], v[188:191], v[52:55]
	v_mfma_f32_16x16x32_bf16 v[52:55], v[170:173], v[192:195], v[52:55]
	v_mfma_f32_16x16x32_bf16 v[40:43], v[174:177], v[188:191], v[40:43]
	v_mfma_f32_16x16x32_bf16 v[40:43], v[178:181], v[192:195], v[40:43]
	v_mfma_f32_16x16x32_bf16 v[24:27], v[174:177], v[196:199], v[24:27]
	v_mfma_f32_16x16x32_bf16 v[24:27], v[178:181], v[200:203], v[24:27]
	v_mfma_f32_16x16x32_bf16 v[32:35], v[160:163], v[196:199], v[32:35]
	v_mfma_f32_16x16x32_bf16 v[32:35], v[170:173], v[200:203], v[32:35]
	v_mfma_f32_16x16x32_bf16 v[16:19], v[160:163], v[204:207], v[16:19]
	v_mfma_f32_16x16x32_bf16 v[16:19], v[170:173], v[208:211], v[16:19]
	v_mfma_f32_16x16x32_bf16 v[8:11], v[174:177], v[204:207], v[8:11]
	v_mfma_f32_16x16x32_bf16 v[8:11], v[178:181], v[208:211], v[8:11]
	v_mfma_f32_16x16x32_bf16 v[0:3], v[174:177], v[212:215], v[0:3]
	v_mfma_f32_16x16x32_bf16 v[0:3], v[178:181], v[216:219], v[0:3]
	v_mfma_f32_16x16x32_bf16 v[4:7], v[160:163], v[212:215], v[4:7]
	v_mfma_f32_16x16x32_bf16 v[4:7], v[170:173], v[216:219], v[4:7]
	s_barrier
; #define PG8_STAGE(bufoff, gbase, voff) do { _Pragma("unroll") for (int _i = 0; _i < 2; ++_i) \
;         __builtin_amdgcn_global_load_lds((const unsigned*)((const char*)(gbase) + (voff)[_i]), (PG8_LAS unsigned*)(lds + (bufoff) + ldsw + _i * 8192), 16, 0, 0); } while (0)
; #define PG8_LDA(dst, b, h) do { _Pragma("unroll") for (int m = 0; m < 4; ++m) _Pragma("unroll") for (int k = 0; k < 2; ++k) dst[m][k] = *(const PG8_LAS bf16x8*)(lds + PG8_SA(b, h) + aoff + m * 2048 + k * 1024); } while (0)
; #define PG8_LDB(dst, b, h) do { _Pragma("unroll") for (int n = 0; n < 2; ++n) _Pragma("unroll") for (int k = 0; k < 2; ++k) dst[n][k] = *(const PG8_LAS bf16x8*)(lds + PG8_SB(b, h) + boff + n * 2048 + k * 1024); } while (0)
; #define PG8_MMA(ai, bj, At, Bt) do { __builtin_amdgcn_s_setprio(1); _Pragma("unroll") for (int m = 0; m < 4; ++m) _Pragma("unroll") for (int n = 0; n < 2; ++n) _Pragma("unroll") for (int k = 0; k < 2; ++k) \
;         acc[ai][bj][m][n] = __builtin_amdgcn_mfma_f32_16x16x32_bf16(Bt[n][k], At[m][k], acc[ai][bj][m][n], 0, 0, 0); __builtin_amdgcn_s_setprio(0); } while (0)
; #define PG8_WAIT_V(n) asm volatile("s_waitcnt vmcnt(" #n ")" ::: "memory")
; #define PG8_WAIT_L(n) asm volatile("s_waitcnt lgkmcnt(" #n ")" ::: "memory")
; #define PG8_BAR __builtin_amdgcn_s_barrier()
; #define PG8_SCHED __builtin_amdgcn_sched_barrier(0)
; template <class Epi, class Sched, bool ALIGN_EPI = false, bool SP2 = false>
; __device__ __forceinline__ void gemm_phase(PG8_LAS unsigned char* lds, const Gemm g, const Sched& S, const Epi& E) {
;     ...
;             PG8_LDB(B0, 1, 0); PG8_LDB(B1, 1, 1); PG8_SCHED; PG8_LDA(At, 1, 0); PG8_STAGE(PG8_SA(0, 1), a2 + hstep, voffA);
;             PG8_WAIT_V(8); PG8_WAIT_L(0); PG8_BAR; PG8_MMA(0, 0, At, B0); PG8_MMA(0, 1, At, B1); PG8_BAR; PG8_SCHED;
;             PG8_LDA(At, 1, 1); PG8_STAGE(PG8_SB(1, 0), b3, voffB); PG8_STAGE(PG8_SB(1, 1), b3 + hstep, voffB); PG8_STAGE(PG8_SA(1, 0), a3, voffA);
;             PG8_WAIT_V(8); PG8_WAIT_L(0); PG8_BAR; PG8_MMA(1, 0, At, B0); PG8_MMA(1, 1, At, B1); PG8_BAR; PG8_SCHED;
	s_add_i32 s12, 0, 0x18000
	s_add_i32 s13, 0, 0x1c000
	v_add_u32_e32 v140, s12, v165
	v_add_u32_e32 v178, s13, v165
	ds_read_b128 v[128:131], v140
	ds_read_b128 v[132:135], v140 offset:1024
	ds_read_b128 v[136:139], v140 offset:2048
	ds_read_b128 v[140:143], v140 offset:3072
	ds_read_b128 v[160:163], v178
	ds_read_b128 v[170:173], v178 offset:1024
	ds_read_b128 v[174:177], v178 offset:2048
	ds_read_b128 v[178:181], v178 offset:3072
	s_mov_b32 m0, s60
	s_nop 0
	global_load_lds_dwordx4 v144, s[54:55]
	s_mov_b32 m0, s61
	s_nop 0
	global_load_lds_dwordx4 v148, s[54:55]
	s_add_u32 s54, s54, 0x40000
	s_addc_u32 s55, s55, 0
	s_mov_b32 m0, s62
	ds_read_b128 v[188:191], v169 offset:32768
	ds_read_b128 v[192:195], v169 offset:33792
	ds_read_b128 v[196:199], v169 offset:34816
	ds_read_b128 v[200:203], v169 offset:35840
	ds_read_b128 v[204:207], v169 offset:36864
	ds_read_b128 v[208:211], v169 offset:37888
	ds_read_b128 v[212:215], v169 offset:38912
	ds_read_b128 v[216:219], v169 offset:39936
	global_load_lds_dwordx4 v144, s[54:55]
	s_mov_b32 m0, s63
	s_nop 0
	global_load_lds_dwordx4 v148, s[54:55]
	s_waitcnt vmcnt(8)
	s_waitcnt lgkmcnt(0)
	s_barrier
	v_mfma_f32_16x16x32_bf16 v[124:127], v[128:131], v[188:191], v[124:127]
	v_mfma_f32_16x16x32_bf16 v[124:127], v[132:135], v[192:195], v[124:127]
	v_mfma_f32_16x16x32_bf16 v[120:123], v[136:139], v[188:191], v[120:123]
	v_mfma_f32_16x16x32_bf16 v[120:123], v[140:143], v[192:195], v[120:123]
	v_mfma_f32_16x16x32_bf16 v[108:111], v[136:139], v[196:199], v[108:111]
	v_mfma_f32_16x16x32_bf16 v[108:111], v[140:143], v[200:203], v[108:111]
	v_mfma_f32_16x16x32_bf16 v[116:119], v[128:131], v[196:199], v[116:119]
	v_mfma_f32_16x16x32_bf16 v[116:119], v[132:135], v[200:203], v[116:119]
	v_mfma_f32_16x16x32_bf16 v[100:103], v[128:131], v[204:207], v[100:103]
	v_mfma_f32_16x16x32_bf16 v[100:103], v[132:135], v[208:211], v[100:103]
	v_mfma_f32_16x16x32_bf16 v[92:95], v[136:139], v[204:207], v[92:95]
	v_mfma_f32_16x16x32_bf16 v[92:95], v[140:143], v[208:211], v[92:95]
	v_mfma_f32_16x16x32_bf16 v[76:79], v[136:139], v[212:215], v[76:79]
	v_mfma_f32_16x16x32_bf16 v[76:79], v[140:143], v[216:219], v[76:79]
	v_mfma_f32_16x16x32_bf16 v[84:87], v[128:131], v[212:215], v[84:87]
	v_mfma_f32_16x16x32_bf16 v[84:87], v[132:135], v[216:219], v[84:87]
	v_mfma_f32_16x16x32_bf16 v[112:115], v[160:163], v[188:191], v[112:115]
	v_mfma_f32_16x16x32_bf16 v[112:115], v[170:173], v[192:195], v[112:115]
	v_mfma_f32_16x16x32_bf16 v[104:107], v[174:177], v[188:191], v[104:107]
	v_mfma_f32_16x16x32_bf16 v[104:107], v[178:181], v[192:195], v[104:107]
	v_mfma_f32_16x16x32_bf16 v[88:91], v[174:177], v[196:199], v[88:91]
	v_mfma_f32_16x16x32_bf16 v[88:91], v[178:181], v[200:203], v[88:91]
	v_mfma_f32_16x16x32_bf16 v[96:99], v[160:163], v[196:199], v[96:99]
	v_mfma_f32_16x16x32_bf16 v[96:99], v[170:173], v[200:203], v[96:99]
	v_mfma_f32_16x16x32_bf16 v[80:83], v[160:163], v[204:207], v[80:83]
	v_mfma_f32_16x16x32_bf16 v[80:83], v[170:173], v[208:211], v[80:83]
	v_mfma_f32_16x16x32_bf16 v[72:75], v[174:177], v[204:207], v[72:75]
	v_mfma_f32_16x16x32_bf16 v[72:75], v[178:181], v[208:211], v[72:75]
	v_mfma_f32_16x16x32_bf16 v[64:67], v[174:177], v[212:215], v[64:67]
	v_mfma_f32_16x16x32_bf16 v[64:67], v[178:181], v[216:219], v[64:67]
	v_mfma_f32_16x16x32_bf16 v[68:71], v[160:163], v[212:215], v[68:71]
	v_mfma_f32_16x16x32_bf16 v[68:71], v[170:173], v[216:219], v[68:71]
	s_barrier
	s_add_i32 s12, s12, s59
	s_add_u32 s98, s52, s22
	s_addc_u32 s99, s53, s23
	s_mov_b32 m0, s12
	ds_read_b128 v[188:191], v169 offset:49152
	ds_read_b128 v[192:195], v169 offset:50176
	ds_read_b128 v[196:199], v169 offset:51200
	ds_read_b128 v[200:203], v169 offset:52224
	ds_read_b128 v[204:207], v169 offset:53248
	ds_read_b128 v[208:211], v169 offset:54272
	ds_read_b128 v[212:215], v169 offset:55296
	ds_read_b128 v[216:219], v169 offset:56320
	global_load_lds_dwordx4 v146, s[98:99]
	s_add_i32 m0, s12, 0x2000
	s_add_u32 s52, s52, 0x40080
	v_lshl_add_u64 v[184:185], v[220:221], 0, s[22:23]
	s_addc_u32 s53, s53, 0
	s_add_i32 s12, s13, s59
	global_load_lds_dwordx4 v[184:185], off
	s_mov_b32 m0, s12
	s_nop 0
	global_load_lds_dwordx4 v146, s[52:53]
	s_add_i32 m0, s12, 0x2000
	s_nop 0
	global_load_lds_dwordx4 v150, s[52:53]
	v_lshl_add_u64 v[184:185], v[222:223], 0, s[22:23]
	s_mov_b32 m0, s69
	s_nop 0
	global_load_lds_dwordx4 v[184:185], off
	v_lshl_add_u64 v[184:185], v[224:225], 0, s[22:23]
	s_mov_b32 m0, s70
	s_nop 0
	global_load_lds_dwordx4 v[184:185], off
	s_waitcnt vmcnt(6)
	s_waitcnt lgkmcnt(0)
	s_barrier
	v_mfma_f32_16x16x32_bf16 v[60:63], v[128:131], v[188:191], v[60:63]
	v_mfma_f32_16x16x32_bf16 v[60:63], v[132:135], v[192:195], v[60:63]
	v_mfma_f32_16x16x32_bf16 v[56:59], v[136:139], v[188:191], v[56:59]
	v_mfma_f32_16x16x32_bf16 v[56:59], v[140:143], v[192:195], v[56:59]
	v_mfma_f32_16x16x32_bf16 v[44:47], v[136:139], v[196:199], v[44:47]
	v_mfma_f32_16x16x32_bf16 v[44:47], v[140:143], v[200:203], v[44:47]
	v_mfma_f32_16x16x32_bf16 v[48:51], v[128:131], v[196:199], v[48:51]
	v_mfma_f32_16x16x32_bf16 v[48:51], v[132:135], v[200:203], v[48:51]
	v_mfma_f32_16x16x32_bf16 v[36:39], v[128:131], v[204:207], v[36:39]
	v_mfma_f32_16x16x32_bf16 v[36:39], v[132:135], v[208:211], v[36:39]
	v_mfma_f32_16x16x32_bf16 v[28:31], v[136:139], v[204:207], v[28:31]
	v_mfma_f32_16x16x32_bf16 v[28:31], v[140:143], v[208:211], v[28:31]
	v_mfma_f32_16x16x32_bf16 v[12:15], v[136:139], v[212:215], v[12:15]
	v_mfma_f32_16x16x32_bf16 v[12:15], v[140:143], v[216:219], v[12:15]
	v_mfma_f32_16x16x32_bf16 v[20:23], v[128:131], v[212:215], v[20:23]
	v_mfma_f32_16x16x32_bf16 v[20:23], v[132:135], v[216:219], v[20:23]
	v_mfma_f32_16x16x32_bf16 v[52:55], v[160:163], v[188:191], v[52:55]
	v_mfma_f32_16x16x32_bf16 v[52:55], v[170:173], v[192:195], v[52:55]
	v_mfma_f32_16x16x32_bf16 v[40:43], v[174:177], v[188:191], v[40:43]
	v_mfma_f32_16x16x32_bf16 v[40:43], v[178:181], v[192:195], v[40:43]
	v_mfma_f32_16x16x32_bf16 v[24:27], v[174:177], v[196:199], v[24:27]
	v_mfma_f32_16x16x32_bf16 v[24:27], v[178:181], v[200:203], v[24:27]
	v_mfma_f32_16x16x32_bf16 v[32:35], v[160:163], v[196:199], v[32:35]
	v_mfma_f32_16x16x32_bf16 v[32:35], v[170:173], v[200:203], v[32:35]
	v_mfma_f32_16x16x32_bf16 v[16:19], v[160:163], v[204:207], v[16:19]
	v_mfma_f32_16x16x32_bf16 v[16:19], v[170:173], v[208:211], v[16:19]
	v_mfma_f32_16x16x32_bf16 v[8:11], v[174:177], v[204:207], v[8:11]
	v_mfma_f32_16x16x32_bf16 v[8:11], v[178:181], v[208:211], v[8:11]
	v_mfma_f32_16x16x32_bf16 v[0:3], v[174:177], v[212:215], v[0:3]
	v_mfma_f32_16x16x32_bf16 v[0:3], v[178:181], v[216:219], v[0:3]
	v_mfma_f32_16x16x32_bf16 v[4:7], v[160:163], v[212:215], v[4:7]
	v_mfma_f32_16x16x32_bf16 v[4:7], v[170:173], v[216:219], v[4:7]
	s_barrier
	s_add_i32 s79, s79, 2
	s_add_u32 s77, s77, 0x100
	s_addc_u32 s78, s78, 0
	s_add_u32 s50, s50, 0x100
	s_addc_u32 s51, s51, 0
	s_cmp_gt_u32 s79, 13
	s_cbranch_scc0 .LBB0_1272
	s_and_b64 vcc, exec, s[36:37]
	s_cbranch_vccz .LBB0_1275
	s_barrier

; #define PG8_STAGE(bufoff, gbase, voff) do { _Pragma("unroll") for (int _i = 0; _i < 2; ++_i) \
;         __builtin_amdgcn_global_load_lds((const unsigned*)((const char*)(gbase) + (voff)[_i]), (PG8_LAS unsigned*)(lds + (bufoff) + ldsw + _i * 8192), 16, 0, 0); } while (0)
; #define PG8_LDA(dst, b, h) do { _Pragma("unroll") for (int m = 0; m < 4; ++m) _Pragma("unroll") for (int k = 0; k < 2; ++k) dst[m][k] = *(const PG8_LAS bf16x8*)(lds + PG8_SA(b, h) + aoff + m * 2048 + k * 1024); } while (0)
; #define PG8_LDB(dst, b, h) do { _Pragma("unroll") for (int n = 0; n < 2; ++n) _Pragma("unroll") for (int k = 0; k < 2; ++k) dst[n][k] = *(const PG8_LAS bf16x8*)(lds + PG8_SB(b, h) + boff + n * 2048 + k * 1024); } while (0)
; #define PG8_MMA(ai, bj, At, Bt) do { __builtin_amdgcn_s_setprio(1); _Pragma("unroll") for (int m = 0; m < 4; ++m) _Pragma("unroll") for (int n = 0; n < 2; ++n) _Pragma("unroll") for (int k = 0; k < 2; ++k) \
;         acc[ai][bj][m][n] = __builtin_amdgcn_mfma_f32_16x16x32_bf16(Bt[n][k], At[m][k], acc[ai][bj][m][n], 0, 0, 0); __builtin_amdgcn_s_setprio(0); } while (0)
; #define PG8_WAIT_V(n) asm volatile("s_waitcnt vmcnt(" #n ")" ::: "memory")
; #define PG8_WAIT_L(n) asm volatile("s_waitcnt lgkmcnt(" #n ")" ::: "memory")
; #define PG8_BAR __builtin_amdgcn_s_barrier()
; #define PG8_SCHED __builtin_amdgcn_sched_barrier(0)
; template <class Epi, class Sched, bool ALIGN_EPI = false, bool SP2 = false>
; __device__ __forceinline__ void gemm_phase(PG8_LAS unsigned char* lds, const Gemm g, const Sched& S, const Epi& E) {
;     ...
;             PG8_LDB(B0, 0, 0); PG8_LDB(B1, 0, 1); PG8_SCHED; PG8_LDA(At, 0, 0); PG8_STAGE(PG8_SA(1, 1), a1 + hstep, voffA);
;             PG8_WAIT_V(8); PG8_WAIT_L(0); PG8_BAR; PG8_MMA(0, 0, At, B0); PG8_MMA(0, 1, At, B1); PG8_BAR; PG8_SCHED;
;             PG8_LDA(At, 0, 1); PG8_STAGE(PG8_SB(0, 0), b2, voffB); PG8_STAGE(PG8_SB(0, 1), b2 + hstep, voffB); PG8_STAGE(PG8_SA(0, 0), a2, voffA);
;             PG8_WAIT_V(8); PG8_WAIT_L(0); PG8_BAR; PG8_MMA(1, 0, At, B0); PG8_MMA(1, 1, At, B1); PG8_BAR; PG8_SCHED;
.LBB0_1358:
	v_add_u32_e32 v130, s71, v163
	ds_read_b128 v[118:121], v130
	ds_read_b128 v[122:125], v130 offset:1024
	ds_read_b128 v[126:129], v130 offset:2048
	ds_read_b128 v[170:173], v130 offset:3072
	v_add_u32_e32 v130, s72, v163
	ds_read_b128 v[174:177], v130
	ds_read_b128 v[178:181], v130 offset:1024
	ds_read_b128 v[184:187], v130 offset:2048
	ds_read_b128 v[188:191], v130 offset:3072
	s_add_u32 s14, s48, 0xfffc0080
	s_addc_u32 s15, s49, -1
	s_and_b64 s[50:51], s[50:51], exec
	s_cselect_b32 s53, s39, s15
	s_cselect_b32 s52, s73, s14
	s_cselect_b32 s51, s37, s47
	s_cselect_b32 s50, s74, s45
	s_add_i32 m0, s58, 0xc000
	ds_read_b128 v[192:195], v168
	ds_read_b128 v[196:199], v168 offset:1024
	ds_read_b128 v[200:203], v168 offset:2048
	ds_read_b128 v[204:207], v168 offset:3072
	ds_read_b128 v[208:211], v168 offset:4096
	ds_read_b128 v[212:215], v168 offset:5120
	ds_read_b128 v[216:219], v168 offset:6144
	ds_read_b128 v[220:223], v168 offset:7168
	global_load_lds_dwordx4 v154, s[48:49]
	s_add_i32 m0, s58, 0xe000
	s_nop 0
	global_load_lds_dwordx4 v152, s[48:49]
	s_waitcnt vmcnt(8)
	s_waitcnt lgkmcnt(0)
	s_barrier
	v_mfma_f32_16x16x32_bf16 v[140:143], v[118:121], v[192:195], v[140:143]
	v_mfma_f32_16x16x32_bf16 v[140:143], v[122:125], v[196:199], v[140:143]
	v_mfma_f32_16x16x32_bf16 v[136:139], v[126:129], v[192:195], v[136:139]
	v_mfma_f32_16x16x32_bf16 v[136:139], v[170:173], v[196:199], v[136:139]
	v_mfma_f32_16x16x32_bf16 v[104:107], v[126:129], v[200:203], v[104:107]
	v_mfma_f32_16x16x32_bf16 v[104:107], v[170:173], v[204:207], v[104:107]
	v_mfma_f32_16x16x32_bf16 v[108:111], v[118:121], v[200:203], v[108:111]
	v_mfma_f32_16x16x32_bf16 v[108:111], v[122:125], v[204:207], v[108:111]
	v_mfma_f32_16x16x32_bf16 v[92:95], v[118:121], v[208:211], v[92:95]
	v_mfma_f32_16x16x32_bf16 v[92:95], v[122:125], v[212:215], v[92:95]
	v_mfma_f32_16x16x32_bf16 v[88:91], v[126:129], v[208:211], v[88:91]
	v_mfma_f32_16x16x32_bf16 v[88:91], v[170:173], v[212:215], v[88:91]
	v_mfma_f32_16x16x32_bf16 v[72:75], v[126:129], v[216:219], v[72:75]
	v_mfma_f32_16x16x32_bf16 v[72:75], v[170:173], v[220:223], v[72:75]
	v_mfma_f32_16x16x32_bf16 v[76:79], v[118:121], v[216:219], v[76:79]
	v_mfma_f32_16x16x32_bf16 v[76:79], v[122:125], v[220:223], v[76:79]
	v_mfma_f32_16x16x32_bf16 v[130:133], v[174:177], v[192:195], v[132:135]
	v_mfma_f32_16x16x32_bf16 v[130:133], v[178:181], v[196:199], v[130:133]
	v_mfma_f32_16x16x32_bf16 v[112:115], v[184:187], v[192:195], v[112:115]
	v_mfma_f32_16x16x32_bf16 v[112:115], v[188:191], v[196:199], v[112:115]
	v_mfma_f32_16x16x32_bf16 v[96:99], v[184:187], v[200:203], v[96:99]
	v_mfma_f32_16x16x32_bf16 v[96:99], v[188:191], v[204:207], v[96:99]
	v_mfma_f32_16x16x32_bf16 v[100:103], v[174:177], v[200:203], v[100:103]
	v_mfma_f32_16x16x32_bf16 v[100:103], v[178:181], v[204:207], v[100:103]
	v_mfma_f32_16x16x32_bf16 v[84:87], v[174:177], v[208:211], v[84:87]
	v_mfma_f32_16x16x32_bf16 v[84:87], v[178:181], v[212:215], v[84:87]
	v_mfma_f32_16x16x32_bf16 v[80:83], v[184:187], v[208:211], v[80:83]
	v_mfma_f32_16x16x32_bf16 v[80:83], v[188:191], v[212:215], v[80:83]
	v_mfma_f32_16x16x32_bf16 v[64:67], v[184:187], v[216:219], v[64:67]
	v_mfma_f32_16x16x32_bf16 v[64:67], v[188:191], v[220:223], v[64:67]
	v_mfma_f32_16x16x32_bf16 v[68:71], v[174:177], v[216:219], v[68:71]
	v_mfma_f32_16x16x32_bf16 v[68:71], v[178:181], v[220:223], v[68:71]
	s_barrier
	s_add_i32 s14, s71, s55
	s_mov_b32 m0, s14
	ds_read_b128 v[192:195], v168 offset:16384
	ds_read_b128 v[196:199], v168 offset:17408
	ds_read_b128 v[200:203], v168 offset:18432
	ds_read_b128 v[204:207], v168 offset:19456
	ds_read_b128 v[208:211], v168 offset:20480
	ds_read_b128 v[212:215], v168 offset:21504
	ds_read_b128 v[216:219], v168 offset:22528
	ds_read_b128 v[220:223], v168 offset:23552
	global_load_lds_dwordx4 v148, s[50:51]
	s_add_i32 m0, s14, 0x2000
	s_add_u32 s76, s50, 0x40000
	v_lshl_add_u64 v[226:227], s[50:51], 0, v[144:145]
	s_addc_u32 s77, s51, 0
	s_add_i32 s14, s72, s55
	global_load_lds_dwordx4 v144, s[50:51]
	s_mov_b32 m0, s14
	v_lshl_add_u64 v[228:229], s[52:53], 0, v[150:151]
	global_load_lds_dwordx4 v148, s[76:77]
	s_add_i32 m0, s14, 0x2000
	v_lshl_add_u64 v[230:231], s[52:53], 0, v[146:147]
	global_load_lds_dwordx4 v144, s[76:77]
	s_waitcnt vmcnt(6)
	s_waitcnt lgkmcnt(0)
	s_barrier
	v_mfma_f32_16x16x32_bf16 v[60:63], v[118:121], v[192:195], v[60:63]
	v_mfma_f32_16x16x32_bf16 v[60:63], v[122:125], v[196:199], v[60:63]
	v_mfma_f32_16x16x32_bf16 v[56:59], v[126:129], v[192:195], v[56:59]
	v_mfma_f32_16x16x32_bf16 v[56:59], v[170:173], v[196:199], v[56:59]
	v_mfma_f32_16x16x32_bf16 v[40:43], v[126:129], v[200:203], v[40:43]
	v_mfma_f32_16x16x32_bf16 v[40:43], v[170:173], v[204:207], v[40:43]
	v_mfma_f32_16x16x32_bf16 v[44:47], v[118:121], v[200:203], v[44:47]
	v_mfma_f32_16x16x32_bf16 v[44:47], v[122:125], v[204:207], v[44:47]
	v_mfma_f32_16x16x32_bf16 v[28:31], v[118:121], v[208:211], v[28:31]
	v_mfma_f32_16x16x32_bf16 v[28:31], v[122:125], v[212:215], v[28:31]
	v_mfma_f32_16x16x32_bf16 v[24:27], v[126:129], v[208:211], v[24:27]
	v_mfma_f32_16x16x32_bf16 v[24:27], v[170:173], v[212:215], v[24:27]
	v_mfma_f32_16x16x32_bf16 v[8:11], v[126:129], v[216:219], v[8:11]
	v_mfma_f32_16x16x32_bf16 v[8:11], v[170:173], v[220:223], v[8:11]
	v_mfma_f32_16x16x32_bf16 v[12:15], v[118:121], v[216:219], v[12:15]
	v_mfma_f32_16x16x32_bf16 v[12:15], v[122:125], v[220:223], v[12:15]
	v_mfma_f32_16x16x32_bf16 v[52:55], v[174:177], v[192:195], v[52:55]
	v_mfma_f32_16x16x32_bf16 v[52:55], v[178:181], v[196:199], v[52:55]
	v_mfma_f32_16x16x32_bf16 v[48:51], v[184:187], v[192:195], v[48:51]
	v_mfma_f32_16x16x32_bf16 v[48:51], v[188:191], v[196:199], v[48:51]
	v_mfma_f32_16x16x32_bf16 v[32:35], v[184:187], v[200:203], v[32:35]
	v_mfma_f32_16x16x32_bf16 v[32:35], v[188:191], v[204:207], v[32:35]
	v_mfma_f32_16x16x32_bf16 v[36:39], v[174:177], v[200:203], v[36:39]
	v_mfma_f32_16x16x32_bf16 v[36:39], v[178:181], v[204:207], v[36:39]
	v_mfma_f32_16x16x32_bf16 v[20:23], v[174:177], v[208:211], v[20:23]
	v_mfma_f32_16x16x32_bf16 v[20:23], v[178:181], v[212:215], v[20:23]
	v_mfma_f32_16x16x32_bf16 v[16:19], v[184:187], v[208:211], v[16:19]
	v_mfma_f32_16x16x32_bf16 v[16:19], v[188:191], v[212:215], v[16:19]
	v_mfma_f32_16x16x32_bf16 v[0:3], v[184:187], v[216:219], v[0:3]
	v_mfma_f32_16x16x32_bf16 v[0:3], v[188:191], v[220:223], v[0:3]
	v_mfma_f32_16x16x32_bf16 v[4:7], v[174:177], v[216:219], v[4:7]
	v_mfma_f32_16x16x32_bf16 v[4:7], v[178:181], v[220:223], v[4:7]
	s_barrier
; #define PG8_STAGE(bufoff, gbase, voff) do { _Pragma("unroll") for (int _i = 0; _i < 2; ++_i) \
;         __builtin_amdgcn_global_load_lds((const unsigned*)((const char*)(gbase) + (voff)[_i]), (PG8_LAS unsigned*)(lds + (bufoff) + ldsw + _i * 8192), 16, 0, 0); } while (0)
; #define PG8_LDA(dst, b, h) do { _Pragma("unroll") for (int m = 0; m < 4; ++m) _Pragma("unroll") for (int k = 0; k < 2; ++k) dst[m][k] = *(const PG8_LAS bf16x8*)(lds + PG8_SA(b, h) + aoff + m * 2048 + k * 1024); } while (0)
; #define PG8_LDB(dst, b, h) do { _Pragma("unroll") for (int n = 0; n < 2; ++n) _Pragma("unroll") for (int k = 0; k < 2; ++k) dst[n][k] = *(const PG8_LAS bf16x8*)(lds + PG8_SB(b, h) + boff + n * 2048 + k * 1024); } while (0)
; #define PG8_MMA(ai, bj, At, Bt) do { __builtin_amdgcn_s_setprio(1); _Pragma("unroll") for (int m = 0; m < 4; ++m) _Pragma("unroll") for (int n = 0; n < 2; ++n) _Pragma("unroll") for (int k = 0; k < 2; ++k) \
;         acc[ai][bj][m][n] = __builtin_amdgcn_mfma_f32_16x16x32_bf16(Bt[n][k], At[m][k], acc[ai][bj][m][n], 0, 0, 0); __builtin_amdgcn_s_setprio(0); } while (0)
; #define PG8_WAIT_V(n) asm volatile("s_waitcnt vmcnt(" #n ")" ::: "memory")
; #define PG8_WAIT_L(n) asm volatile("s_waitcnt lgkmcnt(" #n ")" ::: "memory")
; #define PG8_BAR __builtin_amdgcn_s_barrier()
; #define PG8_SCHED __builtin_amdgcn_sched_barrier(0)
; template <class Epi, class Sched, bool ALIGN_EPI = false, bool SP2 = false>
; __device__ __forceinline__ void gemm_phase(PG8_LAS unsigned char* lds, const Gemm g, const Sched& S, const Epi& E) {
;     ...
;             PG8_LDB(B0, 1, 0); PG8_LDB(B1, 1, 1); PG8_SCHED; PG8_LDA(At, 1, 0); PG8_STAGE(PG8_SA(0, 1), a2 + hstep, voffA);
;             PG8_WAIT_V(8); PG8_WAIT_L(0); PG8_BAR; PG8_MMA(0, 0, At, B0); PG8_MMA(0, 1, At, B1); PG8_BAR; PG8_SCHED;
;             PG8_LDA(At, 1, 1); PG8_STAGE(PG8_SB(1, 0), b3, voffB); PG8_STAGE(PG8_SB(1, 1), b3 + hstep, voffB); PG8_STAGE(PG8_SA(1, 0), a3, voffA);
;             PG8_WAIT_V(8); PG8_WAIT_L(0); PG8_BAR; PG8_MMA(1, 0, At, B0); PG8_MMA(1, 1, At, B1); PG8_BAR; PG8_SCHED;
	s_add_i32 s14, 0, 0x18000
	v_add_u32_e32 v134, s14, v163
	s_add_i32 s15, 0, 0x1c000
	ds_read_b128 v[118:121], v134
	ds_read_b128 v[122:125], v134 offset:1024
	ds_read_b128 v[126:129], v134 offset:2048
	ds_read_b128 v[170:173], v134 offset:3072
	v_add_u32_e32 v134, s15, v163
	ds_read_b128 v[174:177], v134
	ds_read_b128 v[178:181], v134 offset:1024
	ds_read_b128 v[184:187], v134 offset:2048
	ds_read_b128 v[188:191], v134 offset:3072
	s_mov_b32 m0, s58
	s_nop 0
	global_load_lds_dwordx4 v150, s[52:53]
	s_mov_b32 m0, s59
	s_nop 0
	global_load_lds_dwordx4 v146, s[52:53]
	s_add_u32 s52, s52, 0x40000
	s_addc_u32 s53, s53, 0
	s_mov_b32 m0, s60
	ds_read_b128 v[192:195], v168 offset:32768
	ds_read_b128 v[196:199], v168 offset:33792
	ds_read_b128 v[200:203], v168 offset:34816
	ds_read_b128 v[204:207], v168 offset:35840
	ds_read_b128 v[208:211], v168 offset:36864
	ds_read_b128 v[212:215], v168 offset:37888
	ds_read_b128 v[216:219], v168 offset:38912
	ds_read_b128 v[220:223], v168 offset:39936
	global_load_lds_dwordx4 v150, s[52:53]
	s_mov_b32 m0, s61
	s_nop 0
	global_load_lds_dwordx4 v146, s[52:53]
	s_waitcnt vmcnt(8)
	s_waitcnt lgkmcnt(0)
	s_barrier
	v_mfma_f32_16x16x32_bf16 v[140:143], v[118:121], v[192:195], v[140:143]
	v_mfma_f32_16x16x32_bf16 v[140:143], v[122:125], v[196:199], v[140:143]
	v_mfma_f32_16x16x32_bf16 v[134:137], v[126:129], v[192:195], v[136:139]
	v_mfma_f32_16x16x32_bf16 v[136:139], v[170:173], v[196:199], v[134:137]
	v_mfma_f32_16x16x32_bf16 v[104:107], v[126:129], v[200:203], v[104:107]
	v_mfma_f32_16x16x32_bf16 v[104:107], v[170:173], v[204:207], v[104:107]
	v_mfma_f32_16x16x32_bf16 v[108:111], v[118:121], v[200:203], v[108:111]
	v_mfma_f32_16x16x32_bf16 v[108:111], v[122:125], v[204:207], v[108:111]
	v_mfma_f32_16x16x32_bf16 v[92:95], v[118:121], v[208:211], v[92:95]
	v_mfma_f32_16x16x32_bf16 v[92:95], v[122:125], v[212:215], v[92:95]
	v_mfma_f32_16x16x32_bf16 v[88:91], v[126:129], v[208:211], v[88:91]
	v_mfma_f32_16x16x32_bf16 v[88:91], v[170:173], v[212:215], v[88:91]
	v_mfma_f32_16x16x32_bf16 v[72:75], v[126:129], v[216:219], v[72:75]
	v_mfma_f32_16x16x32_bf16 v[72:75], v[170:173], v[220:223], v[72:75]
	v_mfma_f32_16x16x32_bf16 v[76:79], v[118:121], v[216:219], v[76:79]
	v_mfma_f32_16x16x32_bf16 v[76:79], v[122:125], v[220:223], v[76:79]
	v_mfma_f32_16x16x32_bf16 v[130:133], v[174:177], v[192:195], v[130:133]
	v_mfma_f32_16x16x32_bf16 v[132:135], v[178:181], v[196:199], v[130:133]
	v_mfma_f32_16x16x32_bf16 v[112:115], v[184:187], v[192:195], v[112:115]
	v_mfma_f32_16x16x32_bf16 v[112:115], v[188:191], v[196:199], v[112:115]
	v_mfma_f32_16x16x32_bf16 v[96:99], v[184:187], v[200:203], v[96:99]
	v_mfma_f32_16x16x32_bf16 v[96:99], v[188:191], v[204:207], v[96:99]
	v_mfma_f32_16x16x32_bf16 v[100:103], v[174:177], v[200:203], v[100:103]
	v_mfma_f32_16x16x32_bf16 v[100:103], v[178:181], v[204:207], v[100:103]
	v_mfma_f32_16x16x32_bf16 v[84:87], v[174:177], v[208:211], v[84:87]
	v_mfma_f32_16x16x32_bf16 v[84:87], v[178:181], v[212:215], v[84:87]
	v_mfma_f32_16x16x32_bf16 v[80:83], v[184:187], v[208:211], v[80:83]
	v_mfma_f32_16x16x32_bf16 v[80:83], v[188:191], v[212:215], v[80:83]
	v_mfma_f32_16x16x32_bf16 v[64:67], v[184:187], v[216:219], v[64:67]
	v_mfma_f32_16x16x32_bf16 v[64:67], v[188:191], v[220:223], v[64:67]
	v_mfma_f32_16x16x32_bf16 v[68:71], v[174:177], v[216:219], v[68:71]
	v_mfma_f32_16x16x32_bf16 v[68:71], v[178:181], v[220:223], v[68:71]
	s_barrier
	s_add_i32 s14, s14, s55
	s_add_u32 s98, s50, s18
	s_addc_u32 s99, s51, s19
	s_mov_b32 m0, s14
	ds_read_b128 v[192:195], v168 offset:49152
	ds_read_b128 v[196:199], v168 offset:50176
	ds_read_b128 v[200:203], v168 offset:51200
	ds_read_b128 v[204:207], v168 offset:52224
	ds_read_b128 v[208:211], v168 offset:53248
	ds_read_b128 v[212:215], v168 offset:54272
	ds_read_b128 v[216:219], v168 offset:55296
	ds_read_b128 v[220:223], v168 offset:56320
	global_load_lds_dwordx4 v148, s[98:99]
	s_add_i32 m0, s14, 0x2000
	s_add_u32 s50, s50, 0x40080
	v_lshl_add_u64 v[130:131], v[226:227], 0, s[18:19]
	s_addc_u32 s51, s51, 0
	s_add_i32 s14, s15, s55
	global_load_lds_dwordx4 v[130:131], off
	s_mov_b32 m0, s14
	s_nop 0
	global_load_lds_dwordx4 v148, s[50:51]
	s_add_i32 m0, s14, 0x2000
	s_nop 0
	global_load_lds_dwordx4 v144, s[50:51]
	v_lshl_add_u64 v[130:131], v[228:229], 0, s[18:19]
	s_mov_b32 m0, s64
	s_nop 0
	global_load_lds_dwordx4 v[130:131], off
	v_lshl_add_u64 v[130:131], v[230:231], 0, s[18:19]
	s_mov_b32 m0, s65
	s_nop 0
	global_load_lds_dwordx4 v[130:131], off
	s_waitcnt vmcnt(6)
	s_waitcnt lgkmcnt(0)
	s_barrier
	v_mfma_f32_16x16x32_bf16 v[60:63], v[118:121], v[192:195], v[60:63]
	v_mfma_f32_16x16x32_bf16 v[60:63], v[122:125], v[196:199], v[60:63]
	v_mfma_f32_16x16x32_bf16 v[56:59], v[126:129], v[192:195], v[56:59]
	v_mfma_f32_16x16x32_bf16 v[56:59], v[170:173], v[196:199], v[56:59]
	v_mfma_f32_16x16x32_bf16 v[40:43], v[126:129], v[200:203], v[40:43]
	v_mfma_f32_16x16x32_bf16 v[40:43], v[170:173], v[204:207], v[40:43]
	v_mfma_f32_16x16x32_bf16 v[44:47], v[118:121], v[200:203], v[44:47]
	v_mfma_f32_16x16x32_bf16 v[44:47], v[122:125], v[204:207], v[44:47]
	v_mfma_f32_16x16x32_bf16 v[28:31], v[118:121], v[208:211], v[28:31]
	v_mfma_f32_16x16x32_bf16 v[28:31], v[122:125], v[212:215], v[28:31]
	v_mfma_f32_16x16x32_bf16 v[24:27], v[126:129], v[208:211], v[24:27]
	v_mfma_f32_16x16x32_bf16 v[24:27], v[170:173], v[212:215], v[24:27]
	v_mfma_f32_16x16x32_bf16 v[8:11], v[126:129], v[216:219], v[8:11]
	v_mfma_f32_16x16x32_bf16 v[8:11], v[170:173], v[220:223], v[8:11]
	v_mfma_f32_16x16x32_bf16 v[12:15], v[118:121], v[216:219], v[12:15]
	v_mfma_f32_16x16x32_bf16 v[12:15], v[122:125], v[220:223], v[12:15]
	v_mfma_f32_16x16x32_bf16 v[52:55], v[174:177], v[192:195], v[52:55]
	v_mfma_f32_16x16x32_bf16 v[52:55], v[178:181], v[196:199], v[52:55]
	v_mfma_f32_16x16x32_bf16 v[48:51], v[184:187], v[192:195], v[48:51]
	v_mfma_f32_16x16x32_bf16 v[48:51], v[188:191], v[196:199], v[48:51]
	v_mfma_f32_16x16x32_bf16 v[32:35], v[184:187], v[200:203], v[32:35]
	v_mfma_f32_16x16x32_bf16 v[32:35], v[188:191], v[204:207], v[32:35]
	v_mfma_f32_16x16x32_bf16 v[36:39], v[174:177], v[200:203], v[36:39]
	v_mfma_f32_16x16x32_bf16 v[36:39], v[178:181], v[204:207], v[36:39]
	v_mfma_f32_16x16x32_bf16 v[20:23], v[174:177], v[208:211], v[20:23]
	v_mfma_f32_16x16x32_bf16 v[20:23], v[178:181], v[212:215], v[20:23]
	v_mfma_f32_16x16x32_bf16 v[16:19], v[184:187], v[208:211], v[16:19]
	v_mfma_f32_16x16x32_bf16 v[16:19], v[188:191], v[212:215], v[16:19]
	v_mfma_f32_16x16x32_bf16 v[0:3], v[184:187], v[216:219], v[0:3]
	v_mfma_f32_16x16x32_bf16 v[0:3], v[188:191], v[220:223], v[0:3]
	v_mfma_f32_16x16x32_bf16 v[4:7], v[174:177], v[216:219], v[4:7]
	v_mfma_f32_16x16x32_bf16 v[4:7], v[178:181], v[220:223], v[4:7]
	s_barrier
	s_add_i32 s75, s75, 2
	s_add_u32 s45, s45, 0x100
	s_addc_u32 s47, s47, 0
	s_add_u32 s48, s48, 0x100
	s_addc_u32 s49, s49, 0
	s_cmp_gt_u32 s75, 13
	s_cbranch_scc1 .LBB0_1361

; #define PG8_STAGE(bufoff, gbase, voff) do { _Pragma("unroll") for (int _i = 0; _i < 2; ++_i) \
;         __builtin_amdgcn_global_load_lds((const unsigned*)((const char*)(gbase) + (voff)[_i]), (PG8_LAS unsigned*)(lds + (bufoff) + ldsw + _i * 8192), 16, 0, 0); } while (0)
; #define PG8_LDA(dst, b, h) do { _Pragma("unroll") for (int m = 0; m < 4; ++m) _Pragma("unroll") for (int k = 0; k < 2; ++k) dst[m][k] = *(const PG8_LAS bf16x8*)(lds + PG8_SA(b, h) + aoff + m * 2048 + k * 1024); } while (0)
; #define PG8_LDB(dst, b, h) do { _Pragma("unroll") for (int n = 0; n < 2; ++n) _Pragma("unroll") for (int k = 0; k < 2; ++k) dst[n][k] = *(const PG8_LAS bf16x8*)(lds + PG8_SB(b, h) + boff + n * 2048 + k * 1024); } while (0)
; #define PG8_MMA(ai, bj, At, Bt) do { __builtin_amdgcn_s_setprio(1); _Pragma("unroll") for (int m = 0; m < 4; ++m) _Pragma("unroll") for (int n = 0; n < 2; ++n) _Pragma("unroll") for (int k = 0; k < 2; ++k) \
;         acc[ai][bj][m][n] = __builtin_amdgcn_mfma_f32_16x16x32_bf16(Bt[n][k], At[m][k], acc[ai][bj][m][n], 0, 0, 0); __builtin_amdgcn_s_setprio(0); } while (0)
; #define PG8_WAIT_V(n) asm volatile("s_waitcnt vmcnt(" #n ")" ::: "memory")
; #define PG8_WAIT_L(n) asm volatile("s_waitcnt lgkmcnt(" #n ")" ::: "memory")
; #define PG8_BAR __builtin_amdgcn_s_barrier()
; #define PG8_SCHED __builtin_amdgcn_sched_barrier(0)
; template <class Epi, class Sched, bool ALIGN_EPI = false, bool SP2 = false>
; __device__ __forceinline__ void gemm_phase(PG8_LAS unsigned char* lds, const Gemm g, const Sched& S, const Epi& E) {
;     ...
;             PG8_LDB(B0, 0, 0); PG8_LDB(B1, 0, 1); PG8_SCHED; PG8_LDA(At, 0, 0); PG8_STAGE(PG8_SA(1, 1), a1 + hstep, voffA);
;             PG8_WAIT_V(8); PG8_WAIT_L(0); PG8_BAR; PG8_MMA(0, 0, At, B0); PG8_MMA(0, 1, At, B1); PG8_BAR; PG8_SCHED;
;             PG8_LDA(At, 0, 1); PG8_STAGE(PG8_SB(0, 0), b2, voffB); PG8_STAGE(PG8_SB(0, 1), b2 + hstep, voffB); PG8_STAGE(PG8_SA(0, 0), a2, voffA);
;             PG8_WAIT_V(8); PG8_WAIT_L(0); PG8_BAR; PG8_MMA(1, 0, At, B0); PG8_MMA(1, 1, At, B1); PG8_BAR; PG8_SCHED;
.LBB0_1432:
	ds_read_b128 v[128:131], v167
	ds_read_b128 v[132:135], v167 offset:1024
	ds_read_b128 v[136:139], v167 offset:2048
	ds_read_b128 v[140:143], v167 offset:3072
	ds_read_b128 v[160:163], v168
	ds_read_b128 v[170:173], v168 offset:1024
	ds_read_b128 v[174:177], v168 offset:2048
	ds_read_b128 v[178:181], v168 offset:3072
	s_add_u32 s20, s18, 0x100
	s_addc_u32 s21, s19, 0
	s_cmp_eq_u32 s52, 40
	s_cselect_b32 s27, s5, s21
	s_cselect_b32 s26, s4, s20
	s_cselect_b32 s23, s17, s51
	s_cselect_b32 s22, s16, s50
	v_lshl_add_u64 v[214:215], s[18:19], 0, v[154:155]
	s_add_i32 m0, s36, 0xc000
	ds_read_b128 v[182:185], v169
	ds_read_b128 v[186:189], v169 offset:1024
	ds_read_b128 v[190:193], v169 offset:2048
	ds_read_b128 v[194:197], v169 offset:3072
	ds_read_b128 v[198:201], v169 offset:4096
	ds_read_b128 v[202:205], v169 offset:5120
	ds_read_b128 v[206:209], v169 offset:6144
	ds_read_b128 v[210:213], v169 offset:7168
	global_load_lds_dwordx4 v[214:215], off
	v_lshl_add_u64 v[214:215], s[18:19], 0, v[152:153]
	s_add_i32 m0, s36, 0xe000
	s_nop 0
	global_load_lds_dwordx4 v[214:215], off
	s_waitcnt vmcnt(8)
	s_waitcnt lgkmcnt(0)
	s_barrier
	v_mfma_f32_16x16x32_bf16 v[124:127], v[128:131], v[182:185], v[124:127]
	v_mfma_f32_16x16x32_bf16 v[124:127], v[132:135], v[186:189], v[124:127]
	v_mfma_f32_16x16x32_bf16 v[120:123], v[136:139], v[182:185], v[120:123]
	v_mfma_f32_16x16x32_bf16 v[120:123], v[140:143], v[186:189], v[120:123]
	v_mfma_f32_16x16x32_bf16 v[108:111], v[136:139], v[190:193], v[108:111]
	v_mfma_f32_16x16x32_bf16 v[108:111], v[140:143], v[194:197], v[108:111]
	v_mfma_f32_16x16x32_bf16 v[116:119], v[128:131], v[190:193], v[116:119]
	v_mfma_f32_16x16x32_bf16 v[116:119], v[132:135], v[194:197], v[116:119]
	v_mfma_f32_16x16x32_bf16 v[100:103], v[128:131], v[198:201], v[100:103]
	v_mfma_f32_16x16x32_bf16 v[100:103], v[132:135], v[202:205], v[100:103]
	v_mfma_f32_16x16x32_bf16 v[92:95], v[136:139], v[198:201], v[92:95]
	v_mfma_f32_16x16x32_bf16 v[92:95], v[140:143], v[202:205], v[92:95]
	v_mfma_f32_16x16x32_bf16 v[76:79], v[136:139], v[206:209], v[76:79]
	v_mfma_f32_16x16x32_bf16 v[76:79], v[140:143], v[210:213], v[76:79]
	v_mfma_f32_16x16x32_bf16 v[84:87], v[128:131], v[206:209], v[84:87]
	v_mfma_f32_16x16x32_bf16 v[84:87], v[132:135], v[210:213], v[84:87]
	v_mfma_f32_16x16x32_bf16 v[112:115], v[160:163], v[182:185], v[112:115]
	v_mfma_f32_16x16x32_bf16 v[112:115], v[170:173], v[186:189], v[112:115]
	v_mfma_f32_16x16x32_bf16 v[104:107], v[174:177], v[182:185], v[104:107]
	v_mfma_f32_16x16x32_bf16 v[104:107], v[178:181], v[186:189], v[104:107]
	v_mfma_f32_16x16x32_bf16 v[88:91], v[174:177], v[190:193], v[88:91]
	v_mfma_f32_16x16x32_bf16 v[88:91], v[178:181], v[194:197], v[88:91]
	v_mfma_f32_16x16x32_bf16 v[96:99], v[160:163], v[190:193], v[96:99]
	v_mfma_f32_16x16x32_bf16 v[96:99], v[170:173], v[194:197], v[96:99]
	v_mfma_f32_16x16x32_bf16 v[80:83], v[160:163], v[198:201], v[80:83]
	v_mfma_f32_16x16x32_bf16 v[80:83], v[170:173], v[202:205], v[80:83]
	v_mfma_f32_16x16x32_bf16 v[72:75], v[174:177], v[198:201], v[72:75]
	v_mfma_f32_16x16x32_bf16 v[72:75], v[178:181], v[202:205], v[72:75]
	v_mfma_f32_16x16x32_bf16 v[64:67], v[174:177], v[206:209], v[64:67]
	v_mfma_f32_16x16x32_bf16 v[64:67], v[178:181], v[210:213], v[64:67]
	v_mfma_f32_16x16x32_bf16 v[68:71], v[160:163], v[206:209], v[68:71]
	v_mfma_f32_16x16x32_bf16 v[68:71], v[170:173], v[210:213], v[68:71]
	s_barrier
	s_add_i32 s18, s44, s33
	s_mov_b32 m0, s18
	ds_read_b128 v[182:185], v169 offset:16384
	ds_read_b128 v[186:189], v169 offset:17408
	ds_read_b128 v[190:193], v169 offset:18432
	ds_read_b128 v[194:197], v169 offset:19456
	ds_read_b128 v[198:201], v169 offset:20480
	ds_read_b128 v[202:205], v169 offset:21504
	ds_read_b128 v[206:209], v169 offset:22528
	ds_read_b128 v[210:213], v169 offset:23552
	global_load_lds_dwordx4 v148, s[22:23]
	s_add_i32 m0, s18, 0x2000
	s_add_u32 s18, s22, 0xb0000
	v_lshl_add_u64 v[216:217], s[22:23], 0, v[144:145]
	s_addc_u32 s19, s23, 0
	s_add_i32 s53, s45, s33
	global_load_lds_dwordx4 v144, s[22:23]
	s_mov_b32 m0, s53
	s_nop 0
	global_load_lds_dwordx4 v148, s[18:19]
	s_add_i32 m0, s53, 0x2000
	s_nop 0
	global_load_lds_dwordx4 v144, s[18:19]
	s_waitcnt vmcnt(6)
	s_waitcnt lgkmcnt(0)
	s_barrier
	v_mfma_f32_16x16x32_bf16 v[60:63], v[128:131], v[182:185], v[60:63]
	v_mfma_f32_16x16x32_bf16 v[60:63], v[132:135], v[186:189], v[60:63]
	v_mfma_f32_16x16x32_bf16 v[56:59], v[136:139], v[182:185], v[56:59]
	v_mfma_f32_16x16x32_bf16 v[56:59], v[140:143], v[186:189], v[56:59]
	v_mfma_f32_16x16x32_bf16 v[44:47], v[136:139], v[190:193], v[44:47]
	v_mfma_f32_16x16x32_bf16 v[44:47], v[140:143], v[194:197], v[44:47]
	v_mfma_f32_16x16x32_bf16 v[48:51], v[128:131], v[190:193], v[48:51]
	v_mfma_f32_16x16x32_bf16 v[48:51], v[132:135], v[194:197], v[48:51]
	v_mfma_f32_16x16x32_bf16 v[36:39], v[128:131], v[198:201], v[36:39]
	v_mfma_f32_16x16x32_bf16 v[36:39], v[132:135], v[202:205], v[36:39]
	v_mfma_f32_16x16x32_bf16 v[28:31], v[136:139], v[198:201], v[28:31]
	v_mfma_f32_16x16x32_bf16 v[28:31], v[140:143], v[202:205], v[28:31]
	v_mfma_f32_16x16x32_bf16 v[12:15], v[136:139], v[206:209], v[12:15]
	v_mfma_f32_16x16x32_bf16 v[12:15], v[140:143], v[210:213], v[12:15]
	v_mfma_f32_16x16x32_bf16 v[20:23], v[128:131], v[206:209], v[20:23]
	v_mfma_f32_16x16x32_bf16 v[20:23], v[132:135], v[210:213], v[20:23]
	v_mfma_f32_16x16x32_bf16 v[52:55], v[160:163], v[182:185], v[52:55]
	v_mfma_f32_16x16x32_bf16 v[52:55], v[170:173], v[186:189], v[52:55]
	v_mfma_f32_16x16x32_bf16 v[40:43], v[174:177], v[182:185], v[40:43]
	v_mfma_f32_16x16x32_bf16 v[40:43], v[178:181], v[186:189], v[40:43]
	v_mfma_f32_16x16x32_bf16 v[24:27], v[174:177], v[190:193], v[24:27]
	v_mfma_f32_16x16x32_bf16 v[24:27], v[178:181], v[194:197], v[24:27]
	v_mfma_f32_16x16x32_bf16 v[32:35], v[160:163], v[190:193], v[32:35]
	v_mfma_f32_16x16x32_bf16 v[32:35], v[170:173], v[194:197], v[32:35]
	v_mfma_f32_16x16x32_bf16 v[16:19], v[160:163], v[198:201], v[16:19]
	v_mfma_f32_16x16x32_bf16 v[16:19], v[170:173], v[202:205], v[16:19]
	v_mfma_f32_16x16x32_bf16 v[8:11], v[174:177], v[198:201], v[8:11]
	v_mfma_f32_16x16x32_bf16 v[8:11], v[178:181], v[202:205], v[8:11]
	v_mfma_f32_16x16x32_bf16 v[0:3], v[174:177], v[206:209], v[0:3]
	v_mfma_f32_16x16x32_bf16 v[0:3], v[178:181], v[210:213], v[0:3]
	v_mfma_f32_16x16x32_bf16 v[4:7], v[160:163], v[206:209], v[4:7]
	v_mfma_f32_16x16x32_bf16 v[4:7], v[170:173], v[210:213], v[4:7]
	s_barrier
; #define PG8_STAGE(bufoff, gbase, voff) do { _Pragma("unroll") for (int _i = 0; _i < 2; ++_i) \
;         __builtin_amdgcn_global_load_lds((const unsigned*)((const char*)(gbase) + (voff)[_i]), (PG8_LAS unsigned*)(lds + (bufoff) + ldsw + _i * 8192), 16, 0, 0); } while (0)
; #define PG8_LDA(dst, b, h) do { _Pragma("unroll") for (int m = 0; m < 4; ++m) _Pragma("unroll") for (int k = 0; k < 2; ++k) dst[m][k] = *(const PG8_LAS bf16x8*)(lds + PG8_SA(b, h) + aoff + m * 2048 + k * 1024); } while (0)
; #define PG8_LDB(dst, b, h) do { _Pragma("unroll") for (int n = 0; n < 2; ++n) _Pragma("unroll") for (int k = 0; k < 2; ++k) dst[n][k] = *(const PG8_LAS bf16x8*)(lds + PG8_SB(b, h) + boff + n * 2048 + k * 1024); } while (0)
; #define PG8_MMA(ai, bj, At, Bt) do { __builtin_amdgcn_s_setprio(1); _Pragma("unroll") for (int m = 0; m < 4; ++m) _Pragma("unroll") for (int n = 0; n < 2; ++n) _Pragma("unroll") for (int k = 0; k < 2; ++k) \
;         acc[ai][bj][m][n] = __builtin_amdgcn_mfma_f32_16x16x32_bf16(Bt[n][k], At[m][k], acc[ai][bj][m][n], 0, 0, 0); __builtin_amdgcn_s_setprio(0); } while (0)
; #define PG8_WAIT_V(n) asm volatile("s_waitcnt vmcnt(" #n ")" ::: "memory")
; #define PG8_WAIT_L(n) asm volatile("s_waitcnt lgkmcnt(" #n ")" ::: "memory")
; #define PG8_BAR __builtin_amdgcn_s_barrier()
; #define PG8_SCHED __builtin_amdgcn_sched_barrier(0)
; template <class Epi, class Sched, bool ALIGN_EPI = false, bool SP2 = false>
; __device__ __forceinline__ void gemm_phase(PG8_LAS unsigned char* lds, const Gemm g, const Sched& S, const Epi& E) {
;     ...
;             PG8_LDB(B0, 1, 0); PG8_LDB(B1, 1, 1); PG8_SCHED; PG8_LDA(At, 1, 0); PG8_STAGE(PG8_SA(0, 1), a2 + hstep, voffA);
;             PG8_WAIT_V(8); PG8_WAIT_L(0); PG8_BAR; PG8_MMA(0, 0, At, B0); PG8_MMA(0, 1, At, B1); PG8_BAR; PG8_SCHED;
;             PG8_LDA(At, 1, 1); PG8_STAGE(PG8_SB(1, 0), b3, voffB); PG8_STAGE(PG8_SB(1, 1), b3 + hstep, voffB); PG8_STAGE(PG8_SA(1, 0), a3, voffA);
;             PG8_WAIT_V(8); PG8_WAIT_L(0); PG8_BAR; PG8_MMA(1, 0, At, B0); PG8_MMA(1, 1, At, B1); PG8_BAR; PG8_SCHED;
	s_add_i32 s53, 0, 0x18000
	s_add_i32 s54, 0, 0x1c000
	v_add_u32_e32 v140, s53, v165
	v_add_u32_e32 v178, s54, v165
	ds_read_b128 v[128:131], v140
	ds_read_b128 v[132:135], v140 offset:1024
	ds_read_b128 v[136:139], v140 offset:2048
	ds_read_b128 v[140:143], v140 offset:3072
	ds_read_b128 v[160:163], v178
	ds_read_b128 v[170:173], v178 offset:1024
	ds_read_b128 v[174:177], v178 offset:2048
	ds_read_b128 v[178:181], v178 offset:3072
	s_add_u32 s18, s26, 0xb0000
	s_addc_u32 s19, s27, 0
	s_mov_b32 m0, s38
	ds_read_b128 v[182:185], v169 offset:32768
	ds_read_b128 v[186:189], v169 offset:33792
	ds_read_b128 v[190:193], v169 offset:34816
	ds_read_b128 v[194:197], v169 offset:35840
	ds_read_b128 v[198:201], v169 offset:36864
	ds_read_b128 v[202:205], v169 offset:37888
	ds_read_b128 v[206:209], v169 offset:38912
	ds_read_b128 v[210:213], v169 offset:39936
	global_load_lds_dwordx4 v150, s[18:19]
	s_mov_b32 m0, s39
	s_nop 0
	global_load_lds_dwordx4 v146, s[18:19]
	s_mov_b32 m0, s36
	s_nop 0
	global_load_lds_dwordx4 v150, s[26:27]
	s_mov_b32 m0, s37
	s_nop 0
	global_load_lds_dwordx4 v146, s[26:27]
	s_waitcnt vmcnt(8)
	s_waitcnt lgkmcnt(0)
	s_barrier
	v_mfma_f32_16x16x32_bf16 v[124:127], v[128:131], v[182:185], v[124:127]
	v_mfma_f32_16x16x32_bf16 v[124:127], v[132:135], v[186:189], v[124:127]
	v_mfma_f32_16x16x32_bf16 v[120:123], v[136:139], v[182:185], v[120:123]
	v_mfma_f32_16x16x32_bf16 v[120:123], v[140:143], v[186:189], v[120:123]
	v_mfma_f32_16x16x32_bf16 v[108:111], v[136:139], v[190:193], v[108:111]
	v_mfma_f32_16x16x32_bf16 v[108:111], v[140:143], v[194:197], v[108:111]
	v_mfma_f32_16x16x32_bf16 v[116:119], v[128:131], v[190:193], v[116:119]
	v_mfma_f32_16x16x32_bf16 v[116:119], v[132:135], v[194:197], v[116:119]
	v_mfma_f32_16x16x32_bf16 v[100:103], v[128:131], v[198:201], v[100:103]
	v_mfma_f32_16x16x32_bf16 v[100:103], v[132:135], v[202:205], v[100:103]
	v_mfma_f32_16x16x32_bf16 v[92:95], v[136:139], v[198:201], v[92:95]
	v_mfma_f32_16x16x32_bf16 v[92:95], v[140:143], v[202:205], v[92:95]
	v_mfma_f32_16x16x32_bf16 v[76:79], v[136:139], v[206:209], v[76:79]
	v_mfma_f32_16x16x32_bf16 v[76:79], v[140:143], v[210:213], v[76:79]
	v_mfma_f32_16x16x32_bf16 v[84:87], v[128:131], v[206:209], v[84:87]
	v_mfma_f32_16x16x32_bf16 v[84:87], v[132:135], v[210:213], v[84:87]
	v_mfma_f32_16x16x32_bf16 v[112:115], v[160:163], v[182:185], v[112:115]
	v_mfma_f32_16x16x32_bf16 v[112:115], v[170:173], v[186:189], v[112:115]
	v_mfma_f32_16x16x32_bf16 v[104:107], v[174:177], v[182:185], v[104:107]
	v_mfma_f32_16x16x32_bf16 v[104:107], v[178:181], v[186:189], v[104:107]
	v_mfma_f32_16x16x32_bf16 v[88:91], v[174:177], v[190:193], v[88:91]
	v_mfma_f32_16x16x32_bf16 v[88:91], v[178:181], v[194:197], v[88:91]
	v_mfma_f32_16x16x32_bf16 v[96:99], v[160:163], v[190:193], v[96:99]
	v_mfma_f32_16x16x32_bf16 v[96:99], v[170:173], v[194:197], v[96:99]
	v_mfma_f32_16x16x32_bf16 v[80:83], v[160:163], v[198:201], v[80:83]
	v_mfma_f32_16x16x32_bf16 v[80:83], v[170:173], v[202:205], v[80:83]
	v_mfma_f32_16x16x32_bf16 v[72:75], v[174:177], v[198:201], v[72:75]
	v_mfma_f32_16x16x32_bf16 v[72:75], v[178:181], v[202:205], v[72:75]
	v_mfma_f32_16x16x32_bf16 v[64:67], v[174:177], v[206:209], v[64:67]
	v_mfma_f32_16x16x32_bf16 v[64:67], v[178:181], v[210:213], v[64:67]
	v_mfma_f32_16x16x32_bf16 v[68:71], v[160:163], v[206:209], v[68:71]
	v_mfma_f32_16x16x32_bf16 v[68:71], v[170:173], v[210:213], v[68:71]
	s_barrier
	s_add_i32 s18, s53, s33
	s_add_u32 s98, s22, s12
	s_addc_u32 s99, s23, s13
	s_add_u32 s100, s26, s12
	s_addc_u32 s101, s27, s13
	s_mov_b32 m0, s18
	ds_read_b128 v[182:185], v169 offset:49152
	ds_read_b128 v[186:189], v169 offset:50176
	ds_read_b128 v[190:193], v169 offset:51200
	ds_read_b128 v[194:197], v169 offset:52224
	ds_read_b128 v[198:201], v169 offset:53248
	ds_read_b128 v[202:205], v169 offset:54272
	ds_read_b128 v[206:209], v169 offset:55296
	ds_read_b128 v[210:213], v169 offset:56320
	global_load_lds_dwordx4 v148, s[98:99]
	s_add_i32 m0, s18, 0x2000
	s_add_u32 s18, s22, 0xb0080
	v_lshl_add_u64 v[214:215], v[216:217], 0, s[12:13]
	s_addc_u32 s19, s23, 0
	s_add_i32 s22, s54, s33
	global_load_lds_dwordx4 v[214:215], off
	s_mov_b32 m0, s22
	s_nop 0
	global_load_lds_dwordx4 v148, s[18:19]
	s_add_i32 m0, s22, 0x2000
	s_nop 0
	global_load_lds_dwordx4 v144, s[18:19]
	s_mov_b32 m0, s41
	s_nop 0
	global_load_lds_dwordx4 v150, s[100:101]
	s_mov_b32 m0, s42
	s_nop 0
	global_load_lds_dwordx4 v146, s[100:101]
	s_waitcnt vmcnt(6)
	s_waitcnt lgkmcnt(0)
	s_barrier
	v_mfma_f32_16x16x32_bf16 v[60:63], v[128:131], v[182:185], v[60:63]
	v_mfma_f32_16x16x32_bf16 v[60:63], v[132:135], v[186:189], v[60:63]
	v_mfma_f32_16x16x32_bf16 v[56:59], v[136:139], v[182:185], v[56:59]
	v_mfma_f32_16x16x32_bf16 v[56:59], v[140:143], v[186:189], v[56:59]
	v_mfma_f32_16x16x32_bf16 v[44:47], v[136:139], v[190:193], v[44:47]
	v_mfma_f32_16x16x32_bf16 v[44:47], v[140:143], v[194:197], v[44:47]
	v_mfma_f32_16x16x32_bf16 v[48:51], v[128:131], v[190:193], v[48:51]
	v_mfma_f32_16x16x32_bf16 v[48:51], v[132:135], v[194:197], v[48:51]
	v_mfma_f32_16x16x32_bf16 v[36:39], v[128:131], v[198:201], v[36:39]
	v_mfma_f32_16x16x32_bf16 v[36:39], v[132:135], v[202:205], v[36:39]
	v_mfma_f32_16x16x32_bf16 v[28:31], v[136:139], v[198:201], v[28:31]
	v_mfma_f32_16x16x32_bf16 v[28:31], v[140:143], v[202:205], v[28:31]
	v_mfma_f32_16x16x32_bf16 v[12:15], v[136:139], v[206:209], v[12:15]
	v_mfma_f32_16x16x32_bf16 v[12:15], v[140:143], v[210:213], v[12:15]
	v_mfma_f32_16x16x32_bf16 v[20:23], v[128:131], v[206:209], v[20:23]
	v_mfma_f32_16x16x32_bf16 v[20:23], v[132:135], v[210:213], v[20:23]
	v_mfma_f32_16x16x32_bf16 v[52:55], v[160:163], v[182:185], v[52:55]
	v_mfma_f32_16x16x32_bf16 v[52:55], v[170:173], v[186:189], v[52:55]
	v_mfma_f32_16x16x32_bf16 v[40:43], v[174:177], v[182:185], v[40:43]
	v_mfma_f32_16x16x32_bf16 v[40:43], v[178:181], v[186:189], v[40:43]
	v_mfma_f32_16x16x32_bf16 v[24:27], v[174:177], v[190:193], v[24:27]
	v_mfma_f32_16x16x32_bf16 v[24:27], v[178:181], v[194:197], v[24:27]
	v_mfma_f32_16x16x32_bf16 v[32:35], v[160:163], v[190:193], v[32:35]
	v_mfma_f32_16x16x32_bf16 v[32:35], v[170:173], v[194:197], v[32:35]
	v_mfma_f32_16x16x32_bf16 v[16:19], v[160:163], v[198:201], v[16:19]
	v_mfma_f32_16x16x32_bf16 v[16:19], v[170:173], v[202:205], v[16:19]
	v_mfma_f32_16x16x32_bf16 v[8:11], v[174:177], v[198:201], v[8:11]
	v_mfma_f32_16x16x32_bf16 v[8:11], v[178:181], v[202:205], v[8:11]
	v_mfma_f32_16x16x32_bf16 v[0:3], v[174:177], v[206:209], v[0:3]
	v_mfma_f32_16x16x32_bf16 v[0:3], v[178:181], v[210:213], v[0:3]
	v_mfma_f32_16x16x32_bf16 v[4:7], v[160:163], v[206:209], v[4:7]
	v_mfma_f32_16x16x32_bf16 v[4:7], v[170:173], v[210:213], v[4:7]
	s_barrier
	s_add_i32 s52, s52, 2
	s_add_u32 s50, s50, 0x100
	s_addc_u32 s51, s51, 0
	s_cmp_gt_u32 s52, 41
	s_mov_b64 s[18:19], s[20:21]
	s_cbranch_scc0 .LBB0_1432
	s_and_b64 vcc, exec, s[14:15]
	s_cbranch_vccz .LBB0_1435
	s_barrier
